# SSD conv staging (both inlined copies): 16 later raw-row loads issued before the first wait (was load-wait-load), dt/a_log loads hoisted to unit start
# baseline (speedup 1.0000x reference)
; #define LAS __attribute__((address_space(3)))
; template <bool NEED_C>
; __device__ __forceinline__ void ssd_stage(LAS unsigned char* lds, const bf16_t* XBC, const float* cw, const float* cb, const float* DT, const float* a_log, int c, int g, int tid, int lane, int wave) {
;     ...
;         const int cgi = tid & 63, seg = tid >> 6;
;         int col, tch; LAS unsigned char* tile;
;         if (cgi < 32) { col = g * 256 + cgi * 8; tile = lds + SSD_XT + (cgi >> 4) * 32768; tch = cgi & 15; }
;         else if (cgi < 48) { col = 2048 + g * 128 + (cgi - 32) * 8; tile = lds + SSD_BT; tch = cgi - 32; }
;         else { col = 3072 + g * 128 + (cgi - 48) * 8; tile = lds + SSD_CT; tch = cgi - 48; }
;     ...
;     { const int l = tid >> 2, r = tid & 3, hd = 4 * g + r; const float dtv = DT[(size_t)(c * 128 + l) * 32 + hd]; const float a = -expf(a_log[hd]);
.LBB0_506:
	s_and_b32 s89, s87, 7
	s_ashr_i32 s1, s87, 3
	s_lshl_b32 s1, s1, 7
	v_add_u32_e32 v2, s1, v170
	v_ashrrev_i32_e32 v3, 31, v2
	v_lshlrev_b64 v[2:3], 7, v[2:3]
	s_lshl_b32 s1, s89, 2
	v_or_b32_e32 v4, s1, v175
	v_lshlrev_b32_e32 v4, 2, v4
	v_mov_b32_e32 v5, v119
	s_waitcnt lgkmcnt(0)
	global_load_dword v252, v4, s[34:35]
	v_lshl_add_u64 v[2:3], s[36:37], 0, v[2:3]
	v_lshl_add_u64 v[2:3], v[2:3], 0, v[4:5]
	global_load_dword v253, v[2:3], off
	s_and_saveexec_b64 s[4:5], s[38:39]
	s_xor_b64 s[24:25], exec, s[4:5]
	s_cbranch_execz .LBB0_512
	s_lshl_b32 s1, s89, 7
	s_and_saveexec_b64 s[4:5], s[40:41]
	s_xor_b64 s[50:51], exec, s[4:5]
	v_add_u32_e32 v26, s1, v166
	s_or_saveexec_b64 s[50:51], s[50:51]
	v_mov_b32_e32 v234, s64
	v_mov_b32_e32 v235, v165
	s_xor_b64 exec, exec, s[50:51]
	v_add_u32_e32 v26, s1, v167
	v_mov_b32_e32 v234, s62
	v_mov_b32_e32 v235, v164
	s_or_b64 exec, exec, s[50:51]

; __device__ __forceinline__ float silu_f(float x) { return x * __builtin_amdgcn_rcpf(1.f + __expf(-x)); }
; template <bool NEED_C>
; __device__ __forceinline__ void ssd_stage(LAS unsigned char* lds, const bf16_t* XBC, const float* cw, const float* cb, const float* DT, const float* a_log, int c, int g, int tid, int lane, int wave) {
;     ...
;             u32x4 raw[19];
; #pragma unroll
;             for (int k = 0; k < 19; ++k) { const int tt = t0 - 3 + k;
;                 if (k >= 3 || tt >= 0) raw[k] = *(const u32x4*)(XBC + (size_t)tt * XBCC + col);
;                 else raw[k] = (u32x4){0u, 0u, 0u, 0u}; }
;             asm volatile("" ::: "memory");
; #pragma unroll
;             for (int k = 0; k < 3; ++k) unpack8(raw[k], xw[k]);
; #pragma unroll
;             for (int i = 0; i < 16; ++i) { float xv[8]; unpack8(raw[3 + i], xv);
;                 float o[8];
; #pragma unroll
;                 for (int e = 0; e < 8; ++e) { o[e] = silu_f(b[e] + w[0][e] * xw[0][e] + w[1][e] * xw[1][e] + w[2][e] * xw[2][e] + w[3][e] * xv[e]); xw[0][e] = xw[1][e]; xw[1][e] = xw[2][e]; xw[2][e] = xv[e]; }
.LBB0_523:
	s_or_b64 exec, exec, s[24:25]
	v_add_u32_e32 v30, s90, v171
	v_ashrrev_i32_e32 v31, 31, v30
	v_ashrrev_i32_e32 v29, 31, v28
	v_lshlrev_b64 v[30:31], 13, v[30:31]
	v_lshlrev_b64 v[28:29], 13, v[28:29]
	v_lshl_add_u64 v[30:31], v[26:27], 0, v[30:31]
	v_lshl_add_u64 v[26:27], v[26:27], 0, v[28:29]
	global_load_dwordx4 v[114:117], v[30:31], off
	v_add_co_u32_e32 v28, vcc, s3, v26
	s_nop 1
	v_addc_co_u32_e32 v29, vcc, 0, v27, vcc
	global_load_dwordx4 v[78:81], v[28:29], off
	v_add_co_u32_e32 v28, vcc, s66, v26
	s_nop 1
	v_addc_co_u32_e32 v29, vcc, 0, v27, vcc
	global_load_dwordx4 v[82:85], v[28:29], off
	v_add_co_u32_e32 v30, vcc, s65, v26
	s_nop 1
	v_addc_co_u32_e32 v31, vcc, 0, v27, vcc
	global_load_dwordx4 v[70:73], v[30:31], off
	v_add_co_u32_e32 v28, vcc, s67, v26
	s_nop 1
	v_addc_co_u32_e32 v29, vcc, 0, v27, vcc
	global_load_dwordx4 v[74:77], v[28:29], off
	v_add_co_u32_e32 v30, vcc, s61, v26
	s_nop 1
	v_addc_co_u32_e32 v31, vcc, 0, v27, vcc
	global_load_dwordx4 v[62:65], v[30:31], off
	v_add_co_u32_e32 v28, vcc, s68, v26
	s_nop 1
	v_addc_co_u32_e32 v29, vcc, 0, v27, vcc
	global_load_dwordx4 v[66:69], v[28:29], off
	v_add_co_u32_e32 v30, vcc, s69, v26
	s_nop 1
	v_addc_co_u32_e32 v31, vcc, 0, v27, vcc
	global_load_dwordx4 v[54:57], v[30:31], off
	v_add_co_u32_e32 v28, vcc, s70, v26
	s_nop 1
	v_addc_co_u32_e32 v29, vcc, 0, v27, vcc
	global_load_dwordx4 v[58:61], v[28:29], off
	v_add_co_u32_e32 v30, vcc, s63, v26
	s_nop 1
	v_addc_co_u32_e32 v31, vcc, 0, v27, vcc
	global_load_dwordx4 v[46:49], v[30:31], off
	v_add_co_u32_e32 v28, vcc, s71, v26
	s_nop 1
	v_addc_co_u32_e32 v29, vcc, 0, v27, vcc
	global_load_dwordx4 v[50:53], v[28:29], off
	v_add_co_u32_e32 v30, vcc, s72, v26
	s_nop 1
	v_addc_co_u32_e32 v31, vcc, 0, v27, vcc
	global_load_dwordx4 v[38:41], v[30:31], off
	v_add_co_u32_e32 v28, vcc, s73, v26
	s_nop 1
	v_addc_co_u32_e32 v29, vcc, 0, v27, vcc
	global_load_dwordx4 v[42:45], v[28:29], off
	v_add_co_u32_e32 v30, vcc, s75, v26
	s_nop 1
	v_addc_co_u32_e32 v31, vcc, 0, v27, vcc
	global_load_dwordx4 v[30:33], v[30:31], off
	v_add_co_u32_e32 v28, vcc, s80, v26
	s_nop 1
	v_addc_co_u32_e32 v29, vcc, 0, v27, vcc
	global_load_dwordx4 v[34:37], v[28:29], off
	v_add_co_u32_e32 v26, vcc, s81, v26
	s_nop 1
	v_addc_co_u32_e32 v27, vcc, 0, v27, vcc
	global_load_dwordx4 v[26:29], v[26:27], off
	s_waitcnt vmcnt(16)
	v_lshlrev_b32_e32 v241, 16, v98
	s_nop 0
	s_nop 0
	s_nop 0
	v_lshlrev_b32_e32 v240, 16, v94
	v_mov_b32_e32 v150, v106
	v_mov_b32_e32 v151, v14
	v_pk_mul_f32 v[236:237], v[150:151], v[240:241]
	v_lshlrev_b32_e32 v162, 16, v102
	v_add_f32_e32 v14, v22, v236
	v_mov_b32_e32 v152, v110
	v_mov_b32_e32 v153, v18
	v_add_f32_e32 v14, v14, v237
	v_and_b32_e32 v243, 0xffff0000, v98
	v_and_b32_e32 v242, 0xffff0000, v94
	v_and_b32_e32 v160, 0xffff0000, v102
	v_lshlrev_b32_e32 v244, 16, v95
	v_lshlrev_b32_e32 v245, 16, v99
	v_lshlrev_b32_e32 v156, 16, v103
	v_and_b32_e32 v247, 0xffff0000, v99
	v_and_b32_e32 v246, 0xffff0000, v95
	s_nop 0
	v_and_b32_e32 v249, 0xffff0000, v100
	s_nop 0
	s_nop 0
	s_nop 0
	v_and_b32_e32 v248, 0xffff0000, v96
	s_nop 0
	s_nop 0
	s_nop 0
	s_nop 0
	v_lshlrev_b32_e32 v250, 16, v97
	v_lshlrev_b32_e32 v251, 16, v101
	s_nop 0
	v_and_b32_e32 v101, 0xffff0000, v101
	s_nop 0
	s_nop 0
	s_nop 0
	s_waitcnt vmcnt(15)
	v_lshlrev_b32_e32 v163, 16, v114
	v_pk_mul_f32 v[236:237], v[152:153], v[162:163]
	v_and_b32_e32 v161, 0xffff0000, v114
	v_add_f32_e32 v14, v14, v236
	v_add_f32_e32 v158, v14, v237
	v_mul_f32_e32 v14, 0xbfb8aa3b, v158
	v_exp_f32_e32 v14, v14
	v_lshlrev_b32_e32 v157, 16, v115
	s_nop 0
	v_add_f32_e32 v159, 1.0, v14
	v_mov_b32_e32 v14, v107
	v_pk_mul_f32 v[106:107], v[14:15], v[242:243]
	s_nop 0
	s_nop 0
	v_add_f32_e32 v18, v23, v106
	v_add_f32_e32 v94, v18, v107
	v_mov_b32_e32 v18, v111
	v_pk_mul_f32 v[106:107], v[18:19], v[160:161]
	s_nop 0
	v_add_f32_e32 v94, v94, v106
	v_add_f32_e32 v98, v94, v107
	v_mov_b32_e32 v106, v108
	v_mov_b32_e32 v107, v16
	v_pk_mul_f32 v[110:111], v[106:107], v[244:245]
	v_mul_f32_e32 v94, 0xbfb8aa3b, v98
	v_add_f32_e32 v16, v24, v110
	v_add_f32_e32 v16, v16, v111
	v_mov_b32_e32 v110, v112
	v_mov_b32_e32 v111, v20
	v_pk_mul_f32 v[154:155], v[110:111], v[156:157]
	v_exp_f32_e32 v94, v94
	v_add_f32_e32 v16, v16, v154
	v_add_f32_e32 v102, v16, v155
	v_mul_f32_e32 v16, 0xbfb8aa3b, v102
	v_exp_f32_e32 v16, v16
	v_add_f32_e32 v20, 1.0, v94
	v_rcp_f32_e32 v112, v20
	v_and_b32_e32 v155, 0xffff0000, v115
	v_add_f32_e32 v16, 1.0, v16
	v_rcp_f32_e32 v114, v16
	v_mov_b32_e32 v16, v109
	v_pk_mul_f32 v[94:95], v[16:17], v[246:247]
	v_and_b32_e32 v154, 0xffff0000, v103
	v_add_f32_e32 v20, v25, v94
	v_add_f32_e32 v99, v20, v95
	v_mov_b32_e32 v20, v113
	v_pk_mul_f32 v[94:95], v[20:21], v[154:155]
	v_rcp_f32_e32 v108, v159
	v_add_f32_e32 v94, v99, v94
	v_add_f32_e32 v113, v94, v95
	v_mul_f32_e32 v94, 0xbfb8aa3b, v113
	v_exp_f32_e32 v94, v94
	v_mul_f32_e32 v236, v158, v108
	v_mul_f32_e32 v237, v98, v112
	v_lshlrev_b32_e32 v109, 16, v100
	v_add_f32_e32 v94, 1.0, v94
	v_rcp_f32_e32 v112, v94
	v_lshlrev_b32_e32 v108, 16, v96
	v_mov_b32_e32 v94, v86
	v_mov_b32_e32 v95, v2
	v_pk_mul_f32 v[98:99], v[94:95], v[108:109]
	v_lshlrev_b32_e32 v159, 16, v116
	v_add_f32_e32 v2, v10, v98
	v_add_f32_e32 v2, v2, v99
	v_lshlrev_b32_e32 v158, 16, v104
	v_mov_b32_e32 v98, v90
	v_mov_b32_e32 v99, v6
	v_mul_f32_e32 v238, v102, v114
	v_pk_mul_f32 v[102:103], v[98:99], v[158:159]
	v_and_b32_e32 v115, 0xffff0000, v116
	v_add_f32_e32 v2, v2, v102
	v_add_f32_e32 v108, v2, v103
	v_mul_f32_e32 v2, 0xbfb8aa3b, v108
	v_exp_f32_e32 v90, v2
	v_mov_b32_e32 v2, v87
	v_pk_mul_f32 v[86:87], v[2:3], v[248:249]
	v_and_b32_e32 v114, 0xffff0000, v104
; __device__ __forceinline__ unsigned cvt_pk_bf16(float lo, float hi) { unsigned r; asm volatile("v_cvt_pk_bf16_f32 %0, %1, %2" : "=v"(r) : "v"(lo), "v"(hi)); return r; }
; #define LAS __attribute__((address_space(3)))
; __device__ __forceinline__ float silu_f(float x) { return x * __builtin_amdgcn_rcpf(1.f + __expf(-x)); }
; template <bool NEED_C>
; __device__ __forceinline__ void ssd_stage(LAS unsigned char* lds, const bf16_t* XBC, const float* cw, const float* cb, const float* DT, const float* a_log, int c, int g, int tid, int lane, int wave) {
;     ...
;             for (int i = 0; i < 16; ++i) { float xv[8]; unpack8(raw[3 + i], xv);
;                 float o[8];
; #pragma unroll
;                 for (int e = 0; e < 8; ++e) { o[e] = silu_f(b[e] + w[0][e] * xw[0][e] + w[1][e] * xw[1][e] + w[2][e] * xw[2][e] + w[3][e] * xv[e]); xw[0][e] = xw[1][e]; xw[1][e] = xw[2][e]; xw[2][e] = xv[e]; }
;                 u32x4 pk; pk.x = cvt_pk_bf16(o[0], o[1]); pk.y = cvt_pk_bf16(o[2], o[3]); pk.z = cvt_pk_bf16(o[4], o[5]); pk.w = cvt_pk_bf16(o[6], o[7]);
;                 *(LAS u32x4*)(tile + off_b(seg * 16 + i, tch)) = pk; }
	v_add_f32_e32 v6, v11, v86
	v_add_f32_e32 v96, v6, v87
	v_mov_b32_e32 v6, v91
	v_pk_mul_f32 v[86:87], v[6:7], v[114:115]
	v_lshlrev_b32_e32 v102, 16, v105
	v_add_f32_e32 v86, v96, v86
	v_add_f32_e32 v96, v86, v87
	v_mul_f32_e32 v86, 0xbfb8aa3b, v96
	v_exp_f32_e32 v86, v86
	v_add_f32_e32 v87, 1.0, v90
	v_rcp_f32_e32 v116, v87
	v_mov_b32_e32 v87, v4
	v_add_f32_e32 v239, 1.0, v86
	v_mov_b32_e32 v86, v88
	v_pk_mul_f32 v[90:91], v[86:87], v[250:251]
	v_lshlrev_b32_e32 v103, 16, v117
	v_add_f32_e32 v4, v12, v90
	v_add_f32_e32 v4, v4, v91
	v_mov_b32_e32 v90, v92
	v_mov_b32_e32 v91, v8
	v_mul_f32_e32 v104, v113, v112
	v_pk_mul_f32 v[112:113], v[90:91], v[102:103]
	s_nop 0
	v_add_f32_e32 v4, v4, v112
	v_add_f32_e32 v92, v4, v113
	v_mul_f32_e32 v4, 0xbfb8aa3b, v92
	s_nop 0
	v_exp_f32_e32 v240, v4
	v_and_b32_e32 v100, 0xffff0000, v97
	v_mov_b32_e32 v4, v89
	s_nop 0
	v_pk_mul_f32 v[88:89], v[4:5], v[100:101]
	s_nop 0
	s_nop 0
	s_nop 0
	v_add_f32_e32 v8, v13, v88
	s_nop 0
	s_nop 0
	v_add_f32_e32 v97, v8, v89
	v_and_b32_e32 v113, 0xffff0000, v117
	v_and_b32_e32 v112, 0xffff0000, v105
	v_mov_b32_e32 v8, v93
	s_nop 0
	v_pk_mul_f32 v[88:89], v[8:9], v[112:113]
	s_nop 0
	s_nop 0
	v_add_f32_e32 v88, v97, v88
	s_nop 0
	s_nop 0
	s_nop 0
	v_add_f32_e32 v88, v88, v89
	s_nop 0
	s_nop 0
	v_mul_f32_e32 v89, 0xbfb8aa3b, v88
	s_nop 0
	v_exp_f32_e32 v89, v89
	s_nop 0
	s_nop 0
	s_nop 0
	s_nop 0
	s_nop 0
	v_add_f32_e32 v89, 1.0, v89
	s_nop 0
	s_nop 0
	s_nop 0
	v_add_f32_e32 v97, 1.0, v240
	s_nop 0
	s_nop 0
	v_rcp_f32_e32 v89, v89
	s_nop 0
	s_nop 0
	s_nop 0
	s_nop 0
	v_rcp_f32_e32 v93, v239
	v_rcp_f32_e32 v97, v97
	s_nop 0
	s_nop 0
	v_mul_f32_e32 v105, v108, v116
	s_nop 0
	s_nop 0
	v_mul_f32_e32 v88, v88, v89
	v_lshlrev_b32_e32 v116, 4, v235
	s_nop 0
	s_nop 0
	s_nop 0
	v_mul_f32_e32 v93, v96, v93
	v_mul_f32_e32 v92, v92, v97
	v_cvt_pk_bf16_f32 v236, v236, v237
	v_cvt_pk_bf16_f32 v237, v238, v104
	v_cvt_pk_bf16_f32 v238, v105, v93
	v_cvt_pk_bf16_f32 v239, v92, v88
	v_add3_u32 v88, v234, v116, v173
	ds_write_b128 v88, v[236:239]
	v_pk_mov_b32 v[88:89], v[240:241], v[162:163] op_sel:[1,0]
	v_xor_b32_e32 v93, 64, v116
	v_pk_mul_f32 v[88:89], v[150:151], v[88:89]
	s_nop 0
	v_add_f32_e32 v88, v22, v88
	v_add_f32_e32 v92, v88, v89
	v_pk_mov_b32 v[88:89], v[242:243], v[160:161] op_sel:[1,0]
	s_nop 0
	v_pk_mul_f32 v[88:89], v[14:15], v[88:89]
	s_nop 0
	v_add_f32_e32 v88, v23, v88
	v_add_f32_e32 v96, v88, v89
	v_pk_mov_b32 v[88:89], v[244:245], v[156:157] op_sel:[1,0]
	s_nop 0
	v_pk_mul_f32 v[88:89], v[106:107], v[88:89]
	s_nop 0
	v_add_f32_e32 v88, v24, v88
	v_add_f32_e32 v104, v88, v89
	v_pk_mov_b32 v[88:89], v[246:247], v[154:155] op_sel:[1,0]
	v_add3_u32 v246, v234, v93, v173
	v_pk_mul_f32 v[88:89], v[16:17], v[88:89]
	s_nop 0
	v_add_f32_e32 v88, v25, v88
	v_add_f32_e32 v105, v88, v89
	v_pk_mov_b32 v[88:89], v[108:109], v[158:159] op_sel:[1,0]
	s_waitcnt vmcnt(13)
	v_lshlrev_b32_e32 v109, 16, v82
	v_pk_mul_f32 v[88:89], v[94:95], v[88:89]
	v_lshlrev_b32_e32 v108, 16, v78
	v_add_f32_e32 v88, v10, v88
	v_add_f32_e32 v117, v88, v89
	v_pk_mov_b32 v[88:89], v[248:249], v[114:115] op_sel:[1,0]
	s_nop 0
	v_pk_mul_f32 v[88:89], v[2:3], v[88:89]
	s_nop 0
	v_add_f32_e32 v88, v11, v88
	v_add_f32_e32 v235, v88, v89
	v_pk_mov_b32 v[88:89], v[250:251], v[102:103] op_sel:[1,0]
	s_nop 0
	v_pk_mul_f32 v[88:89], v[86:87], v[88:89]
	s_nop 0
	v_add_f32_e32 v88, v12, v88
	v_add_f32_e32 v244, v88, v89
	v_pk_mov_b32 v[88:89], v[100:101], v[112:113] op_sel:[1,0]
	s_nop 0
	v_pk_mul_f32 v[88:89], v[4:5], v[88:89]
	s_nop 0
	v_add_f32_e32 v88, v13, v88
	v_add_f32_e32 v245, v88, v89
	v_pk_mul_f32 v[88:89], v[150:151], v[162:163]
	v_pk_mov_b32 v[162:163], v[162:163], v[108:109] op_sel:[1,0]
	v_add_f32_e32 v88, v22, v88
	v_add_f32_e32 v97, v88, v89
	v_pk_mul_f32 v[88:89], v[152:153], v[162:163]
	s_nop 0
	v_add_f32_e32 v88, v92, v88
	v_add_f32_e32 v100, v88, v89
	v_mul_f32_e32 v88, 0xbfb8aa3b, v100
	v_exp_f32_e32 v92, v88
	v_pk_mul_f32 v[88:89], v[152:153], v[108:109]
	s_nop 0
	v_add_f32_e32 v88, v97, v88
	v_add_f32_e32 v97, v88, v89
	v_mul_f32_e32 v88, 0xbfb8aa3b, v97
	v_exp_f32_e32 v88, v88
	v_add_f32_e32 v89, 1.0, v92
	v_rcp_f32_e32 v101, v89
	v_and_b32_e32 v89, 0xffff0000, v82
	v_add_f32_e32 v88, 1.0, v88
	v_rcp_f32_e32 v238, v88
	v_and_b32_e32 v88, 0xffff0000, v78
	v_pk_mov_b32 v[236:237], v[160:161], v[88:89] op_sel:[1,0]
	v_mul_f32_e32 v100, v100, v101
	v_pk_mul_f32 v[92:93], v[18:19], v[236:237]
	v_mul_f32_e32 v247, v97, v238
	v_add_f32_e32 v78, v96, v92
	v_add_f32_e32 v78, v78, v93
	v_mul_f32_e32 v82, 0xbfb8aa3b, v78
	v_pk_mul_f32 v[92:93], v[14:15], v[160:161]
	v_exp_f32_e32 v82, v82
	v_add_f32_e32 v92, v23, v92
	v_add_f32_e32 v96, v92, v93
	v_pk_mul_f32 v[92:93], v[18:19], v[88:89]
	v_add_f32_e32 v82, 1.0, v82
	v_add_f32_e32 v92, v96, v92
	v_add_f32_e32 v239, v92, v93
	v_mul_f32_e32 v92, 0xbfb8aa3b, v239
	v_rcp_f32_e32 v82, v82
	v_exp_f32_e32 v92, v92
	v_lshlrev_b32_e32 v97, 16, v83
	v_lshlrev_b32_e32 v96, 16, v79
	v_pk_mov_b32 v[160:161], v[156:157], v[96:97] op_sel:[1,0]
	v_mul_f32_e32 v78, v78, v82
	v_add_f32_e32 v82, 1.0, v92
	v_pk_mul_f32 v[92:93], v[110:111], v[160:161]
	v_rcp_f32_e32 v82, v82
	v_add_f32_e32 v92, v104, v92
	v_add_f32_e32 v101, v92, v93
	v_mul_f32_e32 v92, 0xbfb8aa3b, v101
	v_exp_f32_e32 v104, v92
	v_pk_mul_f32 v[92:93], v[106:107], v[156:157]
	v_mul_f32_e32 v248, v239, v82
	v_add_f32_e32 v92, v24, v92
	v_add_f32_e32 v156, v92, v93
	v_add_f32_e32 v92, 1.0, v104
	v_rcp_f32_e32 v104, v92
	v_pk_mul_f32 v[92:93], v[110:111], v[96:97]
	v_and_b32_e32 v83, 0xffff0000, v83
	v_add_f32_e32 v92, v156, v92
	v_add_f32_e32 v92, v92, v93
	v_mul_f32_e32 v93, 0xbfb8aa3b, v92
; __device__ __forceinline__ unsigned cvt_pk_bf16(float lo, float hi) { unsigned r; asm volatile("v_cvt_pk_bf16_f32 %0, %1, %2" : "=v"(r) : "v"(lo), "v"(hi)); return r; }
; #define LAS __attribute__((address_space(3)))
; __device__ __forceinline__ float silu_f(float x) { return x * __builtin_amdgcn_rcpf(1.f + __expf(-x)); }
; template <bool NEED_C>
; __device__ __forceinline__ void ssd_stage(LAS unsigned char* lds, const bf16_t* XBC, const float* cw, const float* cb, const float* DT, const float* a_log, int c, int g, int tid, int lane, int wave) {
;     ...
;             for (int i = 0; i < 16; ++i) { float xv[8]; unpack8(raw[3 + i], xv);
;                 float o[8];
; #pragma unroll
;                 for (int e = 0; e < 8; ++e) { o[e] = silu_f(b[e] + w[0][e] * xw[0][e] + w[1][e] * xw[1][e] + w[2][e] * xw[2][e] + w[3][e] * xv[e]); xw[0][e] = xw[1][e]; xw[1][e] = xw[2][e]; xw[2][e] = xv[e]; }
;                 u32x4 pk; pk.x = cvt_pk_bf16(o[0], o[1]); pk.y = cvt_pk_bf16(o[2], o[3]); pk.z = cvt_pk_bf16(o[4], o[5]); pk.w = cvt_pk_bf16(o[6], o[7]);
;                 *(LAS u32x4*)(tile + off_b(seg * 16 + i, tch)) = pk; }
	v_exp_f32_e32 v93, v93
	v_and_b32_e32 v82, 0xffff0000, v79
	v_cvt_pk_bf16_f32 v156, v100, v78
	v_pk_mov_b32 v[238:239], v[154:155], v[82:83] op_sel:[1,0]
	v_add_f32_e32 v78, 1.0, v93
	v_rcp_f32_e32 v93, v78
	v_pk_mul_f32 v[78:79], v[20:21], v[238:239]
	v_mul_f32_e32 v100, v101, v104
	v_add_f32_e32 v78, v105, v78
	v_add_f32_e32 v101, v78, v79
	v_mul_f32_e32 v78, 0xbfb8aa3b, v101
	v_exp_f32_e32 v104, v78
	v_pk_mul_f32 v[78:79], v[16:17], v[154:155]
	v_mul_f32_e32 v249, v92, v93
	v_add_f32_e32 v78, v25, v78
	v_add_f32_e32 v105, v78, v79
	v_add_f32_e32 v78, 1.0, v104
	v_rcp_f32_e32 v104, v78
	v_pk_mul_f32 v[78:79], v[20:21], v[82:83]
	s_nop 0
	v_add_f32_e32 v78, v105, v78
	v_add_f32_e32 v240, v78, v79
	v_mul_f32_e32 v78, 0xbfb8aa3b, v240
	v_exp_f32_e32 v78, v78
	v_mul_f32_e32 v79, v101, v104
	v_cvt_pk_bf16_f32 v157, v100, v79
	v_lshlrev_b32_e32 v105, 16, v84
	v_add_f32_e32 v78, 1.0, v78
	v_rcp_f32_e32 v92, v78
	v_pk_mul_f32 v[78:79], v[94:95], v[158:159]
	v_lshlrev_b32_e32 v104, 16, v80
	v_add_f32_e32 v78, v10, v78
	v_pk_mov_b32 v[154:155], v[158:159], v[104:105] op_sel:[1,0]
	v_add_f32_e32 v93, v78, v79
	v_pk_mul_f32 v[78:79], v[98:99], v[154:155]
	v_mul_f32_e32 v250, v240, v92
	v_add_f32_e32 v78, v117, v78
	v_add_f32_e32 v100, v78, v79
	v_mul_f32_e32 v78, 0xbfb8aa3b, v100
	v_exp_f32_e32 v101, v78
	v_pk_mul_f32 v[78:79], v[98:99], v[104:105]
	s_nop 0
	v_add_f32_e32 v78, v93, v78
	v_add_f32_e32 v117, v78, v79
	v_mul_f32_e32 v78, 0xbfb8aa3b, v117
	v_exp_f32_e32 v78, v78
	v_add_f32_e32 v79, 1.0, v101
	v_rcp_f32_e32 v101, v79
	v_and_b32_e32 v79, 0xffff0000, v84
	v_add_f32_e32 v78, 1.0, v78
	v_rcp_f32_e32 v158, v78
	v_and_b32_e32 v78, 0xffff0000, v80
	v_pk_mov_b32 v[240:241], v[114:115], v[78:79] op_sel:[1,0]
	v_mul_f32_e32 v117, v117, v158
	v_pk_mul_f32 v[92:93], v[6:7], v[240:241]
	s_nop 0
	v_add_f32_e32 v80, v235, v92
	v_add_f32_e32 v80, v80, v93
	v_mul_f32_e32 v84, 0xbfb8aa3b, v80
	v_pk_mul_f32 v[92:93], v[2:3], v[114:115]
	v_exp_f32_e32 v84, v84
	v_add_f32_e32 v92, v11, v92
	v_add_f32_e32 v114, v92, v93
	v_pk_mul_f32 v[92:93], v[6:7], v[78:79]
	v_add_f32_e32 v84, 1.0, v84
	v_add_f32_e32 v92, v114, v92
	v_add_f32_e32 v114, v92, v93
	v_mul_f32_e32 v92, 0xbfb8aa3b, v114
	v_rcp_f32_e32 v84, v84
	v_exp_f32_e32 v92, v92
	v_lshlrev_b32_e32 v93, 16, v85
	v_mul_f32_e32 v115, v100, v101
	v_mul_f32_e32 v80, v80, v84
	v_add_f32_e32 v84, 1.0, v92
	v_lshlrev_b32_e32 v92, 16, v81
	v_pk_mov_b32 v[242:243], v[102:103], v[92:93] op_sel:[1,0]
	v_rcp_f32_e32 v84, v84
	v_pk_mul_f32 v[100:101], v[90:91], v[242:243]
	v_mul_f32_e32 v114, v114, v84
	v_add_f32_e32 v100, v244, v100
	v_add_f32_e32 v159, v100, v101
	v_mul_f32_e32 v100, 0xbfb8aa3b, v159
	v_exp_f32_e32 v158, v100
	v_pk_mul_f32 v[100:101], v[86:87], v[102:103]
	s_nop 0
	v_add_f32_e32 v100, v12, v100
	v_add_f32_e32 v102, v100, v101
	v_add_f32_e32 v100, 1.0, v158
	v_rcp_f32_e32 v103, v100
	v_pk_mul_f32 v[100:101], v[90:91], v[92:93]
	v_cvt_pk_bf16_f32 v158, v115, v80
	v_mul_f32_e32 v103, v159, v103
	v_add_f32_e32 v100, v102, v100
	v_add_f32_e32 v102, v100, v101
	v_mul_f32_e32 v100, 0xbfb8aa3b, v102
	v_exp_f32_e32 v100, v100
	s_nop 0
	v_add_f32_e32 v80, 1.0, v100
	v_pk_mul_f32 v[100:101], v[4:5], v[112:113]
	v_rcp_f32_e32 v115, v80
	v_add_f32_e32 v80, v13, v100
	v_add_f32_e32 v159, v80, v101
	v_and_b32_e32 v101, 0xffff0000, v85
	v_and_b32_e32 v100, 0xffff0000, v81
	v_pk_mov_b32 v[80:81], v[112:113], v[100:101] op_sel:[1,0]
	v_mul_f32_e32 v102, v102, v115
	v_pk_mul_f32 v[84:85], v[8:9], v[80:81]
	v_pk_mul_f32 v[80:81], v[4:5], v[80:81]
	v_add_f32_e32 v84, v245, v84
	v_add_f32_e32 v112, v84, v85
	v_mul_f32_e32 v84, 0xbfb8aa3b, v112
	v_exp_f32_e32 v113, v84
	v_pk_mul_f32 v[84:85], v[8:9], v[100:101]
	v_add_f32_e32 v80, v13, v80
	v_add_f32_e32 v84, v159, v84
	v_add_f32_e32 v84, v84, v85
	v_mul_f32_e32 v85, 0xbfb8aa3b, v84
	v_exp_f32_e32 v85, v85
	v_add_f32_e32 v113, 1.0, v113
	v_rcp_f32_e32 v113, v113
	v_add_f32_e32 v85, 1.0, v85
	v_rcp_f32_e32 v85, v85
	v_mul_f32_e32 v112, v112, v113
	v_cvt_pk_bf16_f32 v159, v103, v112
	ds_write_b128 v246, v[156:159] offset:256
	v_mul_f32_e32 v84, v84, v85
	v_cvt_pk_bf16_f32 v112, v247, v248
	v_cvt_pk_bf16_f32 v113, v249, v250
	v_cvt_pk_bf16_f32 v114, v117, v114
	v_cvt_pk_bf16_f32 v115, v102, v84
	v_xor_b32_e32 v84, 0x80, v116
	v_add3_u32 v84, v234, v84, v173
	ds_write_b128 v84, v[112:115] offset:512
	v_pk_mul_f32 v[84:85], v[150:151], v[162:163]
	v_add_f32_e32 v163, v80, v81
	v_add_f32_e32 v84, v22, v84
	v_add_f32_e32 v112, v84, v85
	v_pk_mul_f32 v[84:85], v[14:15], v[236:237]
	v_pk_mul_f32 v[80:81], v[150:151], v[108:109]
	v_add_f32_e32 v84, v23, v84
	v_add_f32_e32 v113, v84, v85
	v_pk_mul_f32 v[84:85], v[106:107], v[160:161]
	s_waitcnt vmcnt(11)
; __device__ __forceinline__ unsigned cvt_pk_bf16(float lo, float hi) { unsigned r; asm volatile("v_cvt_pk_bf16_f32 %0, %1, %2" : "=v"(r) : "v"(lo), "v"(hi)); return r; }
; #define LAS __attribute__((address_space(3)))
; __device__ __forceinline__ float silu_f(float x) { return x * __builtin_amdgcn_rcpf(1.f + __expf(-x)); }
; template <bool NEED_C>
; __device__ __forceinline__ void ssd_stage(LAS unsigned char* lds, const bf16_t* XBC, const float* cw, const float* cb, const float* DT, const float* a_log, int c, int g, int tid, int lane, int wave) {
;     ...
;             for (int i = 0; i < 16; ++i) { float xv[8]; unpack8(raw[3 + i], xv);
;                 float o[8];
; #pragma unroll
;                 for (int e = 0; e < 8; ++e) { o[e] = silu_f(b[e] + w[0][e] * xw[0][e] + w[1][e] * xw[1][e] + w[2][e] * xw[2][e] + w[3][e] * xv[e]); xw[0][e] = xw[1][e]; xw[1][e] = xw[2][e]; xw[2][e] = xv[e]; }
;                 u32x4 pk; pk.x = cvt_pk_bf16(o[0], o[1]); pk.y = cvt_pk_bf16(o[2], o[3]); pk.z = cvt_pk_bf16(o[4], o[5]); pk.w = cvt_pk_bf16(o[6], o[7]);
;                 *(LAS u32x4*)(tile + off_b(seg * 16 + i, tch)) = pk; }
	v_lshlrev_b32_e32 v103, 16, v74
	v_add_f32_e32 v84, v24, v84
	v_add_f32_e32 v114, v84, v85
	v_pk_mul_f32 v[84:85], v[16:17], v[238:239]
	v_lshlrev_b32_e32 v102, 16, v70
	v_add_f32_e32 v84, v25, v84
	v_add_f32_e32 v115, v84, v85
	v_pk_mul_f32 v[84:85], v[94:95], v[154:155]
	v_add_f32_e32 v80, v22, v80
	v_add_f32_e32 v84, v10, v84
	v_add_f32_e32 v117, v84, v85
	v_pk_mul_f32 v[84:85], v[2:3], v[240:241]
	v_pk_mov_b32 v[108:109], v[108:109], v[102:103] op_sel:[1,0]
	v_add_f32_e32 v84, v11, v84
	v_add_f32_e32 v160, v84, v85
	v_pk_mul_f32 v[84:85], v[86:87], v[242:243]
	s_nop 0
	v_add_f32_e32 v84, v12, v84
	v_add_f32_e32 v162, v84, v85
	v_add_f32_e32 v85, v80, v81
	v_pk_mul_f32 v[80:81], v[152:153], v[108:109]
	v_xor_b32_e32 v84, 0xc0, v116
	v_add_f32_e32 v80, v112, v80
	v_add_f32_e32 v112, v80, v81
	v_mul_f32_e32 v80, 0xbfb8aa3b, v112
	v_exp_f32_e32 v154, v80
	v_pk_mul_f32 v[80:81], v[152:153], v[102:103]
	v_add3_u32 v235, v234, v84, v173
	v_add_f32_e32 v80, v85, v80
	v_add_f32_e32 v156, v80, v81
	v_mul_f32_e32 v80, 0xbfb8aa3b, v156
	v_exp_f32_e32 v80, v80
	v_add_f32_e32 v81, 1.0, v154
	v_rcp_f32_e32 v157, v81
	v_and_b32_e32 v81, 0xffff0000, v74
	v_add_f32_e32 v80, 1.0, v80
	v_rcp_f32_e32 v158, v80
	v_and_b32_e32 v80, 0xffff0000, v70
	v_pk_mov_b32 v[154:155], v[88:89], v[80:81] op_sel:[1,0]
	v_mul_f32_e32 v157, v112, v157
	v_pk_mul_f32 v[84:85], v[18:19], v[154:155]
	v_mul_f32_e32 v236, v156, v158
	v_add_f32_e32 v70, v113, v84
	v_add_f32_e32 v70, v70, v85
	v_mul_f32_e32 v74, 0xbfb8aa3b, v70
	v_pk_mul_f32 v[84:85], v[14:15], v[88:89]
	v_exp_f32_e32 v74, v74
	v_add_f32_e32 v84, v23, v84
	v_add_f32_e32 v88, v84, v85
	v_pk_mul_f32 v[84:85], v[18:19], v[80:81]
	v_add_f32_e32 v74, 1.0, v74
	v_add_f32_e32 v84, v88, v84
	v_add_f32_e32 v159, v84, v85
	v_mul_f32_e32 v84, 0xbfb8aa3b, v159
	v_rcp_f32_e32 v74, v74
	v_exp_f32_e32 v84, v84
	v_lshlrev_b32_e32 v85, 16, v75
	v_and_b32_e32 v75, 0xffff0000, v75
	v_mul_f32_e32 v70, v70, v74
	v_add_f32_e32 v74, 1.0, v84
	v_lshlrev_b32_e32 v84, 16, v71
	v_pk_mov_b32 v[88:89], v[96:97], v[84:85] op_sel:[1,0]
	v_pk_mul_f32 v[96:97], v[106:107], v[96:97]
	v_pk_mul_f32 v[112:113], v[110:111], v[88:89]
	v_add_f32_e32 v96, v24, v96
	v_add_f32_e32 v112, v114, v112
	v_add_f32_e32 v113, v112, v113
	v_mul_f32_e32 v112, 0xbfb8aa3b, v113
	v_exp_f32_e32 v112, v112
	v_add_f32_e32 v114, v96, v97
	v_rcp_f32_e32 v74, v74
	v_add_f32_e32 v96, 1.0, v112
	v_rcp_f32_e32 v156, v96
	v_pk_mul_f32 v[96:97], v[110:111], v[84:85]
	v_mul_f32_e32 v237, v159, v74
	v_add_f32_e32 v96, v114, v96
	v_add_f32_e32 v96, v96, v97
	v_mul_f32_e32 v97, 0xbfb8aa3b, v96
	v_exp_f32_e32 v97, v97
	v_and_b32_e32 v74, 0xffff0000, v71
	v_cvt_pk_bf16_f32 v112, v157, v70
	v_mul_f32_e32 v113, v113, v156
	v_add_f32_e32 v70, 1.0, v97
	v_pk_mov_b32 v[156:157], v[82:83], v[74:75] op_sel:[1,0]
	v_rcp_f32_e32 v97, v70
	v_pk_mul_f32 v[70:71], v[20:21], v[156:157]
	v_mul_f32_e32 v238, v96, v97
	v_add_f32_e32 v70, v115, v70
	v_add_f32_e32 v114, v70, v71
	v_mul_f32_e32 v70, 0xbfb8aa3b, v114
	v_exp_f32_e32 v115, v70
	v_pk_mul_f32 v[70:71], v[16:17], v[82:83]
	v_lshlrev_b32_e32 v97, 16, v76
	v_add_f32_e32 v70, v25, v70
	v_add_f32_e32 v82, v70, v71
	v_add_f32_e32 v70, 1.0, v115
	v_rcp_f32_e32 v83, v70
	v_pk_mul_f32 v[70:71], v[20:21], v[74:75]
	v_lshlrev_b32_e32 v96, 16, v72
	v_add_f32_e32 v70, v82, v70
	v_add_f32_e32 v82, v70, v71
	v_mul_f32_e32 v70, 0xbfb8aa3b, v82
	v_exp_f32_e32 v70, v70
	v_mul_f32_e32 v71, v114, v83
	v_cvt_pk_bf16_f32 v113, v113, v71
	v_add_f32_e32 v70, 1.0, v70
	v_rcp_f32_e32 v83, v70
	v_pk_mul_f32 v[70:71], v[94:95], v[104:105]
	v_pk_mov_b32 v[104:105], v[104:105], v[96:97] op_sel:[1,0]
	v_add_f32_e32 v70, v10, v70
	v_add_f32_e32 v114, v70, v71
	v_pk_mul_f32 v[70:71], v[98:99], v[104:105]
	v_mul_f32_e32 v239, v82, v83
	v_add_f32_e32 v70, v117, v70
	v_add_f32_e32 v115, v70, v71
	v_mul_f32_e32 v70, 0xbfb8aa3b, v115
	v_exp_f32_e32 v117, v70
	v_pk_mul_f32 v[70:71], v[98:99], v[96:97]
	s_nop 0
	v_add_f32_e32 v70, v114, v70
	v_add_f32_e32 v114, v70, v71
	v_mul_f32_e32 v70, 0xbfb8aa3b, v114
	v_exp_f32_e32 v70, v70
	v_add_f32_e32 v71, 1.0, v117
	v_rcp_f32_e32 v117, v71
	v_and_b32_e32 v71, 0xffff0000, v76
	v_add_f32_e32 v70, 1.0, v70
	v_rcp_f32_e32 v161, v70
	v_and_b32_e32 v70, 0xffff0000, v72
	v_pk_mov_b32 v[158:159], v[78:79], v[70:71] op_sel:[1,0]
	v_pk_mul_f32 v[78:79], v[2:3], v[78:79]
	v_pk_mul_f32 v[82:83], v[6:7], v[158:159]
	v_add_f32_e32 v78, v11, v78
	v_add_f32_e32 v72, v160, v82
	v_add_f32_e32 v72, v72, v83
	v_mul_f32_e32 v76, 0xbfb8aa3b, v72
	v_exp_f32_e32 v76, v76
	v_add_f32_e32 v82, v78, v79
	v_pk_mul_f32 v[78:79], v[6:7], v[70:71]
	v_mul_f32_e32 v115, v115, v117
	v_add_f32_e32 v78, v82, v78
	v_add_f32_e32 v240, v78, v79
	v_add_f32_e32 v76, 1.0, v76
	v_mul_f32_e32 v78, 0xbfb8aa3b, v240
	v_rcp_f32_e32 v76, v76
	v_exp_f32_e32 v78, v78
	v_lshlrev_b32_e32 v79, 16, v77
	v_mul_f32_e32 v117, v114, v161
	v_mul_f32_e32 v72, v72, v76
	v_add_f32_e32 v76, 1.0, v78
	v_lshlrev_b32_e32 v78, 16, v73
	v_pk_mov_b32 v[160:161], v[92:93], v[78:79] op_sel:[1,0]
	v_rcp_f32_e32 v76, v76
	v_pk_mul_f32 v[82:83], v[90:91], v[160:161]
	v_mul_f32_e32 v240, v240, v76
	v_add_f32_e32 v82, v162, v82
	v_add_f32_e32 v162, v82, v83
	v_mul_f32_e32 v82, 0xbfb8aa3b, v162
	v_exp_f32_e32 v114, v82
	v_pk_mul_f32 v[82:83], v[86:87], v[92:93]
	s_nop 0
	v_add_f32_e32 v82, v12, v82
	v_add_f32_e32 v92, v82, v83
	v_add_f32_e32 v82, 1.0, v114
	v_rcp_f32_e32 v93, v82
	v_pk_mul_f32 v[82:83], v[90:91], v[78:79]
	v_cvt_pk_bf16_f32 v114, v115, v72
	v_mul_f32_e32 v93, v162, v93
	v_add_f32_e32 v82, v92, v82
	v_add_f32_e32 v92, v82, v83
	v_mul_f32_e32 v82, 0xbfb8aa3b, v92
	v_exp_f32_e32 v82, v82
	s_nop 0
; __device__ __forceinline__ unsigned cvt_pk_bf16(float lo, float hi) { unsigned r; asm volatile("v_cvt_pk_bf16_f32 %0, %1, %2" : "=v"(r) : "v"(lo), "v"(hi)); return r; }
; #define LAS __attribute__((address_space(3)))
; __device__ __forceinline__ float silu_f(float x) { return x * __builtin_amdgcn_rcpf(1.f + __expf(-x)); }
; template <bool NEED_C>
; __device__ __forceinline__ void ssd_stage(LAS unsigned char* lds, const bf16_t* XBC, const float* cw, const float* cb, const float* DT, const float* a_log, int c, int g, int tid, int lane, int wave) {
;     ...
;             for (int i = 0; i < 16; ++i) { float xv[8]; unpack8(raw[3 + i], xv);
;                 float o[8];
; #pragma unroll
;                 for (int e = 0; e < 8; ++e) { o[e] = silu_f(b[e] + w[0][e] * xw[0][e] + w[1][e] * xw[1][e] + w[2][e] * xw[2][e] + w[3][e] * xv[e]); xw[0][e] = xw[1][e]; xw[1][e] = xw[2][e]; xw[2][e] = xv[e]; }
;                 u32x4 pk; pk.x = cvt_pk_bf16(o[0], o[1]); pk.y = cvt_pk_bf16(o[2], o[3]); pk.z = cvt_pk_bf16(o[4], o[5]); pk.w = cvt_pk_bf16(o[6], o[7]);
;                 *(LAS u32x4*)(tile + off_b(seg * 16 + i, tch)) = pk; }
	v_add_f32_e32 v72, 1.0, v82
	v_pk_mul_f32 v[82:83], v[4:5], v[100:101]
	v_rcp_f32_e32 v115, v72
	v_add_f32_e32 v72, v13, v82
	v_add_f32_e32 v162, v72, v83
	v_and_b32_e32 v83, 0xffff0000, v77
	v_and_b32_e32 v82, 0xffff0000, v73
	v_pk_mov_b32 v[72:73], v[100:101], v[82:83] op_sel:[1,0]
	v_mul_f32_e32 v92, v92, v115
	v_pk_mul_f32 v[76:77], v[8:9], v[72:73]
	v_pk_mul_f32 v[72:73], v[4:5], v[72:73]
	v_add_f32_e32 v76, v163, v76
	v_add_f32_e32 v100, v76, v77
	v_mul_f32_e32 v76, 0xbfb8aa3b, v100
	v_exp_f32_e32 v101, v76
	v_pk_mul_f32 v[76:77], v[8:9], v[82:83]
	v_add_f32_e32 v72, v13, v72
	v_add_f32_e32 v76, v162, v76
	v_add_f32_e32 v76, v76, v77
	v_mul_f32_e32 v77, 0xbfb8aa3b, v76
	v_exp_f32_e32 v77, v77
	v_add_f32_e32 v101, 1.0, v101
	v_rcp_f32_e32 v101, v101
	v_add_f32_e32 v77, 1.0, v77
	v_rcp_f32_e32 v77, v77
	v_mul_f32_e32 v100, v100, v101
	v_cvt_pk_bf16_f32 v115, v93, v100
	ds_write_b128 v235, v[112:115] offset:768
	v_mul_f32_e32 v76, v76, v77
	v_cvt_pk_bf16_f32 v112, v236, v237
	v_cvt_pk_bf16_f32 v113, v238, v239
	v_cvt_pk_bf16_f32 v114, v117, v240
	v_cvt_pk_bf16_f32 v115, v92, v76
	v_xor_b32_e32 v76, 16, v116
	v_add3_u32 v76, v234, v76, v173
	ds_write_b128 v76, v[112:115] offset:1024
	v_pk_mul_f32 v[76:77], v[150:151], v[108:109]
	s_nop 0
	v_add_f32_e32 v76, v22, v76
	v_add_f32_e32 v100, v76, v77
	v_pk_mul_f32 v[76:77], v[14:15], v[154:155]
	s_nop 0
	v_add_f32_e32 v76, v23, v76
	v_add_f32_e32 v101, v76, v77
	v_pk_mul_f32 v[76:77], v[106:107], v[88:89]
	s_waitcnt vmcnt(9)
	v_lshlrev_b32_e32 v89, 16, v66
	v_add_f32_e32 v76, v24, v76
	v_add_f32_e32 v112, v76, v77
	v_pk_mul_f32 v[76:77], v[16:17], v[156:157]
	v_add_f32_e32 v157, v72, v73
	v_add_f32_e32 v76, v25, v76
	v_add_f32_e32 v114, v76, v77
	v_pk_mul_f32 v[76:77], v[94:95], v[104:105]
	v_pk_mul_f32 v[72:73], v[150:151], v[102:103]
	v_add_f32_e32 v76, v10, v76
	v_add_f32_e32 v115, v76, v77
	v_pk_mul_f32 v[76:77], v[2:3], v[158:159]
	v_lshlrev_b32_e32 v88, 16, v62
	v_add_f32_e32 v76, v11, v76
	v_add_f32_e32 v117, v76, v77
	v_pk_mul_f32 v[76:77], v[86:87], v[160:161]
	v_add_f32_e32 v72, v22, v72
	v_add_f32_e32 v76, v12, v76
	v_pk_mov_b32 v[92:93], v[102:103], v[88:89] op_sel:[1,0]
	v_add_f32_e32 v156, v76, v77
	v_add_f32_e32 v77, v72, v73
	v_pk_mul_f32 v[72:73], v[152:153], v[92:93]
	v_xor_b32_e32 v76, 0x50, v116
	v_add_f32_e32 v72, v100, v72
	v_add_f32_e32 v100, v72, v73
	v_mul_f32_e32 v72, 0xbfb8aa3b, v100
	v_exp_f32_e32 v102, v72
	v_pk_mul_f32 v[72:73], v[152:153], v[88:89]
	v_add3_u32 v158, v234, v76, v173
	v_add_f32_e32 v72, v77, v72
	v_add_f32_e32 v103, v72, v73
	v_mul_f32_e32 v72, 0xbfb8aa3b, v103
	v_exp_f32_e32 v72, v72
	v_add_f32_e32 v73, 1.0, v102
	v_rcp_f32_e32 v102, v73
	v_and_b32_e32 v73, 0xffff0000, v66
	v_add_f32_e32 v72, 1.0, v72
	v_rcp_f32_e32 v108, v72
	v_and_b32_e32 v72, 0xffff0000, v62
	v_pk_mov_b32 v[104:105], v[80:81], v[72:73] op_sel:[1,0]
	v_mul_f32_e32 v100, v100, v102
	v_pk_mul_f32 v[76:77], v[18:19], v[104:105]
	v_mul_f32_e32 v159, v103, v108
	v_add_f32_e32 v62, v101, v76
	v_add_f32_e32 v62, v62, v77
	v_mul_f32_e32 v66, 0xbfb8aa3b, v62
	v_pk_mul_f32 v[76:77], v[14:15], v[80:81]
	v_exp_f32_e32 v66, v66
	v_add_f32_e32 v76, v23, v76
	v_add_f32_e32 v80, v76, v77
	v_pk_mul_f32 v[76:77], v[18:19], v[72:73]
	v_add_f32_e32 v66, 1.0, v66
	v_add_f32_e32 v76, v80, v76
	v_add_f32_e32 v101, v76, v77
	v_mul_f32_e32 v76, 0xbfb8aa3b, v101
	v_rcp_f32_e32 v66, v66
	v_exp_f32_e32 v76, v76
	v_lshlrev_b32_e32 v77, 16, v67
	v_and_b32_e32 v67, 0xffff0000, v67
	v_mul_f32_e32 v62, v62, v66
	v_add_f32_e32 v66, 1.0, v76
	v_lshlrev_b32_e32 v76, 16, v63
	v_pk_mov_b32 v[108:109], v[84:85], v[76:77] op_sel:[1,0]
	v_rcp_f32_e32 v66, v66
	v_pk_mul_f32 v[80:81], v[110:111], v[108:109]
	v_cvt_pk_bf16_f32 v100, v100, v62
	s_nop 0
	v_add_f32_e32 v80, v112, v80
	v_add_f32_e32 v102, v80, v81
	v_mul_f32_e32 v80, 0xbfb8aa3b, v102
	v_exp_f32_e32 v103, v80
	v_pk_mul_f32 v[80:81], v[106:107], v[84:85]
	s_nop 0
	v_add_f32_e32 v80, v24, v80
	v_add_f32_e32 v84, v80, v81
	v_add_f32_e32 v80, 1.0, v103
	v_rcp_f32_e32 v85, v80
	v_pk_mul_f32 v[80:81], v[110:111], v[76:77]
	v_mul_f32_e32 v85, v102, v85
	v_add_f32_e32 v80, v84, v80
	v_add_f32_e32 v80, v80, v81
	v_mul_f32_e32 v81, 0xbfb8aa3b, v80
	v_exp_f32_e32 v81, v81
	v_mul_f32_e32 v84, v101, v66
	v_and_b32_e32 v66, 0xffff0000, v63
	v_pk_mov_b32 v[112:113], v[74:75], v[66:67] op_sel:[1,0]
	v_add_f32_e32 v62, 1.0, v81
	v_rcp_f32_e32 v81, v62
	v_pk_mul_f32 v[62:63], v[20:21], v[112:113]
	v_mul_f32_e32 v160, v80, v81
	v_add_f32_e32 v62, v114, v62
	v_add_f32_e32 v101, v62, v63
	v_mul_f32_e32 v62, 0xbfb8aa3b, v101
	v_exp_f32_e32 v102, v62
	v_pk_mul_f32 v[62:63], v[16:17], v[74:75]
	v_lshlrev_b32_e32 v81, 16, v68
	v_add_f32_e32 v62, v25, v62
	v_add_f32_e32 v74, v62, v63
	v_add_f32_e32 v62, 1.0, v102
	v_rcp_f32_e32 v75, v62
	v_pk_mul_f32 v[62:63], v[20:21], v[66:67]
	v_lshlrev_b32_e32 v80, 16, v64
	v_add_f32_e32 v62, v74, v62
	v_add_f32_e32 v74, v62, v63
	v_mul_f32_e32 v62, 0xbfb8aa3b, v74
	v_exp_f32_e32 v62, v62
	v_mul_f32_e32 v63, v101, v75
	v_cvt_pk_bf16_f32 v101, v85, v63
	v_add_f32_e32 v62, 1.0, v62
	v_rcp_f32_e32 v75, v62
	v_pk_mul_f32 v[62:63], v[94:95], v[96:97]
	v_pk_mov_b32 v[96:97], v[96:97], v[80:81] op_sel:[1,0]
	v_add_f32_e32 v62, v10, v62
	v_add_f32_e32 v85, v62, v63
	v_pk_mul_f32 v[62:63], v[98:99], v[96:97]
	v_mul_f32_e32 v161, v74, v75
	v_add_f32_e32 v62, v115, v62
	v_add_f32_e32 v102, v62, v63
	v_mul_f32_e32 v62, 0xbfb8aa3b, v102
	v_exp_f32_e32 v103, v62
	v_pk_mul_f32 v[62:63], v[98:99], v[80:81]
	s_nop 0
	v_add_f32_e32 v62, v85, v62
	v_add_f32_e32 v85, v62, v63
	v_mul_f32_e32 v62, 0xbfb8aa3b, v85
	v_exp_f32_e32 v62, v62
	v_add_f32_e32 v63, 1.0, v103
; __device__ __forceinline__ unsigned cvt_pk_bf16(float lo, float hi) { unsigned r; asm volatile("v_cvt_pk_bf16_f32 %0, %1, %2" : "=v"(r) : "v"(lo), "v"(hi)); return r; }
; #define LAS __attribute__((address_space(3)))
; __device__ __forceinline__ float silu_f(float x) { return x * __builtin_amdgcn_rcpf(1.f + __expf(-x)); }
; template <bool NEED_C>
; __device__ __forceinline__ void ssd_stage(LAS unsigned char* lds, const bf16_t* XBC, const float* cw, const float* cb, const float* DT, const float* a_log, int c, int g, int tid, int lane, int wave) {
;     ...
;             for (int i = 0; i < 16; ++i) { float xv[8]; unpack8(raw[3 + i], xv);
;                 float o[8];
; #pragma unroll
;                 for (int e = 0; e < 8; ++e) { o[e] = silu_f(b[e] + w[0][e] * xw[0][e] + w[1][e] * xw[1][e] + w[2][e] * xw[2][e] + w[3][e] * xv[e]); xw[0][e] = xw[1][e]; xw[1][e] = xw[2][e]; xw[2][e] = xv[e]; }
;                 u32x4 pk; pk.x = cvt_pk_bf16(o[0], o[1]); pk.y = cvt_pk_bf16(o[2], o[3]); pk.z = cvt_pk_bf16(o[4], o[5]); pk.w = cvt_pk_bf16(o[6], o[7]);
;                 *(LAS u32x4*)(tile + off_b(seg * 16 + i, tch)) = pk; }
	v_rcp_f32_e32 v103, v63
	v_and_b32_e32 v63, 0xffff0000, v68
	v_add_f32_e32 v62, 1.0, v62
	v_rcp_f32_e32 v154, v62
	v_and_b32_e32 v62, 0xffff0000, v64
	v_pk_mov_b32 v[114:115], v[70:71], v[62:63] op_sel:[1,0]
	v_pk_mul_f32 v[70:71], v[2:3], v[70:71]
	v_pk_mul_f32 v[74:75], v[6:7], v[114:115]
	v_add_f32_e32 v70, v11, v70
	v_add_f32_e32 v64, v117, v74
	v_add_f32_e32 v64, v64, v75
	v_mul_f32_e32 v68, 0xbfb8aa3b, v64
	v_exp_f32_e32 v68, v68
	v_add_f32_e32 v74, v70, v71
	v_pk_mul_f32 v[70:71], v[6:7], v[62:63]
	v_mul_f32_e32 v85, v85, v154
	v_add_f32_e32 v70, v74, v70
	v_add_f32_e32 v117, v70, v71
	v_add_f32_e32 v68, 1.0, v68
	v_mul_f32_e32 v70, 0xbfb8aa3b, v117
	v_rcp_f32_e32 v68, v68
	v_exp_f32_e32 v70, v70
	v_lshlrev_b32_e32 v71, 16, v69
	v_mul_f32_e32 v102, v102, v103
	v_mul_f32_e32 v64, v64, v68
	v_add_f32_e32 v68, 1.0, v70
	v_lshlrev_b32_e32 v70, 16, v65
	v_pk_mov_b32 v[154:155], v[78:79], v[70:71] op_sel:[1,0]
	v_rcp_f32_e32 v68, v68
	v_pk_mul_f32 v[74:75], v[90:91], v[154:155]
	v_cvt_pk_bf16_f32 v102, v102, v64
	v_mul_f32_e32 v117, v117, v68
	v_add_f32_e32 v74, v156, v74
	v_add_f32_e32 v103, v74, v75
	v_mul_f32_e32 v74, 0xbfb8aa3b, v103
	v_exp_f32_e32 v156, v74
	v_pk_mul_f32 v[74:75], v[86:87], v[78:79]
	s_nop 0
	v_add_f32_e32 v74, v12, v74
	v_add_f32_e32 v78, v74, v75
	v_add_f32_e32 v74, 1.0, v156
	v_rcp_f32_e32 v79, v74
	v_pk_mul_f32 v[74:75], v[90:91], v[70:71]
	v_mul_f32_e32 v79, v103, v79
	v_add_f32_e32 v74, v78, v74
	v_add_f32_e32 v78, v74, v75
	v_mul_f32_e32 v74, 0xbfb8aa3b, v78
	v_exp_f32_e32 v74, v74
	s_nop 0
	v_add_f32_e32 v64, 1.0, v74
	v_pk_mul_f32 v[74:75], v[4:5], v[82:83]
	v_rcp_f32_e32 v103, v64
	v_add_f32_e32 v64, v13, v74
	v_add_f32_e32 v156, v64, v75
	v_and_b32_e32 v75, 0xffff0000, v69
	v_and_b32_e32 v74, 0xffff0000, v65
	v_pk_mov_b32 v[64:65], v[82:83], v[74:75] op_sel:[1,0]
	v_mul_f32_e32 v78, v78, v103
	v_pk_mul_f32 v[68:69], v[8:9], v[64:65]
	v_pk_mul_f32 v[64:65], v[4:5], v[64:65]
	v_add_f32_e32 v68, v157, v68
	v_add_f32_e32 v82, v68, v69
	v_mul_f32_e32 v68, 0xbfb8aa3b, v82
	v_exp_f32_e32 v83, v68
	v_pk_mul_f32 v[68:69], v[8:9], v[74:75]
	v_add_f32_e32 v64, v13, v64
	v_add_f32_e32 v68, v156, v68
	v_add_f32_e32 v68, v68, v69
	v_mul_f32_e32 v69, 0xbfb8aa3b, v68
	v_exp_f32_e32 v69, v69
	v_add_f32_e32 v83, 1.0, v83
	v_rcp_f32_e32 v83, v83
	v_add_f32_e32 v69, 1.0, v69
	v_rcp_f32_e32 v69, v69
	v_mul_f32_e32 v82, v82, v83
	v_cvt_pk_bf16_f32 v103, v79, v82
	ds_write_b128 v158, v[100:103] offset:1280
	v_mul_f32_e32 v68, v68, v69
	v_cvt_pk_bf16_f32 v82, v159, v84
	v_cvt_pk_bf16_f32 v83, v160, v161
	v_cvt_pk_bf16_f32 v84, v85, v117
	v_cvt_pk_bf16_f32 v85, v78, v68
	v_xor_b32_e32 v68, 0x90, v116
	v_add3_u32 v68, v234, v68, v173
	ds_write_b128 v68, v[82:85] offset:1536
	v_pk_mul_f32 v[68:69], v[150:151], v[92:93]
	s_waitcnt vmcnt(7)
	v_lshlrev_b32_e32 v79, 16, v58
	v_add_f32_e32 v68, v22, v68
	v_add_f32_e32 v82, v68, v69
	v_pk_mul_f32 v[68:69], v[14:15], v[104:105]
	v_add_f32_e32 v105, v64, v65
	v_add_f32_e32 v68, v23, v68
	v_add_f32_e32 v83, v68, v69
	v_pk_mul_f32 v[68:69], v[106:107], v[108:109]
	v_pk_mul_f32 v[64:65], v[150:151], v[88:89]
	v_add_f32_e32 v68, v24, v68
	v_add_f32_e32 v84, v68, v69
	v_pk_mul_f32 v[68:69], v[16:17], v[112:113]
	v_lshlrev_b32_e32 v78, 16, v54
	v_add_f32_e32 v68, v25, v68
	v_add_f32_e32 v85, v68, v69
	v_pk_mul_f32 v[68:69], v[94:95], v[96:97]
	v_add_f32_e32 v64, v22, v64
	v_add_f32_e32 v68, v10, v68
	v_add_f32_e32 v100, v68, v69
	v_pk_mul_f32 v[68:69], v[2:3], v[114:115]
	v_pk_mov_b32 v[88:89], v[88:89], v[78:79] op_sel:[1,0]
	v_add_f32_e32 v68, v11, v68
	v_add_f32_e32 v102, v68, v69
	v_pk_mul_f32 v[68:69], v[86:87], v[154:155]
	s_nop 0
	v_add_f32_e32 v68, v12, v68
	v_add_f32_e32 v104, v68, v69
	v_add_f32_e32 v69, v64, v65
	v_pk_mul_f32 v[64:65], v[152:153], v[88:89]
	v_xor_b32_e32 v68, 0xd0, v116
	v_add_f32_e32 v64, v82, v64
	v_add_f32_e32 v82, v64, v65
	v_mul_f32_e32 v64, 0xbfb8aa3b, v82
	v_exp_f32_e32 v92, v64
	v_pk_mul_f32 v[64:65], v[152:153], v[78:79]
	v_add3_u32 v108, v234, v68, v173
	v_add_f32_e32 v64, v69, v64
	v_add_f32_e32 v96, v64, v65
	v_mul_f32_e32 v64, 0xbfb8aa3b, v96
	v_exp_f32_e32 v64, v64
	v_add_f32_e32 v65, 1.0, v92
	v_rcp_f32_e32 v97, v65
	v_and_b32_e32 v65, 0xffff0000, v58
	v_add_f32_e32 v64, 1.0, v64
	v_rcp_f32_e32 v101, v64
	v_and_b32_e32 v64, 0xffff0000, v54
	v_pk_mov_b32 v[92:93], v[72:73], v[64:65] op_sel:[1,0]
	v_mul_f32_e32 v97, v82, v97
	v_pk_mul_f32 v[68:69], v[18:19], v[92:93]
	v_mul_f32_e32 v109, v96, v101
	v_add_f32_e32 v54, v83, v68
	v_add_f32_e32 v54, v54, v69
	v_mul_f32_e32 v58, 0xbfb8aa3b, v54
	v_pk_mul_f32 v[68:69], v[14:15], v[72:73]
	v_exp_f32_e32 v58, v58
	v_add_f32_e32 v68, v23, v68
	v_add_f32_e32 v72, v68, v69
	v_pk_mul_f32 v[68:69], v[18:19], v[64:65]
	v_add_f32_e32 v58, 1.0, v58
	v_add_f32_e32 v68, v72, v68
	v_add_f32_e32 v103, v68, v69
	v_mul_f32_e32 v68, 0xbfb8aa3b, v103
	v_rcp_f32_e32 v58, v58
	v_exp_f32_e32 v68, v68
	v_lshlrev_b32_e32 v69, 16, v59
	v_and_b32_e32 v59, 0xffff0000, v59
	v_mul_f32_e32 v54, v54, v58
	v_add_f32_e32 v58, 1.0, v68
	v_lshlrev_b32_e32 v68, 16, v55
	v_pk_mov_b32 v[72:73], v[76:77], v[68:69] op_sel:[1,0]
	v_pk_mul_f32 v[76:77], v[106:107], v[76:77]
	v_pk_mul_f32 v[82:83], v[110:111], v[72:73]
	v_add_f32_e32 v76, v24, v76
	v_add_f32_e32 v82, v84, v82
	v_add_f32_e32 v83, v82, v83
	v_mul_f32_e32 v82, 0xbfb8aa3b, v83
	v_exp_f32_e32 v82, v82
	v_add_f32_e32 v84, v76, v77
	v_rcp_f32_e32 v58, v58
	v_add_f32_e32 v76, 1.0, v82
	v_rcp_f32_e32 v96, v76
	v_pk_mul_f32 v[76:77], v[110:111], v[68:69]
	v_mul_f32_e32 v112, v103, v58
	v_add_f32_e32 v76, v84, v76
	v_add_f32_e32 v76, v76, v77
	v_mul_f32_e32 v77, 0xbfb8aa3b, v76
	v_exp_f32_e32 v77, v77
; __device__ __forceinline__ unsigned cvt_pk_bf16(float lo, float hi) { unsigned r; asm volatile("v_cvt_pk_bf16_f32 %0, %1, %2" : "=v"(r) : "v"(lo), "v"(hi)); return r; }
; #define LAS __attribute__((address_space(3)))
; __device__ __forceinline__ float silu_f(float x) { return x * __builtin_amdgcn_rcpf(1.f + __expf(-x)); }
; template <bool NEED_C>
; __device__ __forceinline__ void ssd_stage(LAS unsigned char* lds, const bf16_t* XBC, const float* cw, const float* cb, const float* DT, const float* a_log, int c, int g, int tid, int lane, int wave) {
;     ...
;             for (int i = 0; i < 16; ++i) { float xv[8]; unpack8(raw[3 + i], xv);
;                 float o[8];
; #pragma unroll
;                 for (int e = 0; e < 8; ++e) { o[e] = silu_f(b[e] + w[0][e] * xw[0][e] + w[1][e] * xw[1][e] + w[2][e] * xw[2][e] + w[3][e] * xv[e]); xw[0][e] = xw[1][e]; xw[1][e] = xw[2][e]; xw[2][e] = xv[e]; }
;                 u32x4 pk; pk.x = cvt_pk_bf16(o[0], o[1]); pk.y = cvt_pk_bf16(o[2], o[3]); pk.z = cvt_pk_bf16(o[4], o[5]); pk.w = cvt_pk_bf16(o[6], o[7]);
;                 *(LAS u32x4*)(tile + off_b(seg * 16 + i, tch)) = pk; }
	v_and_b32_e32 v58, 0xffff0000, v55
	v_cvt_pk_bf16_f32 v82, v97, v54
	v_mul_f32_e32 v83, v83, v96
	v_add_f32_e32 v54, 1.0, v77
	v_pk_mov_b32 v[96:97], v[66:67], v[58:59] op_sel:[1,0]
	v_rcp_f32_e32 v77, v54
	v_pk_mul_f32 v[54:55], v[20:21], v[96:97]
	v_mul_f32_e32 v113, v76, v77
	v_add_f32_e32 v54, v85, v54
	v_add_f32_e32 v84, v54, v55
	v_mul_f32_e32 v54, 0xbfb8aa3b, v84
	v_exp_f32_e32 v85, v54
	v_pk_mul_f32 v[54:55], v[16:17], v[66:67]
	v_lshlrev_b32_e32 v77, 16, v60
	v_add_f32_e32 v54, v25, v54
	v_add_f32_e32 v66, v54, v55
	v_add_f32_e32 v54, 1.0, v85
	v_rcp_f32_e32 v67, v54
	v_pk_mul_f32 v[54:55], v[20:21], v[58:59]
	v_lshlrev_b32_e32 v76, 16, v56
	v_add_f32_e32 v54, v66, v54
	v_add_f32_e32 v66, v54, v55
	v_mul_f32_e32 v54, 0xbfb8aa3b, v66
	v_exp_f32_e32 v54, v54
	v_mul_f32_e32 v55, v84, v67
	v_cvt_pk_bf16_f32 v83, v83, v55
	v_add_f32_e32 v54, 1.0, v54
	v_rcp_f32_e32 v67, v54
	v_pk_mul_f32 v[54:55], v[94:95], v[80:81]
	v_pk_mov_b32 v[80:81], v[80:81], v[76:77] op_sel:[1,0]
	v_add_f32_e32 v54, v10, v54
	v_add_f32_e32 v84, v54, v55
	v_pk_mul_f32 v[54:55], v[98:99], v[80:81]
	v_mul_f32_e32 v114, v66, v67
	v_add_f32_e32 v54, v100, v54
	v_add_f32_e32 v85, v54, v55
	v_mul_f32_e32 v54, 0xbfb8aa3b, v85
	v_exp_f32_e32 v100, v54
	v_pk_mul_f32 v[54:55], v[98:99], v[76:77]
	s_nop 0
	v_add_f32_e32 v54, v84, v54
	v_add_f32_e32 v84, v54, v55
	v_mul_f32_e32 v54, 0xbfb8aa3b, v84
	v_exp_f32_e32 v54, v54
	v_add_f32_e32 v55, 1.0, v100
	v_rcp_f32_e32 v103, v55
	v_and_b32_e32 v55, 0xffff0000, v60
	v_add_f32_e32 v54, 1.0, v54
	v_rcp_f32_e32 v115, v54
	v_and_b32_e32 v54, 0xffff0000, v56
	v_pk_mov_b32 v[100:101], v[62:63], v[54:55] op_sel:[1,0]
	v_pk_mul_f32 v[62:63], v[2:3], v[62:63]
	v_pk_mul_f32 v[66:67], v[6:7], v[100:101]
	v_add_f32_e32 v62, v11, v62
	v_add_f32_e32 v56, v102, v66
	v_add_f32_e32 v56, v56, v67
	v_mul_f32_e32 v60, 0xbfb8aa3b, v56
	v_exp_f32_e32 v60, v60
	v_add_f32_e32 v66, v62, v63
	v_pk_mul_f32 v[62:63], v[6:7], v[54:55]
	v_lshlrev_b32_e32 v67, 16, v61
	v_add_f32_e32 v62, v66, v62
	v_add_f32_e32 v117, v62, v63
	v_add_f32_e32 v60, 1.0, v60
	v_mul_f32_e32 v62, 0xbfb8aa3b, v117
	v_rcp_f32_e32 v60, v60
	v_exp_f32_e32 v62, v62
	v_lshlrev_b32_e32 v66, 16, v57
	v_mul_f32_e32 v85, v85, v103
	v_pk_mov_b32 v[102:103], v[70:71], v[66:67] op_sel:[1,0]
	v_mul_f32_e32 v56, v56, v60
	v_add_f32_e32 v60, 1.0, v62
	v_pk_mul_f32 v[62:63], v[90:91], v[102:103]
	v_mul_f32_e32 v115, v84, v115
	v_add_f32_e32 v62, v104, v62
	v_add_f32_e32 v104, v62, v63
	v_mul_f32_e32 v62, 0xbfb8aa3b, v104
	v_exp_f32_e32 v84, v62
	v_pk_mul_f32 v[62:63], v[86:87], v[70:71]
	v_rcp_f32_e32 v60, v60
	v_add_f32_e32 v62, v12, v62
	v_add_f32_e32 v70, v62, v63
	v_add_f32_e32 v62, 1.0, v84
	v_rcp_f32_e32 v71, v62
	v_pk_mul_f32 v[62:63], v[90:91], v[66:67]
	v_cvt_pk_bf16_f32 v84, v85, v56
	v_mul_f32_e32 v117, v117, v60
	v_add_f32_e32 v62, v70, v62
	v_add_f32_e32 v154, v62, v63
	v_mul_f32_e32 v62, 0xbfb8aa3b, v154
	v_exp_f32_e32 v62, v62
	v_mul_f32_e32 v85, v104, v71
	v_and_b32_e32 v71, 0xffff0000, v61
	v_and_b32_e32 v70, 0xffff0000, v57
	v_add_f32_e32 v56, 1.0, v62
	v_pk_mul_f32 v[62:63], v[4:5], v[74:75]
	v_rcp_f32_e32 v104, v56
	v_add_f32_e32 v56, v13, v62
	v_add_f32_e32 v62, v56, v63
	v_pk_mov_b32 v[56:57], v[74:75], v[70:71] op_sel:[1,0]
	s_nop 0
	v_pk_mul_f32 v[60:61], v[8:9], v[56:57]
	v_pk_mul_f32 v[56:57], v[4:5], v[56:57]
	v_add_f32_e32 v60, v105, v60
	v_add_f32_e32 v63, v60, v61
	v_mul_f32_e32 v60, 0xbfb8aa3b, v63
	v_exp_f32_e32 v74, v60
	v_pk_mul_f32 v[60:61], v[8:9], v[70:71]
	v_add_f32_e32 v56, v13, v56
	v_add_f32_e32 v60, v62, v60
	v_add_f32_e32 v60, v60, v61
	v_mul_f32_e32 v61, 0xbfb8aa3b, v60
	v_exp_f32_e32 v61, v61
	v_add_f32_e32 v62, 1.0, v74
	v_rcp_f32_e32 v62, v62
	v_mul_f32_e32 v74, v154, v104
	v_add_f32_e32 v61, 1.0, v61
	v_rcp_f32_e32 v61, v61
	v_mul_f32_e32 v62, v63, v62
	v_cvt_pk_bf16_f32 v85, v85, v62
	ds_write_b128 v108, v[82:85] offset:1792
	v_mul_f32_e32 v63, v60, v61
	v_cvt_pk_bf16_f32 v60, v109, v112
	v_cvt_pk_bf16_f32 v61, v113, v114
	v_cvt_pk_bf16_f32 v62, v115, v117
	v_cvt_pk_bf16_f32 v63, v74, v63
	v_xor_b32_e32 v74, 32, v116
	v_add3_u32 v74, v234, v74, v173
	ds_write_b128 v74, v[60:63] offset:2048
	v_pk_mul_f32 v[60:61], v[150:151], v[88:89]
	v_add_f32_e32 v89, v56, v57
	v_add_f32_e32 v60, v22, v60
	v_add_f32_e32 v62, v60, v61
	v_pk_mul_f32 v[60:61], v[14:15], v[92:93]
	v_pk_mul_f32 v[56:57], v[150:151], v[78:79]
	v_add_f32_e32 v60, v23, v60
	v_add_f32_e32 v63, v60, v61
	v_pk_mul_f32 v[60:61], v[106:107], v[72:73]
	s_waitcnt vmcnt(5)
; __device__ __forceinline__ unsigned cvt_pk_bf16(float lo, float hi) { unsigned r; asm volatile("v_cvt_pk_bf16_f32 %0, %1, %2" : "=v"(r) : "v"(lo), "v"(hi)); return r; }
; #define LAS __attribute__((address_space(3)))
; __device__ __forceinline__ float silu_f(float x) { return x * __builtin_amdgcn_rcpf(1.f + __expf(-x)); }
; template <bool NEED_C>
; __device__ __forceinline__ void ssd_stage(LAS unsigned char* lds, const bf16_t* XBC, const float* cw, const float* cb, const float* DT, const float* a_log, int c, int g, int tid, int lane, int wave) {
;     ...
;             for (int i = 0; i < 16; ++i) { float xv[8]; unpack8(raw[3 + i], xv);
;                 float o[8];
; #pragma unroll
;                 for (int e = 0; e < 8; ++e) { o[e] = silu_f(b[e] + w[0][e] * xw[0][e] + w[1][e] * xw[1][e] + w[2][e] * xw[2][e] + w[3][e] * xv[e]); xw[0][e] = xw[1][e]; xw[1][e] = xw[2][e]; xw[2][e] = xv[e]; }
;                 u32x4 pk; pk.x = cvt_pk_bf16(o[0], o[1]); pk.y = cvt_pk_bf16(o[2], o[3]); pk.z = cvt_pk_bf16(o[4], o[5]); pk.w = cvt_pk_bf16(o[6], o[7]);
;                 *(LAS u32x4*)(tile + off_b(seg * 16 + i, tch)) = pk; }
	v_lshlrev_b32_e32 v73, 16, v50
	v_add_f32_e32 v60, v24, v60
	v_add_f32_e32 v82, v60, v61
	v_pk_mul_f32 v[60:61], v[16:17], v[96:97]
	v_lshlrev_b32_e32 v72, 16, v46
	v_add_f32_e32 v60, v25, v60
	v_add_f32_e32 v83, v60, v61
	v_pk_mul_f32 v[60:61], v[94:95], v[80:81]
	v_add_f32_e32 v56, v22, v56
	v_add_f32_e32 v60, v10, v60
	v_add_f32_e32 v80, v60, v61
	v_pk_mul_f32 v[60:61], v[2:3], v[100:101]
	v_pk_mov_b32 v[74:75], v[78:79], v[72:73] op_sel:[1,0]
	v_add_f32_e32 v60, v11, v60
	v_add_f32_e32 v84, v60, v61
	v_pk_mul_f32 v[60:61], v[86:87], v[102:103]
	s_nop 0
	v_add_f32_e32 v60, v12, v60
	v_add_f32_e32 v88, v60, v61
	v_add_f32_e32 v61, v56, v57
	v_pk_mul_f32 v[56:57], v[152:153], v[74:75]
	v_xor_b32_e32 v60, 0x60, v116
	v_add_f32_e32 v56, v62, v56
	v_add_f32_e32 v62, v56, v57
	v_mul_f32_e32 v56, 0xbfb8aa3b, v62
	v_exp_f32_e32 v78, v56
	v_pk_mul_f32 v[56:57], v[152:153], v[72:73]
	v_add3_u32 v92, v234, v60, v173
	v_add_f32_e32 v56, v61, v56
	v_add_f32_e32 v81, v56, v57
	v_mul_f32_e32 v56, 0xbfb8aa3b, v81
	v_exp_f32_e32 v56, v56
	v_add_f32_e32 v57, 1.0, v78
	v_rcp_f32_e32 v85, v57
	v_and_b32_e32 v57, 0xffff0000, v50
	v_add_f32_e32 v56, 1.0, v56
	v_rcp_f32_e32 v93, v56
	v_and_b32_e32 v56, 0xffff0000, v46
	v_pk_mov_b32 v[78:79], v[64:65], v[56:57] op_sel:[1,0]
	v_mul_f32_e32 v85, v62, v85
	v_pk_mul_f32 v[60:61], v[18:19], v[78:79]
	v_lshlrev_b32_e32 v62, 16, v47
	v_add_f32_e32 v46, v63, v60
	v_add_f32_e32 v46, v46, v61
	v_mul_f32_e32 v50, 0xbfb8aa3b, v46
	v_pk_mul_f32 v[60:61], v[14:15], v[64:65]
	v_exp_f32_e32 v50, v50
	v_add_f32_e32 v60, v23, v60
	v_add_f32_e32 v63, v60, v61
	v_pk_mul_f32 v[60:61], v[18:19], v[56:57]
	v_add_f32_e32 v50, 1.0, v50
	v_add_f32_e32 v60, v63, v60
	v_add_f32_e32 v96, v60, v61
	v_mul_f32_e32 v60, 0xbfb8aa3b, v96
	v_rcp_f32_e32 v50, v50
	v_exp_f32_e32 v60, v60
	v_lshlrev_b32_e32 v63, 16, v51
	v_pk_mov_b32 v[64:65], v[68:69], v[62:63] op_sel:[1,0]
	v_mul_f32_e32 v46, v46, v50
	v_add_f32_e32 v50, 1.0, v60
	v_pk_mul_f32 v[60:61], v[110:111], v[64:65]
	v_mul_f32_e32 v93, v81, v93
	v_add_f32_e32 v60, v82, v60
	v_add_f32_e32 v81, v60, v61
	v_mul_f32_e32 v60, 0xbfb8aa3b, v81
	v_exp_f32_e32 v82, v60
	v_pk_mul_f32 v[60:61], v[106:107], v[68:69]
	v_rcp_f32_e32 v50, v50
	v_add_f32_e32 v60, v24, v60
	v_add_f32_e32 v68, v60, v61
	v_add_f32_e32 v60, 1.0, v82
	v_rcp_f32_e32 v69, v60
	v_pk_mul_f32 v[60:61], v[110:111], v[62:63]
	v_mul_f32_e32 v96, v96, v50
	v_add_f32_e32 v60, v68, v60
	v_add_f32_e32 v82, v60, v61
	v_mul_f32_e32 v60, 0xbfb8aa3b, v82
	v_exp_f32_e32 v60, v60
	v_and_b32_e32 v61, 0xffff0000, v51
	v_cvt_pk_bf16_f32 v46, v85, v46
	v_mul_f32_e32 v81, v81, v69
	v_add_f32_e32 v50, 1.0, v60
	v_and_b32_e32 v60, 0xffff0000, v47
	v_rcp_f32_e32 v85, v50
	v_pk_mov_b32 v[50:51], v[58:59], v[60:61] op_sel:[1,0]
	v_pk_mul_f32 v[58:59], v[16:17], v[58:59]
	v_pk_mul_f32 v[68:69], v[20:21], v[50:51]
	v_add_f32_e32 v58, v25, v58
	v_add_f32_e32 v47, v83, v68
	v_add_f32_e32 v47, v47, v69
	v_mul_f32_e32 v68, 0xbfb8aa3b, v47
	v_exp_f32_e32 v68, v68
	v_add_f32_e32 v69, v58, v59
	v_mul_f32_e32 v97, v82, v85
	v_add_f32_e32 v58, 1.0, v68
	v_rcp_f32_e32 v68, v58
	v_pk_mul_f32 v[58:59], v[20:21], v[60:61]
	v_mul_f32_e32 v47, v47, v68
	v_add_f32_e32 v58, v69, v58
	v_add_f32_e32 v83, v58, v59
	v_mul_f32_e32 v58, 0xbfb8aa3b, v83
	v_exp_f32_e32 v58, v58
	v_cvt_pk_bf16_f32 v47, v81, v47
	v_lshlrev_b32_e32 v69, 16, v52
	v_lshlrev_b32_e32 v68, 16, v48
	v_add_f32_e32 v58, 1.0, v58
	v_rcp_f32_e32 v81, v58
	v_pk_mul_f32 v[58:59], v[94:95], v[76:77]
	v_pk_mov_b32 v[76:77], v[76:77], v[68:69] op_sel:[1,0]
	v_add_f32_e32 v58, v10, v58
	v_add_f32_e32 v82, v58, v59
	v_pk_mul_f32 v[58:59], v[98:99], v[76:77]
	v_mul_f32_e32 v101, v83, v81
	v_add_f32_e32 v58, v80, v58
	v_add_f32_e32 v85, v58, v59
	v_mul_f32_e32 v58, 0xbfb8aa3b, v85
	v_exp_f32_e32 v80, v58
	v_pk_mul_f32 v[58:59], v[98:99], v[68:69]
	s_nop 0
	v_add_f32_e32 v58, v82, v58
	v_add_f32_e32 v100, v58, v59
	v_mul_f32_e32 v58, 0xbfb8aa3b, v100
	v_exp_f32_e32 v58, v58
	v_add_f32_e32 v59, 1.0, v80
	v_rcp_f32_e32 v102, v59
	v_and_b32_e32 v59, 0xffff0000, v52
	v_add_f32_e32 v58, 1.0, v58
	v_rcp_f32_e32 v103, v58
	v_and_b32_e32 v58, 0xffff0000, v48
	v_pk_mov_b32 v[80:81], v[54:55], v[58:59] op_sel:[1,0]
	v_pk_mul_f32 v[54:55], v[2:3], v[54:55]
	v_pk_mul_f32 v[82:83], v[6:7], v[80:81]
	v_add_f32_e32 v54, v11, v54
	v_add_f32_e32 v48, v84, v82
	v_add_f32_e32 v48, v48, v83
	v_mul_f32_e32 v52, 0xbfb8aa3b, v48
	v_exp_f32_e32 v52, v52
	v_add_f32_e32 v82, v54, v55
	v_pk_mul_f32 v[54:55], v[6:7], v[58:59]
	v_mul_f32_e32 v102, v85, v102
	v_add_f32_e32 v54, v82, v54
	v_add_f32_e32 v104, v54, v55
	v_add_f32_e32 v52, 1.0, v52
	v_mul_f32_e32 v54, 0xbfb8aa3b, v104
	v_rcp_f32_e32 v52, v52
	v_exp_f32_e32 v54, v54
	v_lshlrev_b32_e32 v55, 16, v53
	v_mul_f32_e32 v100, v100, v103
	v_mul_f32_e32 v48, v48, v52
	v_add_f32_e32 v52, 1.0, v54
	v_lshlrev_b32_e32 v54, 16, v49
	v_pk_mov_b32 v[82:83], v[66:67], v[54:55] op_sel:[1,0]
	v_pk_mul_f32 v[66:67], v[86:87], v[66:67]
	v_pk_mul_f32 v[84:85], v[90:91], v[82:83]
	v_add_f32_e32 v66, v12, v66
	v_add_f32_e32 v84, v88, v84
	v_add_f32_e32 v84, v84, v85
	v_mul_f32_e32 v85, 0xbfb8aa3b, v84
	v_exp_f32_e32 v85, v85
	v_add_f32_e32 v88, v66, v67
	v_rcp_f32_e32 v52, v52
	v_cvt_pk_bf16_f32 v48, v102, v48
	v_add_f32_e32 v66, 1.0, v85
	v_rcp_f32_e32 v85, v66
	v_pk_mul_f32 v[66:67], v[90:91], v[54:55]
	v_mul_f32_e32 v102, v104, v52
	v_add_f32_e32 v66, v88, v66
	v_add_f32_e32 v88, v66, v67
	v_mul_f32_e32 v66, 0xbfb8aa3b, v88
	v_exp_f32_e32 v66, v66
	v_mul_f32_e32 v84, v84, v85
	v_add_f32_e32 v52, 1.0, v66
	v_pk_mul_f32 v[66:67], v[4:5], v[70:71]
	v_rcp_f32_e32 v85, v52
	v_add_f32_e32 v52, v13, v66
	v_add_f32_e32 v103, v52, v67
	v_and_b32_e32 v67, 0xffff0000, v53
	v_and_b32_e32 v66, 0xffff0000, v49
	v_pk_mov_b32 v[52:53], v[70:71], v[66:67] op_sel:[1,0]
	v_mul_f32_e32 v85, v88, v85
	v_pk_mul_f32 v[70:71], v[8:9], v[52:53]
	s_nop 0
	v_add_f32_e32 v49, v89, v70
	v_add_f32_e32 v49, v49, v71
	v_mul_f32_e32 v70, 0xbfb8aa3b, v49
	v_exp_f32_e32 v89, v70
	v_pk_mul_f32 v[70:71], v[8:9], v[66:67]
	v_add_f32_e32 v89, 1.0, v89
	v_add_f32_e32 v70, v103, v70
	v_add_f32_e32 v70, v70, v71
	v_mul_f32_e32 v71, 0xbfb8aa3b, v70
	v_exp_f32_e32 v71, v71
	v_rcp_f32_e32 v89, v89
	v_add_f32_e32 v71, 1.0, v71
	v_rcp_f32_e32 v71, v71
	v_mul_f32_e32 v49, v49, v89
	v_cvt_pk_bf16_f32 v49, v84, v49
	ds_write_b128 v92, v[46:49] offset:2304
	v_mul_f32_e32 v49, v70, v71
	v_xor_b32_e32 v70, 0xa0, v116
	v_cvt_pk_bf16_f32 v46, v93, v96
	v_cvt_pk_bf16_f32 v47, v97, v101
	v_add3_u32 v70, v234, v70, v173
	v_cvt_pk_bf16_f32 v48, v100, v102
	v_cvt_pk_bf16_f32 v49, v85, v49
	ds_write_b128 v70, v[46:49] offset:2560
	v_pk_mul_f32 v[46:47], v[150:151], v[74:75]
	s_nop 0
	v_add_f32_e32 v46, v22, v46
	v_add_f32_e32 v48, v46, v47
	v_pk_mul_f32 v[46:47], v[14:15], v[78:79]
	s_nop 0
	v_add_f32_e32 v46, v23, v46
	v_add_f32_e32 v49, v46, v47
	v_pk_mul_f32 v[46:47], v[106:107], v[64:65]
	s_waitcnt vmcnt(3)
; __device__ __forceinline__ unsigned cvt_pk_bf16(float lo, float hi) { unsigned r; asm volatile("v_cvt_pk_bf16_f32 %0, %1, %2" : "=v"(r) : "v"(lo), "v"(hi)); return r; }
; #define LAS __attribute__((address_space(3)))
; __device__ __forceinline__ float silu_f(float x) { return x * __builtin_amdgcn_rcpf(1.f + __expf(-x)); }
; template <bool NEED_C>
; __device__ __forceinline__ void ssd_stage(LAS unsigned char* lds, const bf16_t* XBC, const float* cw, const float* cb, const float* DT, const float* a_log, int c, int g, int tid, int lane, int wave) {
;     ...
;             for (int i = 0; i < 16; ++i) { float xv[8]; unpack8(raw[3 + i], xv);
;                 float o[8];
; #pragma unroll
;                 for (int e = 0; e < 8; ++e) { o[e] = silu_f(b[e] + w[0][e] * xw[0][e] + w[1][e] * xw[1][e] + w[2][e] * xw[2][e] + w[3][e] * xv[e]); xw[0][e] = xw[1][e]; xw[1][e] = xw[2][e]; xw[2][e] = xv[e]; }
;                 u32x4 pk; pk.x = cvt_pk_bf16(o[0], o[1]); pk.y = cvt_pk_bf16(o[2], o[3]); pk.z = cvt_pk_bf16(o[4], o[5]); pk.w = cvt_pk_bf16(o[6], o[7]);
;                 *(LAS u32x4*)(tile + off_b(seg * 16 + i, tch)) = pk; }
	v_lshlrev_b32_e32 v65, 16, v42
	v_add_f32_e32 v46, v24, v46
	v_add_f32_e32 v78, v46, v47
	v_pk_mul_f32 v[46:47], v[16:17], v[50:51]
	v_lshlrev_b32_e32 v64, 16, v38
	v_add_f32_e32 v46, v25, v46
	v_add_f32_e32 v79, v46, v47
	v_pk_mul_f32 v[46:47], v[94:95], v[76:77]
	v_pk_mov_b32 v[70:71], v[72:73], v[64:65] op_sel:[1,0]
	v_add_f32_e32 v46, v10, v46
	v_add_f32_e32 v76, v46, v47
	v_pk_mul_f32 v[46:47], v[2:3], v[80:81]
	v_xor_b32_e32 v50, 0xe0, v116
	v_add_f32_e32 v46, v11, v46
	v_add_f32_e32 v77, v46, v47
	v_pk_mul_f32 v[46:47], v[86:87], v[82:83]
	v_add3_u32 v82, v234, v50, v173
	v_add_f32_e32 v46, v12, v46
	v_add_f32_e32 v80, v46, v47
	v_pk_mul_f32 v[46:47], v[4:5], v[52:53]
	v_and_b32_e32 v50, 0xffff0000, v38
	v_add_f32_e32 v46, v13, v46
	v_add_f32_e32 v81, v46, v47
	v_pk_mul_f32 v[46:47], v[150:151], v[72:73]
	s_nop 0
	v_add_f32_e32 v46, v22, v46
	v_add_f32_e32 v51, v46, v47
	v_pk_mul_f32 v[46:47], v[152:153], v[70:71]
	s_nop 0
	v_add_f32_e32 v46, v48, v46
	v_add_f32_e32 v48, v46, v47
	v_mul_f32_e32 v46, 0xbfb8aa3b, v48
	v_exp_f32_e32 v52, v46
	v_pk_mul_f32 v[46:47], v[152:153], v[64:65]
	s_nop 0
	v_add_f32_e32 v46, v51, v46
	v_add_f32_e32 v53, v46, v47
	v_mul_f32_e32 v46, 0xbfb8aa3b, v53
	v_exp_f32_e32 v46, v46
	v_and_b32_e32 v51, 0xffff0000, v42
	v_add_f32_e32 v47, 1.0, v52
	v_pk_mov_b32 v[72:73], v[56:57], v[50:51] op_sel:[1,0]
	v_add_f32_e32 v46, 1.0, v46
	v_rcp_f32_e32 v52, v47
	v_rcp_f32_e32 v74, v46
	v_pk_mul_f32 v[46:47], v[18:19], v[72:73]
	v_mul_f32_e32 v52, v48, v52
	v_add_f32_e32 v38, v49, v46
	v_add_f32_e32 v38, v38, v47
	v_mul_f32_e32 v42, 0xbfb8aa3b, v38
	v_pk_mul_f32 v[46:47], v[14:15], v[56:57]
	v_exp_f32_e32 v42, v42
	v_add_f32_e32 v46, v23, v46
	v_add_f32_e32 v49, v46, v47
	v_pk_mul_f32 v[46:47], v[18:19], v[50:51]
	v_add_f32_e32 v42, 1.0, v42
	v_add_f32_e32 v46, v49, v46
	v_add_f32_e32 v57, v46, v47
	v_mul_f32_e32 v46, 0xbfb8aa3b, v57
	v_rcp_f32_e32 v42, v42
	v_exp_f32_e32 v46, v46
	v_lshlrev_b32_e32 v49, 16, v43
	v_lshlrev_b32_e32 v48, 16, v39
	v_mul_f32_e32 v83, v53, v74
	v_pk_mov_b32 v[74:75], v[62:63], v[48:49] op_sel:[1,0]
	v_mul_f32_e32 v38, v38, v42
	v_add_f32_e32 v42, 1.0, v46
	v_pk_mul_f32 v[46:47], v[110:111], v[74:75]
	v_rcp_f32_e32 v42, v42
	v_add_f32_e32 v46, v78, v46
	v_add_f32_e32 v53, v46, v47
	v_mul_f32_e32 v46, 0xbfb8aa3b, v53
	v_exp_f32_e32 v56, v46
	v_pk_mul_f32 v[46:47], v[106:107], v[62:63]
	v_mul_f32_e32 v84, v57, v42
	v_add_f32_e32 v46, v24, v46
	v_add_f32_e32 v62, v46, v47
	v_add_f32_e32 v46, 1.0, v56
	v_rcp_f32_e32 v63, v46
	v_pk_mul_f32 v[46:47], v[110:111], v[48:49]
	v_cvt_pk_bf16_f32 v56, v52, v38
	v_mul_f32_e32 v42, v53, v63
	v_add_f32_e32 v46, v62, v46
	v_add_f32_e32 v78, v46, v47
	v_mul_f32_e32 v46, 0xbfb8aa3b, v78
	v_exp_f32_e32 v46, v46
	v_and_b32_e32 v47, 0xffff0000, v43
	v_add_f32_e32 v38, 1.0, v46
	v_and_b32_e32 v46, 0xffff0000, v39
	v_pk_mov_b32 v[62:63], v[60:61], v[46:47] op_sel:[1,0]
	v_rcp_f32_e32 v52, v38
	v_pk_mul_f32 v[38:39], v[20:21], v[62:63]
	v_mul_f32_e32 v78, v78, v52
	v_add_f32_e32 v38, v79, v38
	v_add_f32_e32 v43, v38, v39
	v_mul_f32_e32 v38, 0xbfb8aa3b, v43
	v_exp_f32_e32 v53, v38
	v_pk_mul_f32 v[38:39], v[16:17], v[60:61]
	v_lshlrev_b32_e32 v52, 16, v40
	v_add_f32_e32 v38, v25, v38
	v_add_f32_e32 v57, v38, v39
	v_add_f32_e32 v38, 1.0, v53
	v_rcp_f32_e32 v53, v38
	v_pk_mul_f32 v[38:39], v[20:21], v[46:47]
	s_nop 0
	v_add_f32_e32 v38, v57, v38
	v_add_f32_e32 v79, v38, v39
	v_mul_f32_e32 v38, 0xbfb8aa3b, v79
	v_exp_f32_e32 v38, v38
	v_mul_f32_e32 v39, v43, v53
	v_cvt_pk_bf16_f32 v57, v42, v39
	v_lshlrev_b32_e32 v53, 16, v44
	v_add_f32_e32 v38, 1.0, v38
	v_rcp_f32_e32 v42, v38
	v_pk_mul_f32 v[38:39], v[94:95], v[68:69]
	v_pk_mov_b32 v[60:61], v[68:69], v[52:53] op_sel:[1,0]
	v_add_f32_e32 v38, v10, v38
	v_add_f32_e32 v43, v38, v39
	v_pk_mul_f32 v[38:39], v[98:99], v[60:61]
	v_mul_f32_e32 v79, v79, v42
	v_add_f32_e32 v38, v76, v38
	v_add_f32_e32 v76, v38, v39
	v_mul_f32_e32 v38, 0xbfb8aa3b, v76
	v_exp_f32_e32 v68, v38
	v_pk_mul_f32 v[38:39], v[98:99], v[52:53]
	v_and_b32_e32 v42, 0xffff0000, v40
	v_add_f32_e32 v38, v43, v38
	v_add_f32_e32 v85, v38, v39
	v_mul_f32_e32 v38, 0xbfb8aa3b, v85
	v_exp_f32_e32 v38, v38
	v_and_b32_e32 v43, 0xffff0000, v44
	v_add_f32_e32 v39, 1.0, v68
	v_pk_mov_b32 v[68:69], v[58:59], v[42:43] op_sel:[1,0]
	v_add_f32_e32 v38, 1.0, v38
	v_rcp_f32_e32 v88, v39
	v_rcp_f32_e32 v89, v38
	v_pk_mul_f32 v[38:39], v[6:7], v[68:69]
	v_mul_f32_e32 v88, v76, v88
	v_add_f32_e32 v38, v77, v38
	v_add_f32_e32 v40, v38, v39
	v_mul_f32_e32 v38, 0xbfb8aa3b, v40
	v_exp_f32_e32 v44, v38
	v_pk_mul_f32 v[38:39], v[2:3], v[58:59]
	v_mul_f32_e32 v85, v85, v89
	v_add_f32_e32 v38, v11, v38
	v_add_f32_e32 v58, v38, v39
	v_add_f32_e32 v38, 1.0, v44
	v_rcp_f32_e32 v44, v38
	v_pk_mul_f32 v[38:39], v[6:7], v[42:43]
	v_mul_f32_e32 v40, v40, v44
	v_add_f32_e32 v38, v58, v38
	v_add_f32_e32 v92, v38, v39
	v_mul_f32_e32 v38, 0xbfb8aa3b, v92
	v_exp_f32_e32 v38, v38
	v_lshlrev_b32_e32 v39, 16, v45
	v_and_b32_e32 v45, 0xffff0000, v45
	v_add_f32_e32 v38, 1.0, v38
	v_rcp_f32_e32 v44, v38
	v_lshlrev_b32_e32 v38, 16, v41
	v_pk_mov_b32 v[76:77], v[54:55], v[38:39] op_sel:[1,0]
	v_pk_mul_f32 v[54:55], v[86:87], v[54:55]
	v_pk_mul_f32 v[58:59], v[90:91], v[76:77]
	v_add_f32_e32 v54, v12, v54
	v_add_f32_e32 v58, v80, v58
	v_add_f32_e32 v59, v58, v59
	v_mul_f32_e32 v58, 0xbfb8aa3b, v59
	v_exp_f32_e32 v58, v58
	v_add_f32_e32 v80, v54, v55
	v_add_f32_e32 v54, 1.0, v58
	v_rcp_f32_e32 v89, v54
	v_pk_mul_f32 v[54:55], v[90:91], v[38:39]
	v_cvt_pk_bf16_f32 v58, v88, v40
	v_mul_f32_e32 v88, v92, v44
	v_add_f32_e32 v54, v80, v54
	v_add_f32_e32 v80, v54, v55
	v_mul_f32_e32 v54, 0xbfb8aa3b, v80
; __device__ __forceinline__ unsigned cvt_pk_bf16(float lo, float hi) { unsigned r; asm volatile("v_cvt_pk_bf16_f32 %0, %1, %2" : "=v"(r) : "v"(lo), "v"(hi)); return r; }
; #define LAS __attribute__((address_space(3)))
; __device__ __forceinline__ float silu_f(float x) { return x * __builtin_amdgcn_rcpf(1.f + __expf(-x)); }
; template <bool NEED_C>
; __device__ __forceinline__ void ssd_stage(LAS unsigned char* lds, const bf16_t* XBC, const float* cw, const float* cb, const float* DT, const float* a_log, int c, int g, int tid, int lane, int wave) {
;     ...
;             for (int i = 0; i < 16; ++i) { float xv[8]; unpack8(raw[3 + i], xv);
;                 float o[8];
; #pragma unroll
;                 for (int e = 0; e < 8; ++e) { o[e] = silu_f(b[e] + w[0][e] * xw[0][e] + w[1][e] * xw[1][e] + w[2][e] * xw[2][e] + w[3][e] * xv[e]); xw[0][e] = xw[1][e]; xw[1][e] = xw[2][e]; xw[2][e] = xv[e]; }
;                 u32x4 pk; pk.x = cvt_pk_bf16(o[0], o[1]); pk.y = cvt_pk_bf16(o[2], o[3]); pk.z = cvt_pk_bf16(o[4], o[5]); pk.w = cvt_pk_bf16(o[6], o[7]);
;                 *(LAS u32x4*)(tile + off_b(seg * 16 + i, tch)) = pk; }
	v_exp_f32_e32 v54, v54
	v_mul_f32_e32 v59, v59, v89
	v_and_b32_e32 v44, 0xffff0000, v41
	v_add_f32_e32 v40, 1.0, v54
	v_pk_mul_f32 v[54:55], v[4:5], v[66:67]
	v_rcp_f32_e32 v89, v40
	v_add_f32_e32 v40, v13, v54
	v_add_f32_e32 v92, v40, v55
	v_pk_mov_b32 v[40:41], v[66:67], v[44:45] op_sel:[1,0]
	v_mul_f32_e32 v80, v80, v89
	v_pk_mul_f32 v[54:55], v[8:9], v[40:41]
	v_pk_mul_f32 v[40:41], v[4:5], v[40:41]
	v_add_f32_e32 v54, v81, v54
	v_add_f32_e32 v66, v54, v55
	v_mul_f32_e32 v54, 0xbfb8aa3b, v66
	v_exp_f32_e32 v67, v54
	v_pk_mul_f32 v[54:55], v[8:9], v[44:45]
	v_add_f32_e32 v40, v13, v40
	v_add_f32_e32 v54, v92, v54
	v_add_f32_e32 v54, v54, v55
	v_mul_f32_e32 v55, 0xbfb8aa3b, v54
	v_exp_f32_e32 v55, v55
	v_add_f32_e32 v67, 1.0, v67
	v_rcp_f32_e32 v67, v67
	v_add_f32_e32 v55, 1.0, v55
	v_rcp_f32_e32 v55, v55
	v_mul_f32_e32 v66, v66, v67
	v_cvt_pk_bf16_f32 v59, v59, v66
	ds_write_b128 v82, v[56:59] offset:2816
	v_xor_b32_e32 v58, 48, v116
	v_mul_f32_e32 v57, v54, v55
	v_cvt_pk_bf16_f32 v54, v83, v84
	v_cvt_pk_bf16_f32 v55, v78, v79
	v_add3_u32 v58, v234, v58, v173
	v_cvt_pk_bf16_f32 v56, v85, v88
	v_cvt_pk_bf16_f32 v57, v80, v57
	ds_write_b128 v58, v[54:57] offset:3072
	v_pk_mul_f32 v[54:55], v[150:151], v[70:71]
	v_xor_b32_e32 v59, 0x70, v116
	v_add_f32_e32 v54, v22, v54
	v_add_f32_e32 v58, v54, v55
	v_pk_mul_f32 v[54:55], v[14:15], v[72:73]
	v_add_f32_e32 v73, v40, v41
	v_add_f32_e32 v54, v23, v54
	v_add_f32_e32 v66, v54, v55
	v_pk_mul_f32 v[54:55], v[106:107], v[74:75]
	v_pk_mul_f32 v[40:41], v[150:151], v[64:65]
	v_add_f32_e32 v54, v24, v54
	v_add_f32_e32 v67, v54, v55
	v_pk_mul_f32 v[54:55], v[16:17], v[62:63]
	v_add_f32_e32 v40, v22, v40
	v_add_f32_e32 v54, v25, v54
	v_add_f32_e32 v70, v54, v55
	v_pk_mul_f32 v[54:55], v[94:95], v[60:61]
	v_add_f32_e32 v60, v40, v41
	v_add_f32_e32 v54, v10, v54
	v_add_f32_e32 v71, v54, v55
	v_pk_mul_f32 v[54:55], v[2:3], v[68:69]
	s_waitcnt vmcnt(2)
	v_lshlrev_b32_e32 v40, 16, v30
	v_add_f32_e32 v54, v11, v54
	v_add_f32_e32 v68, v54, v55
	v_pk_mul_f32 v[54:55], v[86:87], v[76:77]
	s_waitcnt vmcnt(1)
	v_lshlrev_b32_e32 v41, 16, v34
	v_add_f32_e32 v54, v12, v54
	v_add_f32_e32 v72, v54, v55
	v_pk_mov_b32 v[54:55], v[64:65], v[40:41] op_sel:[1,0]
	v_add3_u32 v74, v234, v59, v173
	v_pk_mul_f32 v[56:57], v[152:153], v[54:55]
	v_pk_mul_f32 v[54:55], v[150:151], v[54:55]
	v_add_f32_e32 v56, v58, v56
	v_add_f32_e32 v62, v56, v57
	v_mul_f32_e32 v56, 0xbfb8aa3b, v62
	v_exp_f32_e32 v58, v56
	v_pk_mul_f32 v[56:57], v[152:153], v[40:41]
	v_add_f32_e32 v22, v22, v54
	v_add_f32_e32 v40, v60, v56
	v_add_f32_e32 v40, v40, v57
	v_mul_f32_e32 v56, 0xbfb8aa3b, v40
	v_exp_f32_e32 v56, v56
	v_add_f32_e32 v57, 1.0, v58
	v_rcp_f32_e32 v63, v57
	v_and_b32_e32 v57, 0xffff0000, v34
	v_add_f32_e32 v56, 1.0, v56
	v_rcp_f32_e32 v64, v56
	v_and_b32_e32 v56, 0xffff0000, v30
	v_pk_mov_b32 v[58:59], v[50:51], v[56:57] op_sel:[1,0]
	v_pk_mul_f32 v[50:51], v[14:15], v[50:51]
	v_pk_mul_f32 v[60:61], v[18:19], v[58:59]
	v_add_f32_e32 v50, v23, v50
	v_add_f32_e32 v30, v66, v60
	v_add_f32_e32 v30, v30, v61
	v_mul_f32_e32 v34, 0xbfb8aa3b, v30
	v_exp_f32_e32 v34, v34
	v_add_f32_e32 v60, v50, v51
	v_pk_mul_f32 v[50:51], v[18:19], v[56:57]
	v_mul_f32_e32 v65, v62, v63
	v_add_f32_e32 v50, v60, v50
	v_add_f32_e32 v56, v50, v51
	v_add_f32_e32 v34, 1.0, v34
	v_mul_f32_e32 v50, 0xbfb8aa3b, v56
	v_rcp_f32_e32 v34, v34
	v_exp_f32_e32 v50, v50
	v_lshlrev_b32_e32 v51, 16, v35
	v_mul_f32_e32 v40, v40, v64
	v_mul_f32_e32 v30, v30, v34
	v_add_f32_e32 v34, 1.0, v50
	v_lshlrev_b32_e32 v50, 16, v31
	v_pk_mov_b32 v[60:61], v[48:49], v[50:51] op_sel:[1,0]
	v_pk_mul_f32 v[48:49], v[106:107], v[48:49]
	v_pk_mul_f32 v[62:63], v[110:111], v[60:61]
	v_add_f32_e32 v48, v24, v48
	v_add_f32_e32 v62, v67, v62
	v_add_f32_e32 v62, v62, v63
	v_mul_f32_e32 v63, 0xbfb8aa3b, v62
	v_exp_f32_e32 v63, v63
	v_add_f32_e32 v64, v48, v49
	v_rcp_f32_e32 v34, v34
	v_cvt_pk_bf16_f32 v30, v65, v30
	v_add_f32_e32 v48, 1.0, v63
	v_rcp_f32_e32 v63, v48
	v_pk_mul_f32 v[48:49], v[110:111], v[50:51]
	v_mul_f32_e32 v56, v56, v34
	v_add_f32_e32 v48, v64, v48
	v_add_f32_e32 v50, v48, v49
	v_mul_f32_e32 v48, 0xbfb8aa3b, v50
	v_exp_f32_e32 v48, v48
	v_and_b32_e32 v35, 0xffff0000, v35
	v_mul_f32_e32 v64, v62, v63
	v_pk_mul_f32 v[14:15], v[14:15], v[58:59]
	v_add_f32_e32 v34, 1.0, v48
	v_rcp_f32_e32 v65, v34
	v_and_b32_e32 v34, 0xffff0000, v31
	v_pk_mov_b32 v[48:49], v[46:47], v[34:35] op_sel:[1,0]
	v_pk_mul_f32 v[46:47], v[16:17], v[46:47]
	v_pk_mul_f32 v[62:63], v[20:21], v[48:49]
	v_add_f32_e32 v46, v25, v46
	v_add_f32_e32 v31, v70, v62
	v_add_f32_e32 v31, v31, v63
	v_mul_f32_e32 v62, 0xbfb8aa3b, v31
	v_exp_f32_e32 v62, v62
	v_add_f32_e32 v63, v46, v47
	v_mul_f32_e32 v50, v50, v65
	v_add_f32_e32 v14, v23, v14
	v_add_f32_e32 v46, 1.0, v62
	v_rcp_f32_e32 v62, v46
	v_pk_mul_f32 v[46:47], v[20:21], v[34:35]
	v_add_f32_e32 v23, v14, v15
	v_add_f32_e32 v34, v63, v46
	v_add_f32_e32 v34, v34, v47
	v_mul_f32_e32 v46, 0xbfb8aa3b, v34
	v_exp_f32_e32 v46, v46
	v_mul_f32_e32 v31, v31, v62
	v_cvt_pk_bf16_f32 v31, v64, v31
	v_add_f32_e32 v22, v22, v55
	v_add_f32_e32 v46, 1.0, v46
	v_rcp_f32_e32 v64, v46
	v_pk_mul_f32 v[46:47], v[94:95], v[52:53]
	v_mul_f32_e32 v34, v34, v64
	v_add_f32_e32 v46, v10, v46
	v_add_f32_e32 v65, v46, v47
	v_lshlrev_b32_e32 v46, 16, v32
	v_lshlrev_b32_e32 v47, 16, v36
	v_pk_mov_b32 v[52:53], v[52:53], v[46:47] op_sel:[1,0]
	s_nop 0
	v_pk_mul_f32 v[62:63], v[98:99], v[52:53]
	s_nop 0
	v_add_f32_e32 v62, v71, v62
	v_add_f32_e32 v69, v62, v63
	v_mul_f32_e32 v62, 0xbfb8aa3b, v69
	v_exp_f32_e32 v66, v62
	v_pk_mul_f32 v[62:63], v[98:99], v[46:47]
	s_nop 0
	v_add_f32_e32 v46, v65, v62
; __device__ __forceinline__ unsigned cvt_pk_bf16(float lo, float hi) { unsigned r; asm volatile("v_cvt_pk_bf16_f32 %0, %1, %2" : "=v"(r) : "v"(lo), "v"(hi)); return r; }
; #define LAS __attribute__((address_space(3)))
; __device__ __forceinline__ float silu_f(float x) { return x * __builtin_amdgcn_rcpf(1.f + __expf(-x)); }
; template <bool NEED_C>
; __device__ __forceinline__ void ssd_stage(LAS unsigned char* lds, const bf16_t* XBC, const float* cw, const float* cb, const float* DT, const float* a_log, int c, int g, int tid, int lane, int wave) {
;     ...
;             for (int i = 0; i < 16; ++i) { float xv[8]; unpack8(raw[3 + i], xv);
;                 float o[8];
; #pragma unroll
;                 for (int e = 0; e < 8; ++e) { o[e] = silu_f(b[e] + w[0][e] * xw[0][e] + w[1][e] * xw[1][e] + w[2][e] * xw[2][e] + w[3][e] * xv[e]); xw[0][e] = xw[1][e]; xw[1][e] = xw[2][e]; xw[2][e] = xv[e]; }
;                 u32x4 pk; pk.x = cvt_pk_bf16(o[0], o[1]); pk.y = cvt_pk_bf16(o[2], o[3]); pk.z = cvt_pk_bf16(o[4], o[5]); pk.w = cvt_pk_bf16(o[6], o[7]);
;                 *(LAS u32x4*)(tile + off_b(seg * 16 + i, tch)) = pk; }
	v_add_f32_e32 v46, v46, v63
	v_mul_f32_e32 v62, 0xbfb8aa3b, v46
	v_exp_f32_e32 v62, v62
	v_add_f32_e32 v63, 1.0, v66
	v_rcp_f32_e32 v70, v63
	v_and_b32_e32 v63, 0xffff0000, v36
	v_add_f32_e32 v62, 1.0, v62
	v_rcp_f32_e32 v71, v62
	v_and_b32_e32 v62, 0xffff0000, v32
	v_pk_mov_b32 v[64:65], v[42:43], v[62:63] op_sel:[1,0]
	v_pk_mul_f32 v[42:43], v[2:3], v[42:43]
	v_pk_mul_f32 v[66:67], v[6:7], v[64:65]
	v_add_f32_e32 v42, v11, v42
	v_add_f32_e32 v32, v68, v66
	v_add_f32_e32 v32, v32, v67
	v_mul_f32_e32 v36, 0xbfb8aa3b, v32
	v_exp_f32_e32 v36, v36
	v_add_f32_e32 v66, v42, v43
	v_pk_mul_f32 v[42:43], v[6:7], v[62:63]
	v_mul_f32_e32 v70, v69, v70
	v_add_f32_e32 v42, v66, v42
	v_add_f32_e32 v62, v42, v43
	v_add_f32_e32 v36, 1.0, v36
	v_mul_f32_e32 v42, 0xbfb8aa3b, v62
	v_rcp_f32_e32 v36, v36
	v_exp_f32_e32 v42, v42
	v_lshlrev_b32_e32 v43, 16, v37
	v_mul_f32_e32 v46, v46, v71
	v_mul_f32_e32 v32, v32, v36
	v_add_f32_e32 v36, 1.0, v42
	v_lshlrev_b32_e32 v42, 16, v33
	v_pk_mov_b32 v[66:67], v[38:39], v[42:43] op_sel:[1,0]
	v_pk_mul_f32 v[38:39], v[86:87], v[38:39]
	v_pk_mul_f32 v[68:69], v[90:91], v[66:67]
	v_add_f32_e32 v38, v12, v38
	v_add_f32_e32 v68, v72, v68
	v_add_f32_e32 v68, v68, v69
	v_mul_f32_e32 v69, 0xbfb8aa3b, v68
	v_exp_f32_e32 v69, v69
	v_add_f32_e32 v71, v38, v39
	v_rcp_f32_e32 v36, v36
	v_cvt_pk_bf16_f32 v32, v70, v32
	v_add_f32_e32 v38, 1.0, v69
	v_rcp_f32_e32 v69, v38
	v_pk_mul_f32 v[38:39], v[90:91], v[42:43]
	v_mul_f32_e32 v62, v62, v36
	v_add_f32_e32 v38, v71, v38
	v_add_f32_e32 v42, v38, v39
	v_mul_f32_e32 v38, 0xbfb8aa3b, v42
	v_exp_f32_e32 v38, v38
	v_mul_f32_e32 v68, v68, v69
	v_and_b32_e32 v37, 0xffff0000, v37
	v_pk_mul_f32 v[2:3], v[2:3], v[64:65]
	v_add_f32_e32 v36, 1.0, v38
	v_pk_mul_f32 v[38:39], v[4:5], v[44:45]
	v_rcp_f32_e32 v69, v36
	v_add_f32_e32 v36, v13, v38
	v_add_f32_e32 v70, v36, v39
	v_and_b32_e32 v36, 0xffff0000, v33
	v_pk_mov_b32 v[38:39], v[44:45], v[36:37] op_sel:[1,0]
	v_mul_f32_e32 v42, v42, v69
	v_pk_mul_f32 v[44:45], v[8:9], v[38:39]
	s_waitcnt vmcnt(0)
	v_lshlrev_b32_e32 v69, 16, v28
	v_add_f32_e32 v33, v73, v44
	v_add_f32_e32 v33, v33, v45
	v_mul_f32_e32 v44, 0xbfb8aa3b, v33
	v_exp_f32_e32 v71, v44
	v_pk_mul_f32 v[44:45], v[8:9], v[36:37]
	v_add_f32_e32 v2, v11, v2
	v_add_f32_e32 v36, v70, v44
	v_add_f32_e32 v36, v36, v45
	v_mul_f32_e32 v44, 0xbfb8aa3b, v36
	v_exp_f32_e32 v44, v44
	v_add_f32_e32 v45, 1.0, v71
	v_rcp_f32_e32 v45, v45
	v_add_f32_e32 v11, v2, v3
	v_add_f32_e32 v44, 1.0, v44
	v_rcp_f32_e32 v44, v44
	v_mul_f32_e32 v33, v33, v45
	v_cvt_pk_bf16_f32 v33, v68, v33
	ds_write_b128 v74, v[30:33] offset:3328
	v_mul_f32_e32 v33, v36, v44
	v_cvt_pk_bf16_f32 v30, v40, v56
	v_cvt_pk_bf16_f32 v31, v50, v34
	v_xor_b32_e32 v34, 0xb0, v116
	v_cvt_pk_bf16_f32 v32, v46, v62
	v_cvt_pk_bf16_f32 v33, v42, v33
	v_add3_u32 v34, v234, v34, v173
	ds_write_b128 v34, v[30:33] offset:3584
	v_and_b32_e32 v33, 0xffff0000, v26
	v_mov_b32_e32 v32, v57
	v_pk_mul_f32 v[14:15], v[18:19], v[32:33]
	v_lshlrev_b32_e32 v45, 16, v27
	v_add_f32_e32 v14, v23, v14
	v_add_f32_e32 v18, v14, v15
	v_mul_f32_e32 v14, 0xbfb8aa3b, v18
	v_exp_f32_e32 v19, v14
	v_pk_mul_f32 v[14:15], v[106:107], v[60:61]
	v_mov_b32_e32 v44, v51
	v_add_f32_e32 v14, v24, v14
	v_lshlrev_b32_e32 v31, 16, v26
	v_mov_b32_e32 v30, v41
	v_add_f32_e32 v23, v14, v15
	v_pk_mul_f32 v[14:15], v[110:111], v[44:45]
	v_pk_mul_f32 v[30:31], v[152:153], v[30:31]
	v_add_f32_e32 v14, v23, v14
	v_add_f32_e32 v22, v22, v30
	v_add_f32_e32 v23, v14, v15
	v_add_f32_e32 v22, v22, v31
	v_mul_f32_e32 v14, 0xbfb8aa3b, v23
	v_mul_f32_e32 v26, 0xbfb8aa3b, v22
	v_exp_f32_e32 v14, v14
	v_exp_f32_e32 v26, v26
	v_add_f32_e32 v15, 1.0, v19
	v_and_b32_e32 v31, 0xffff0000, v28
	v_add_f32_e32 v14, 1.0, v14
	v_add_f32_e32 v26, 1.0, v26
	v_rcp_f32_e32 v19, v15
	v_rcp_f32_e32 v28, v14
	v_pk_mul_f32 v[14:15], v[16:17], v[48:49]
	v_and_b32_e32 v27, 0xffff0000, v27
	v_rcp_f32_e32 v24, v26
	v_add_f32_e32 v14, v25, v14
	v_mov_b32_e32 v26, v35
	v_add_f32_e32 v16, v14, v15
	v_pk_mul_f32 v[14:15], v[20:21], v[26:27]
	v_mov_b32_e32 v68, v47
	v_add_f32_e32 v14, v16, v14
	v_add_f32_e32 v16, v14, v15
	v_mul_f32_e32 v14, 0xbfb8aa3b, v16
	v_exp_f32_e32 v14, v14
	v_mov_b32_e32 v30, v63
	v_pk_mul_f32 v[2:3], v[6:7], v[30:31]
	v_lshlrev_b32_e32 v41, 16, v29
	v_add_f32_e32 v14, 1.0, v14
	v_rcp_f32_e32 v20, v14
	v_pk_mul_f32 v[14:15], v[94:95], v[52:53]
	v_add_f32_e32 v2, v11, v2
	v_add_f32_e32 v10, v10, v14
	v_add_f32_e32 v10, v10, v15
	v_pk_mul_f32 v[14:15], v[98:99], v[68:69]
	v_add_f32_e32 v6, v2, v3
	v_add_f32_e32 v10, v10, v14
	v_add_f32_e32 v10, v10, v15
	v_mul_f32_e32 v14, 0xbfb8aa3b, v10
	v_exp_f32_e32 v14, v14
	v_mul_f32_e32 v2, 0xbfb8aa3b, v6
	v_exp_f32_e32 v2, v2
	v_mov_b32_e32 v40, v43
	v_add_f32_e32 v3, 1.0, v14
	v_rcp_f32_e32 v11, v3
	v_add_f32_e32 v14, 1.0, v2
	v_pk_mul_f32 v[2:3], v[86:87], v[66:67]
	v_and_b32_e32 v29, 0xffff0000, v29
	v_add_f32_e32 v2, v12, v2
	v_add_f32_e32 v12, v2, v3
	v_pk_mul_f32 v[2:3], v[90:91], v[40:41]
	v_mul_f32_e32 v18, v18, v19
	v_add_f32_e32 v2, v12, v2
	v_add_f32_e32 v12, v2, v3
	v_mul_f32_e32 v2, 0xbfb8aa3b, v12
	v_exp_f32_e32 v15, v2
	v_pk_mul_f32 v[2:3], v[4:5], v[38:39]
	v_mul_f32_e32 v19, v23, v28
	v_add_f32_e32 v2, v13, v2
	v_mov_b32_e32 v28, v37
	v_add_f32_e32 v4, v2, v3
	v_pk_mul_f32 v[2:3], v[8:9], v[28:29]
	v_add_f32_e32 v5, 1.0, v15
	v_add_f32_e32 v2, v4, v2
	v_add_f32_e32 v2, v2, v3
	v_mul_f32_e32 v3, 0xbfb8aa3b, v2
	v_exp_f32_e32 v3, v3
	v_rcp_f32_e32 v4, v14
	v_rcp_f32_e32 v5, v5
	v_mul_f32_e32 v17, v22, v24
	v_add_f32_e32 v3, 1.0, v3
	v_rcp_f32_e32 v3, v3
	v_mul_f32_e32 v4, v6, v4
	v_mul_f32_e32 v5, v12, v5
	v_mul_f32_e32 v7, v16, v20
	v_mul_f32_e32 v6, v2, v3
	v_mul_f32_e32 v8, v10, v11
	v_cvt_pk_bf16_f32 v2, v17, v18
	v_cvt_pk_bf16_f32 v3, v19, v7
	v_cvt_pk_bf16_f32 v4, v8, v4
	v_cvt_pk_bf16_f32 v5, v5, v6
	v_xor_b32_e32 v6, 0xf0, v116
	v_add3_u32 v6, v234, v6, v174
	ds_write_b128 v6, v[2:5]
	v_mov_b32_e32 v2, s90
; #define LAS __attribute__((address_space(3)))
; template <bool NEED_C>
; __device__ __forceinline__ void ssd_stage(LAS unsigned char* lds, const bf16_t* XBC, const float* cw, const float* cb, const float* DT, const float* a_log, int c, int g, int tid, int lane, int wave) {
;     ...
;     { const int l = tid >> 2, r = tid & 3, hd = 4 * g + r; const float dtv = DT[(size_t)(c * 128 + l) * 32 + hd]; const float a = -expf(a_log[hd]);
;       ((LAS float*)(lds + SSD_DT))[r * 128 + l] = dtv; ((LAS float*)(lds + SSD_ACS))[r * 128 + l] = dtv * a; }
;     __syncthreads();
;     if (wave < 4) { LAS float* ac = (LAS float*)(lds + SSD_ACS) + wave * 128; const float v0 = ac[2 * lane], v1 = ac[2 * lane + 1]; const float s = v0 + v1; float inc = s;
; #pragma unroll
;         for (int o = 1; o < 64; o <<= 1) { const float t = __shfl_up(inc, o); if (lane >= o) inc += t; }
;         ac[2 * lane] = inc - s + v0; ac[2 * lane + 1] = inc; }
.LBB0_524:
	s_or_b64 exec, exec, s[50:51]
	s_lshl_b32 s1, s89, 2
	s_waitcnt lgkmcnt(0)
	s_andn2_b64 vcc, exec, s[42:43]
	s_waitcnt vmcnt(0)
	v_mov_b32_e32 v6, v252
	v_mov_b32_e32 v2, v253
	v_mul_f32_e32 v3, 0x3fb8aa3b, v6
	v_fma_f32 v4, v6, s84, -v3
	v_rndne_f32_e32 v5, v3
	v_fmac_f32_e32 v4, 0x32a5705f, v6
	v_sub_f32_e32 v3, v3, v5
	v_add_f32_e32 v3, v3, v4
	v_cvt_i32_f32_e32 v5, v5
	v_exp_f32_e32 v3, v3
	v_cmp_ngt_f32_e64 s[24:25], s85, v6
	ds_write_b32 v198, v2
	v_ldexp_f32 v3, v3, v5
	v_cndmask_b32_e64 v3, 0, v3, s[24:25]
	v_cmp_nlt_f32_e64 s[24:25], s86, v6
	s_nop 1
	v_cndmask_b32_e64 v3, v232, v3, s[24:25]
	v_mul_f32_e64 v2, v2, -v3
	ds_write_b32 v199, v2
	s_waitcnt lgkmcnt(0)
	s_barrier
	s_cbranch_vccnz .LBB0_526
	v_add_u32_e32 v4, s54, v1
	ds_read_b64 v[2:3], v4
	v_and_b32_e32 v5, 64, v233
	v_add_u32_e32 v6, -1, v233
	v_cmp_lt_i32_e32 vcc, v6, v5
	v_add_u32_e32 v8, -4, v233
	s_waitcnt lgkmcnt(0)
	v_add_f32_e32 v7, v2, v3
	v_cndmask_b32_e32 v6, v6, v233, vcc
	v_lshlrev_b32_e32 v3, 2, v6
	ds_bpermute_b32 v3, v3, v7
	v_add_u32_e32 v6, -2, v233
	v_cmp_lt_i32_e32 vcc, v6, v5
	s_waitcnt lgkmcnt(0)
	v_add_f32_e32 v3, v7, v3
	v_cndmask_b32_e32 v6, v6, v233, vcc
	v_cndmask_b32_e64 v3, v3, v7, s[8:9]
	v_lshlrev_b32_e32 v6, 2, v6
	ds_bpermute_b32 v6, v6, v3
	v_cmp_lt_i32_e32 vcc, v8, v5
	s_waitcnt lgkmcnt(0)
	v_add_f32_e32 v6, v3, v6
	v_cndmask_b32_e32 v8, v8, v233, vcc
	v_cndmask_b32_e64 v3, v6, v3, s[10:11]
	v_lshlrev_b32_e32 v6, 2, v8
	ds_bpermute_b32 v6, v6, v3
	v_add_u32_e32 v8, -8, v233
	v_cmp_lt_i32_e32 vcc, v8, v5
	s_waitcnt lgkmcnt(0)
	v_add_f32_e32 v6, v3, v6
	v_cndmask_b32_e32 v8, v8, v233, vcc
	v_cndmask_b32_e64 v3, v6, v3, s[12:13]
	v_lshlrev_b32_e32 v6, 2, v8
	ds_bpermute_b32 v6, v6, v3
	v_add_u32_e32 v8, -16, v233
	v_cmp_lt_i32_e32 vcc, v8, v5
	s_waitcnt lgkmcnt(0)
	v_add_f32_e32 v6, v3, v6
	v_cndmask_b32_e32 v8, v8, v233, vcc
	v_cndmask_b32_e64 v3, v6, v3, s[14:15]
	v_lshlrev_b32_e32 v6, 2, v8
	ds_bpermute_b32 v6, v6, v3
	v_subrev_u32_e32 v8, 32, v233
	v_cmp_lt_i32_e32 vcc, v8, v5
	s_waitcnt lgkmcnt(0)
	v_add_f32_e32 v6, v3, v6
	v_cndmask_b32_e32 v5, v8, v233, vcc
	v_cndmask_b32_e64 v3, v6, v3, s[16:17]
	v_lshlrev_b32_e32 v5, 2, v5
	ds_bpermute_b32 v5, v5, v3
	s_waitcnt lgkmcnt(0)
	v_add_f32_e32 v5, v3, v5
	v_cndmask_b32_e64 v3, v5, v3, s[6:7]
	v_sub_f32_e32 v5, v3, v7
	v_add_f32_e32 v2, v2, v5
	ds_write_b64 v4, v[2:3]

; #define LAS __attribute__((address_space(3)))
; template <bool NEED_C>
; __device__ __forceinline__ void ssd_stage(LAS unsigned char* lds, const bf16_t* XBC, const float* cw, const float* cb, const float* DT, const float* a_log, int c, int g, int tid, int lane, int wave) {
;     ...
;         const int cgi = tid & 63, seg = tid >> 6;
;         int col, tch; LAS unsigned char* tile;
;         if (cgi < 32) { col = g * 256 + cgi * 8; tile = lds + SSD_XT + (cgi >> 4) * 32768; tch = cgi & 15; }
;         else if (cgi < 48) { col = 2048 + g * 128 + (cgi - 32) * 8; tile = lds + SSD_BT; tch = cgi - 32; }
;         else { col = 3072 + g * 128 + (cgi - 48) * 8; tile = lds + SSD_CT; tch = cgi - 48; }
;     ...
;     { const int l = tid >> 2, r = tid & 3, hd = 4 * g + r; const float dtv = DT[(size_t)(c * 128 + l) * 32 + hd]; const float a = -expf(a_log[hd]);
.LBB0_1036:
	s_and_b32 s42, s88, 7
	s_ashr_i32 s1, s88, 3
	s_lshl_b32 s1, s1, 7
	v_add_u32_e32 v2, s1, v144
	v_ashrrev_i32_e32 v3, 31, v2
	v_lshlrev_b64 v[2:3], 7, v[2:3]
	s_lshl_b32 s1, s42, 2
	v_or_b32_e32 v4, s1, v149
	v_lshlrev_b32_e32 v4, 2, v4
	v_mov_b32_e32 v5, v119
	s_waitcnt lgkmcnt(0)
	global_load_dword v252, v4, s[30:31]
	v_lshl_add_u64 v[2:3], s[36:37], 0, v[2:3]
	v_lshl_add_u64 v[2:3], v[2:3], 0, v[4:5]
	global_load_dword v253, v[2:3], off
	s_and_saveexec_b64 s[4:5], s[38:39]
	s_xor_b64 s[20:21], exec, s[4:5]
	s_cbranch_execz .LBB0_1042
	s_lshl_b32 s1, s42, 7
	s_and_saveexec_b64 s[4:5], s[40:41]
	s_xor_b64 s[58:59], exec, s[4:5]
	v_add_u32_e32 v118, s1, v139
	s_or_saveexec_b64 s[58:59], s[58:59]
	v_mov_b32_e32 v123, s63
	v_mov_b32_e32 v220, v138
	s_xor_b64 exec, exec, s[58:59]
	s_add_i32 s4, 0, 0x10000
	v_add_u32_e32 v118, s1, v140
	v_mov_b32_e32 v123, s4
	v_mov_b32_e32 v220, v1
	s_or_b64 exec, exec, s[58:59]

; __device__ __forceinline__ float silu_f(float x) { return x * __builtin_amdgcn_rcpf(1.f + __expf(-x)); }
; template <bool NEED_C>
; __device__ __forceinline__ void ssd_stage(LAS unsigned char* lds, const bf16_t* XBC, const float* cw, const float* cb, const float* DT, const float* a_log, int c, int g, int tid, int lane, int wave) {
;     ...
;             u32x4 raw[19];
; #pragma unroll
;             for (int k = 0; k < 19; ++k) { const int tt = t0 - 3 + k;
;                 if (k >= 3 || tt >= 0) raw[k] = *(const u32x4*)(XBC + (size_t)tt * XBCC + col);
;                 else raw[k] = (u32x4){0u, 0u, 0u, 0u}; }
;             asm volatile("" ::: "memory");
; #pragma unroll
;             for (int k = 0; k < 3; ++k) unpack8(raw[k], xw[k]);
; #pragma unroll
;             for (int i = 0; i < 16; ++i) { float xv[8]; unpack8(raw[3 + i], xv);
;                 float o[8];
; #pragma unroll
;                 for (int e = 0; e < 8; ++e) { o[e] = silu_f(b[e] + w[0][e] * xw[0][e] + w[1][e] * xw[1][e] + w[2][e] * xw[2][e] + w[3][e] * xv[e]); xw[0][e] = xw[1][e]; xw[1][e] = xw[2][e]; xw[2][e] = xv[e]; }
.LBB0_1050:
	s_or_b64 exec, exec, s[20:21]
	v_add_u32_e32 v30, s90, v145
	v_ashrrev_i32_e32 v31, 31, v30
	v_ashrrev_i32_e32 v29, 31, v28
	v_lshlrev_b64 v[30:31], 13, v[30:31]
	v_lshlrev_b64 v[28:29], 13, v[28:29]
	v_lshl_add_u64 v[30:31], v[26:27], 0, v[30:31]
	v_lshl_add_u64 v[26:27], v[26:27], 0, v[28:29]
	global_load_dwordx4 v[114:117], v[30:31], off
	v_add_co_u32_e32 v28, vcc, s3, v26
	s_nop 1
	v_addc_co_u32_e32 v29, vcc, 0, v27, vcc
	global_load_dwordx4 v[78:81], v[28:29], off
	v_add_co_u32_e32 v28, vcc, s68, v26
	s_nop 1
	v_addc_co_u32_e32 v29, vcc, 0, v27, vcc
	global_load_dwordx4 v[82:85], v[28:29], off
	v_add_co_u32_e32 v30, vcc, s67, v26
	s_nop 1
	v_addc_co_u32_e32 v31, vcc, 0, v27, vcc
	global_load_dwordx4 v[70:73], v[30:31], off
	v_add_co_u32_e32 v28, vcc, s69, v26
	s_nop 1
	v_addc_co_u32_e32 v29, vcc, 0, v27, vcc
	global_load_dwordx4 v[74:77], v[28:29], off
	v_add_co_u32_e32 v30, vcc, s65, v26
	s_nop 1
	v_addc_co_u32_e32 v31, vcc, 0, v27, vcc
	global_load_dwordx4 v[62:65], v[30:31], off
	v_add_co_u32_e32 v28, vcc, s70, v26
	s_nop 1
	v_addc_co_u32_e32 v29, vcc, 0, v27, vcc
	global_load_dwordx4 v[66:69], v[28:29], off
	v_add_co_u32_e32 v30, vcc, s71, v26
	s_nop 1
	v_addc_co_u32_e32 v31, vcc, 0, v27, vcc
	global_load_dwordx4 v[54:57], v[30:31], off
	v_add_co_u32_e32 v28, vcc, s72, v26
	s_nop 1
	v_addc_co_u32_e32 v29, vcc, 0, v27, vcc
	global_load_dwordx4 v[58:61], v[28:29], off
	v_add_co_u32_e32 v30, vcc, s62, v26
	s_nop 1
	v_addc_co_u32_e32 v31, vcc, 0, v27, vcc
	global_load_dwordx4 v[46:49], v[30:31], off
	v_add_co_u32_e32 v28, vcc, s73, v26
	s_nop 1
	v_addc_co_u32_e32 v29, vcc, 0, v27, vcc
	global_load_dwordx4 v[50:53], v[28:29], off
	v_add_co_u32_e32 v30, vcc, s75, v26
	s_nop 1
	v_addc_co_u32_e32 v31, vcc, 0, v27, vcc
	global_load_dwordx4 v[38:41], v[30:31], off
	v_add_co_u32_e32 v28, vcc, s80, v26
	s_nop 1
	v_addc_co_u32_e32 v29, vcc, 0, v27, vcc
	global_load_dwordx4 v[42:45], v[28:29], off
	v_add_co_u32_e32 v30, vcc, s81, v26
	s_nop 1
	v_addc_co_u32_e32 v31, vcc, 0, v27, vcc
	global_load_dwordx4 v[30:33], v[30:31], off
	v_add_co_u32_e32 v28, vcc, s82, v26
	s_nop 1
	v_addc_co_u32_e32 v29, vcc, 0, v27, vcc
	global_load_dwordx4 v[34:37], v[28:29], off
	v_add_co_u32_e32 v26, vcc, s83, v26
	s_nop 1
	v_addc_co_u32_e32 v27, vcc, 0, v27, vcc
	global_load_dwordx4 v[26:29], v[26:27], off
	s_waitcnt vmcnt(16)
	v_lshlrev_b32_e32 v227, 16, v98
	s_nop 0
	s_nop 0
	s_nop 0
	v_lshlrev_b32_e32 v226, 16, v94
	v_mov_b32_e32 v124, v106
	v_mov_b32_e32 v125, v14
	v_pk_mul_f32 v[250:251], v[124:125], v[226:227]
	v_lshlrev_b32_e32 v136, 16, v102
	v_add_f32_e32 v14, v22, v250
	v_mov_b32_e32 v126, v110
	v_mov_b32_e32 v127, v18
	v_add_f32_e32 v14, v14, v251
	v_and_b32_e32 v229, 0xffff0000, v98
	v_and_b32_e32 v228, 0xffff0000, v94
	v_and_b32_e32 v134, 0xffff0000, v102
	v_lshlrev_b32_e32 v230, 16, v95
	v_lshlrev_b32_e32 v231, 16, v99
	v_lshlrev_b32_e32 v130, 16, v103
	v_and_b32_e32 v233, 0xffff0000, v99
	v_and_b32_e32 v232, 0xffff0000, v95
	s_nop 0
	v_and_b32_e32 v235, 0xffff0000, v100
	s_nop 0
	s_nop 0
	s_nop 0
	v_and_b32_e32 v234, 0xffff0000, v96
	s_nop 0
	s_nop 0
	s_nop 0
	s_nop 0
	v_lshlrev_b32_e32 v236, 16, v97
	v_lshlrev_b32_e32 v237, 16, v101
	s_nop 0
	v_and_b32_e32 v101, 0xffff0000, v101
	s_nop 0
	s_nop 0
	s_nop 0
	s_lshl_b32 s1, s42, 2
	s_nop 0
	s_nop 0
	s_nop 0
	s_nop 0
	s_nop 0
	s_waitcnt vmcnt(15)
	v_lshlrev_b32_e32 v137, 16, v114
	v_pk_mul_f32 v[250:251], v[126:127], v[136:137]
	v_and_b32_e32 v135, 0xffff0000, v114
	v_add_f32_e32 v14, v14, v250
	v_add_f32_e32 v118, v14, v251
	v_mul_f32_e32 v14, 0xbfb8aa3b, v118
	v_exp_f32_e32 v14, v14
	v_lshlrev_b32_e32 v131, 16, v115
	v_lshlrev_b32_e32 v133, 16, v116
	s_nop 0
	v_add_f32_e32 v132, 1.0, v14
	v_mov_b32_e32 v14, v107
	v_pk_mul_f32 v[106:107], v[14:15], v[228:229]
	s_nop 0
	v_add_f32_e32 v18, v23, v106
	v_add_f32_e32 v94, v18, v107
	v_mov_b32_e32 v18, v111
	v_pk_mul_f32 v[106:107], v[18:19], v[134:135]
	s_nop 0
	v_add_f32_e32 v94, v94, v106
	v_add_f32_e32 v98, v94, v107
	v_mov_b32_e32 v106, v108
	v_mov_b32_e32 v107, v16
	v_pk_mul_f32 v[110:111], v[106:107], v[230:231]
	v_mul_f32_e32 v94, 0xbfb8aa3b, v98
	v_add_f32_e32 v16, v24, v110
	v_add_f32_e32 v16, v16, v111
	v_mov_b32_e32 v110, v112
	v_mov_b32_e32 v111, v20
	v_pk_mul_f32 v[128:129], v[110:111], v[130:131]
	v_exp_f32_e32 v94, v94
	v_add_f32_e32 v16, v16, v128
	v_add_f32_e32 v102, v16, v129
	v_mul_f32_e32 v16, 0xbfb8aa3b, v102
	v_exp_f32_e32 v16, v16
	v_add_f32_e32 v20, 1.0, v94
	v_rcp_f32_e32 v112, v20
	v_and_b32_e32 v129, 0xffff0000, v115
	v_add_f32_e32 v16, 1.0, v16
	v_rcp_f32_e32 v114, v16
	v_mov_b32_e32 v16, v109
	v_pk_mul_f32 v[94:95], v[16:17], v[232:233]
	v_and_b32_e32 v128, 0xffff0000, v103
	v_add_f32_e32 v20, v25, v94
	v_add_f32_e32 v99, v20, v95
	v_mov_b32_e32 v20, v113
	v_pk_mul_f32 v[94:95], v[20:21], v[128:129]
	v_rcp_f32_e32 v108, v132
	v_add_f32_e32 v94, v99, v94
	v_add_f32_e32 v113, v94, v95
	v_mul_f32_e32 v94, 0xbfb8aa3b, v113
	v_exp_f32_e32 v94, v94
	v_mul_f32_e32 v118, v118, v108
	v_mul_f32_e32 v221, v98, v112
	v_lshlrev_b32_e32 v109, 16, v100
	v_add_f32_e32 v94, 1.0, v94
	v_rcp_f32_e32 v112, v94
	v_lshlrev_b32_e32 v108, 16, v96
	v_mov_b32_e32 v94, v86
	v_mov_b32_e32 v95, v2
	v_pk_mul_f32 v[98:99], v[94:95], v[108:109]
	v_lshlrev_b32_e32 v132, 16, v104
	v_add_f32_e32 v2, v10, v98
	v_add_f32_e32 v2, v2, v99
	v_mov_b32_e32 v98, v90
	v_mov_b32_e32 v99, v6
	v_mul_f32_e32 v223, v102, v114
	v_pk_mul_f32 v[102:103], v[98:99], v[132:133]
	v_and_b32_e32 v115, 0xffff0000, v116
	v_add_f32_e32 v2, v2, v102
	v_add_f32_e32 v108, v2, v103
	v_mul_f32_e32 v2, 0xbfb8aa3b, v108
	v_exp_f32_e32 v90, v2
	v_mov_b32_e32 v2, v87
; __device__ __forceinline__ unsigned cvt_pk_bf16(float lo, float hi) { unsigned r; asm volatile("v_cvt_pk_bf16_f32 %0, %1, %2" : "=v"(r) : "v"(lo), "v"(hi)); return r; }
; #define LAS __attribute__((address_space(3)))
; __device__ __forceinline__ float silu_f(float x) { return x * __builtin_amdgcn_rcpf(1.f + __expf(-x)); }
; template <bool NEED_C>
; __device__ __forceinline__ void ssd_stage(LAS unsigned char* lds, const bf16_t* XBC, const float* cw, const float* cb, const float* DT, const float* a_log, int c, int g, int tid, int lane, int wave) {
;     ...
;             for (int i = 0; i < 16; ++i) { float xv[8]; unpack8(raw[3 + i], xv);
;                 float o[8];
; #pragma unroll
;                 for (int e = 0; e < 8; ++e) { o[e] = silu_f(b[e] + w[0][e] * xw[0][e] + w[1][e] * xw[1][e] + w[2][e] * xw[2][e] + w[3][e] * xv[e]); xw[0][e] = xw[1][e]; xw[1][e] = xw[2][e]; xw[2][e] = xv[e]; }
;                 u32x4 pk; pk.x = cvt_pk_bf16(o[0], o[1]); pk.y = cvt_pk_bf16(o[2], o[3]); pk.z = cvt_pk_bf16(o[4], o[5]); pk.w = cvt_pk_bf16(o[6], o[7]);
;                 *(LAS u32x4*)(tile + off_b(seg * 16 + i, tch)) = pk; }
	v_pk_mul_f32 v[86:87], v[2:3], v[234:235]
	v_and_b32_e32 v114, 0xffff0000, v104
	v_add_f32_e32 v6, v11, v86
	v_add_f32_e32 v96, v6, v87
	v_mov_b32_e32 v6, v91
	v_pk_mul_f32 v[86:87], v[6:7], v[114:115]
	v_lshlrev_b32_e32 v102, 16, v105
	v_add_f32_e32 v86, v96, v86
	v_add_f32_e32 v96, v86, v87
	v_mul_f32_e32 v86, 0xbfb8aa3b, v96
	v_exp_f32_e32 v86, v86
	v_add_f32_e32 v87, 1.0, v90
	v_rcp_f32_e32 v116, v87
	v_mov_b32_e32 v87, v4
	v_add_f32_e32 v222, 1.0, v86
	v_mov_b32_e32 v86, v88
	v_pk_mul_f32 v[90:91], v[86:87], v[236:237]
	v_lshlrev_b32_e32 v103, 16, v117
	v_add_f32_e32 v4, v12, v90
	v_add_f32_e32 v4, v4, v91
	v_mov_b32_e32 v90, v92
	v_mov_b32_e32 v91, v8
	v_mul_f32_e32 v104, v113, v112
	v_pk_mul_f32 v[112:113], v[90:91], v[102:103]
	v_and_b32_e32 v100, 0xffff0000, v97
	v_add_f32_e32 v4, v4, v112
	v_add_f32_e32 v92, v4, v113
	v_mul_f32_e32 v4, 0xbfb8aa3b, v92
	v_exp_f32_e32 v224, v4
	v_mov_b32_e32 v4, v89
	v_pk_mul_f32 v[88:89], v[4:5], v[100:101]
	s_nop 0
	s_nop 0
	s_nop 0
	v_add_f32_e32 v8, v13, v88
	s_nop 0
	s_nop 0
	v_add_f32_e32 v97, v8, v89
	v_and_b32_e32 v113, 0xffff0000, v117
	v_and_b32_e32 v112, 0xffff0000, v105
	v_mov_b32_e32 v8, v93
	s_nop 0
	v_pk_mul_f32 v[88:89], v[8:9], v[112:113]
	s_nop 0
	s_nop 0
	v_add_f32_e32 v88, v97, v88
	s_nop 0
	s_nop 0
	s_nop 0
	v_add_f32_e32 v88, v88, v89
	s_nop 0
	s_nop 0
	v_mul_f32_e32 v89, 0xbfb8aa3b, v88
	s_nop 0
	v_exp_f32_e32 v89, v89
	s_nop 0
	s_nop 0
	s_nop 0
	s_nop 0
	s_nop 0
	v_add_f32_e32 v89, 1.0, v89
	s_nop 0
	s_nop 0
	s_nop 0
	v_add_f32_e32 v97, 1.0, v224
	s_nop 0
	s_nop 0
	v_rcp_f32_e32 v89, v89
	s_nop 0
	s_nop 0
	s_nop 0
	s_nop 0
	v_rcp_f32_e32 v93, v222
	v_rcp_f32_e32 v97, v97
	s_nop 0
	s_nop 0
	v_mul_f32_e32 v105, v108, v116
	s_nop 0
	s_nop 0
	v_mul_f32_e32 v88, v88, v89
	v_lshlrev_b32_e32 v116, 4, v220
	s_nop 0
	s_nop 0
	s_nop 0
	v_mul_f32_e32 v93, v96, v93
	v_mul_f32_e32 v92, v92, v97
	v_cvt_pk_bf16_f32 v222, v118, v221
	v_cvt_pk_bf16_f32 v223, v223, v104
	v_cvt_pk_bf16_f32 v224, v105, v93
	v_cvt_pk_bf16_f32 v225, v92, v88
	v_add3_u32 v88, v123, v116, v147
	ds_write_b128 v88, v[222:225]
	v_pk_mov_b32 v[88:89], v[226:227], v[136:137] op_sel:[1,0]
	v_xor_b32_e32 v93, 64, v116
	v_pk_mul_f32 v[88:89], v[124:125], v[88:89]
	s_nop 0
	v_add_f32_e32 v88, v22, v88
	v_add_f32_e32 v92, v88, v89
	v_pk_mov_b32 v[88:89], v[228:229], v[134:135] op_sel:[1,0]
	s_nop 0
	v_pk_mul_f32 v[88:89], v[14:15], v[88:89]
	s_nop 0
	v_add_f32_e32 v88, v23, v88
	v_add_f32_e32 v96, v88, v89
	v_pk_mov_b32 v[88:89], v[230:231], v[130:131] op_sel:[1,0]
	v_add3_u32 v230, v123, v93, v147
	v_pk_mul_f32 v[88:89], v[106:107], v[88:89]
	s_nop 0
	v_add_f32_e32 v88, v24, v88
	v_add_f32_e32 v104, v88, v89
	v_pk_mov_b32 v[88:89], v[232:233], v[128:129] op_sel:[1,0]
	s_nop 0
	v_pk_mul_f32 v[88:89], v[16:17], v[88:89]
	s_nop 0
	v_add_f32_e32 v88, v25, v88
	v_add_f32_e32 v105, v88, v89
	v_pk_mov_b32 v[88:89], v[108:109], v[132:133] op_sel:[1,0]
	s_waitcnt vmcnt(13)
	v_lshlrev_b32_e32 v109, 16, v82
	v_pk_mul_f32 v[88:89], v[94:95], v[88:89]
	v_lshlrev_b32_e32 v108, 16, v78
	v_add_f32_e32 v88, v10, v88
	v_add_f32_e32 v117, v88, v89
	v_pk_mov_b32 v[88:89], v[234:235], v[114:115] op_sel:[1,0]
	s_nop 0
	v_pk_mul_f32 v[88:89], v[2:3], v[88:89]
	s_nop 0
	v_add_f32_e32 v88, v11, v88
	v_add_f32_e32 v118, v88, v89
	v_pk_mov_b32 v[88:89], v[236:237], v[102:103] op_sel:[1,0]
	s_nop 0
	v_pk_mul_f32 v[88:89], v[86:87], v[88:89]
	s_nop 0
	v_add_f32_e32 v88, v12, v88
	v_add_f32_e32 v228, v88, v89
	v_pk_mov_b32 v[88:89], v[100:101], v[112:113] op_sel:[1,0]
	s_nop 0
	v_pk_mul_f32 v[88:89], v[4:5], v[88:89]
	s_nop 0
	v_add_f32_e32 v88, v13, v88
	v_add_f32_e32 v229, v88, v89
	v_pk_mul_f32 v[88:89], v[124:125], v[136:137]
	v_pk_mov_b32 v[136:137], v[136:137], v[108:109] op_sel:[1,0]
	v_add_f32_e32 v88, v22, v88
	v_add_f32_e32 v97, v88, v89
	v_pk_mul_f32 v[88:89], v[126:127], v[136:137]
	s_nop 0
	v_add_f32_e32 v88, v92, v88
	v_add_f32_e32 v100, v88, v89
	v_mul_f32_e32 v88, 0xbfb8aa3b, v100
	v_exp_f32_e32 v92, v88
	v_pk_mul_f32 v[88:89], v[126:127], v[108:109]
	s_nop 0
	v_add_f32_e32 v88, v97, v88
	v_add_f32_e32 v97, v88, v89
	v_mul_f32_e32 v88, 0xbfb8aa3b, v97
	v_exp_f32_e32 v88, v88
	v_add_f32_e32 v89, 1.0, v92
	v_rcp_f32_e32 v101, v89
	v_and_b32_e32 v89, 0xffff0000, v82
	v_add_f32_e32 v88, 1.0, v88
	v_rcp_f32_e32 v222, v88
	v_and_b32_e32 v88, 0xffff0000, v78
	v_pk_mov_b32 v[220:221], v[134:135], v[88:89] op_sel:[1,0]
	v_mul_f32_e32 v100, v100, v101
	v_pk_mul_f32 v[92:93], v[18:19], v[220:221]
	v_mul_f32_e32 v231, v97, v222
	v_add_f32_e32 v78, v96, v92
	v_add_f32_e32 v78, v78, v93
	v_mul_f32_e32 v82, 0xbfb8aa3b, v78
	v_pk_mul_f32 v[92:93], v[14:15], v[134:135]
	v_exp_f32_e32 v82, v82
	v_add_f32_e32 v92, v23, v92
	v_add_f32_e32 v96, v92, v93
	v_pk_mul_f32 v[92:93], v[18:19], v[88:89]
	v_add_f32_e32 v82, 1.0, v82
	v_add_f32_e32 v92, v96, v92
	v_add_f32_e32 v223, v92, v93
	v_mul_f32_e32 v92, 0xbfb8aa3b, v223
	v_rcp_f32_e32 v82, v82
	v_exp_f32_e32 v92, v92
	v_lshlrev_b32_e32 v97, 16, v83
	v_lshlrev_b32_e32 v96, 16, v79
	v_pk_mov_b32 v[134:135], v[130:131], v[96:97] op_sel:[1,0]
	v_mul_f32_e32 v78, v78, v82
	v_add_f32_e32 v82, 1.0, v92
	v_pk_mul_f32 v[92:93], v[110:111], v[134:135]
	v_rcp_f32_e32 v82, v82
	v_add_f32_e32 v92, v104, v92
	v_add_f32_e32 v101, v92, v93
	v_mul_f32_e32 v92, 0xbfb8aa3b, v101
	v_exp_f32_e32 v104, v92
	v_pk_mul_f32 v[92:93], v[106:107], v[130:131]
	v_mul_f32_e32 v232, v223, v82
	v_add_f32_e32 v92, v24, v92
	v_add_f32_e32 v130, v92, v93
	v_add_f32_e32 v92, 1.0, v104
	v_rcp_f32_e32 v104, v92
	v_pk_mul_f32 v[92:93], v[110:111], v[96:97]
	v_and_b32_e32 v83, 0xffff0000, v83
	v_add_f32_e32 v92, v130, v92
	v_add_f32_e32 v92, v92, v93
; __device__ __forceinline__ unsigned cvt_pk_bf16(float lo, float hi) { unsigned r; asm volatile("v_cvt_pk_bf16_f32 %0, %1, %2" : "=v"(r) : "v"(lo), "v"(hi)); return r; }
; #define LAS __attribute__((address_space(3)))
; __device__ __forceinline__ float silu_f(float x) { return x * __builtin_amdgcn_rcpf(1.f + __expf(-x)); }
; template <bool NEED_C>
; __device__ __forceinline__ void ssd_stage(LAS unsigned char* lds, const bf16_t* XBC, const float* cw, const float* cb, const float* DT, const float* a_log, int c, int g, int tid, int lane, int wave) {
;     ...
;             for (int i = 0; i < 16; ++i) { float xv[8]; unpack8(raw[3 + i], xv);
;                 float o[8];
; #pragma unroll
;                 for (int e = 0; e < 8; ++e) { o[e] = silu_f(b[e] + w[0][e] * xw[0][e] + w[1][e] * xw[1][e] + w[2][e] * xw[2][e] + w[3][e] * xv[e]); xw[0][e] = xw[1][e]; xw[1][e] = xw[2][e]; xw[2][e] = xv[e]; }
;                 u32x4 pk; pk.x = cvt_pk_bf16(o[0], o[1]); pk.y = cvt_pk_bf16(o[2], o[3]); pk.z = cvt_pk_bf16(o[4], o[5]); pk.w = cvt_pk_bf16(o[6], o[7]);
;                 *(LAS u32x4*)(tile + off_b(seg * 16 + i, tch)) = pk; }
	v_mul_f32_e32 v93, 0xbfb8aa3b, v92
	v_exp_f32_e32 v93, v93
	v_and_b32_e32 v82, 0xffff0000, v79
	v_cvt_pk_bf16_f32 v130, v100, v78
	v_pk_mov_b32 v[222:223], v[128:129], v[82:83] op_sel:[1,0]
	v_add_f32_e32 v78, 1.0, v93
	v_rcp_f32_e32 v93, v78
	v_pk_mul_f32 v[78:79], v[20:21], v[222:223]
	v_mul_f32_e32 v100, v101, v104
	v_add_f32_e32 v78, v105, v78
	v_add_f32_e32 v101, v78, v79
	v_mul_f32_e32 v78, 0xbfb8aa3b, v101
	v_exp_f32_e32 v104, v78
	v_pk_mul_f32 v[78:79], v[16:17], v[128:129]
	v_mul_f32_e32 v233, v92, v93
	v_add_f32_e32 v78, v25, v78
	v_add_f32_e32 v105, v78, v79
	v_add_f32_e32 v78, 1.0, v104
	v_rcp_f32_e32 v104, v78
	v_pk_mul_f32 v[78:79], v[20:21], v[82:83]
	s_nop 0
	v_add_f32_e32 v78, v105, v78
	v_add_f32_e32 v224, v78, v79
	v_mul_f32_e32 v78, 0xbfb8aa3b, v224
	v_exp_f32_e32 v78, v78
	v_mul_f32_e32 v79, v101, v104
	v_cvt_pk_bf16_f32 v131, v100, v79
	v_lshlrev_b32_e32 v105, 16, v84
	v_add_f32_e32 v78, 1.0, v78
	v_rcp_f32_e32 v92, v78
	v_pk_mul_f32 v[78:79], v[94:95], v[132:133]
	v_lshlrev_b32_e32 v104, 16, v80
	v_add_f32_e32 v78, v10, v78
	v_pk_mov_b32 v[128:129], v[132:133], v[104:105] op_sel:[1,0]
	v_add_f32_e32 v93, v78, v79
	v_pk_mul_f32 v[78:79], v[98:99], v[128:129]
	v_mul_f32_e32 v234, v224, v92
	v_add_f32_e32 v78, v117, v78
	v_add_f32_e32 v100, v78, v79
	v_mul_f32_e32 v78, 0xbfb8aa3b, v100
	v_exp_f32_e32 v101, v78
	v_pk_mul_f32 v[78:79], v[98:99], v[104:105]
	s_nop 0
	v_add_f32_e32 v78, v93, v78
	v_add_f32_e32 v117, v78, v79
	v_mul_f32_e32 v78, 0xbfb8aa3b, v117
	v_exp_f32_e32 v78, v78
	v_add_f32_e32 v79, 1.0, v101
	v_rcp_f32_e32 v101, v79
	v_and_b32_e32 v79, 0xffff0000, v84
	v_add_f32_e32 v78, 1.0, v78
	v_rcp_f32_e32 v132, v78
	v_and_b32_e32 v78, 0xffff0000, v80
	v_pk_mov_b32 v[224:225], v[114:115], v[78:79] op_sel:[1,0]
	v_mul_f32_e32 v117, v117, v132
	v_pk_mul_f32 v[92:93], v[6:7], v[224:225]
	s_nop 0
	v_add_f32_e32 v80, v118, v92
	v_add_f32_e32 v80, v80, v93
	v_mul_f32_e32 v84, 0xbfb8aa3b, v80
	v_pk_mul_f32 v[92:93], v[2:3], v[114:115]
	v_exp_f32_e32 v84, v84
	v_add_f32_e32 v92, v11, v92
	v_add_f32_e32 v114, v92, v93
	v_pk_mul_f32 v[92:93], v[6:7], v[78:79]
	v_add_f32_e32 v84, 1.0, v84
	v_add_f32_e32 v92, v114, v92
	v_add_f32_e32 v114, v92, v93
	v_mul_f32_e32 v92, 0xbfb8aa3b, v114
	v_rcp_f32_e32 v84, v84
	v_exp_f32_e32 v92, v92
	v_lshlrev_b32_e32 v93, 16, v85
	v_mul_f32_e32 v115, v100, v101
	v_mul_f32_e32 v80, v80, v84
	v_add_f32_e32 v84, 1.0, v92
	v_lshlrev_b32_e32 v92, 16, v81
	v_pk_mov_b32 v[226:227], v[102:103], v[92:93] op_sel:[1,0]
	v_rcp_f32_e32 v84, v84
	v_pk_mul_f32 v[100:101], v[90:91], v[226:227]
	v_mul_f32_e32 v114, v114, v84
	v_add_f32_e32 v100, v228, v100
	v_add_f32_e32 v118, v100, v101
	v_mul_f32_e32 v100, 0xbfb8aa3b, v118
	v_exp_f32_e32 v132, v100
	v_pk_mul_f32 v[100:101], v[86:87], v[102:103]
	s_nop 0
	v_add_f32_e32 v100, v12, v100
	v_add_f32_e32 v102, v100, v101
	v_add_f32_e32 v100, 1.0, v132
	v_rcp_f32_e32 v103, v100
	v_pk_mul_f32 v[100:101], v[90:91], v[92:93]
	v_cvt_pk_bf16_f32 v132, v115, v80
	v_mul_f32_e32 v103, v118, v103
	v_add_f32_e32 v100, v102, v100
	v_add_f32_e32 v102, v100, v101
	v_mul_f32_e32 v100, 0xbfb8aa3b, v102
	v_exp_f32_e32 v100, v100
	s_nop 0
	v_add_f32_e32 v80, 1.0, v100
	v_pk_mul_f32 v[100:101], v[4:5], v[112:113]
	v_rcp_f32_e32 v115, v80
	v_add_f32_e32 v80, v13, v100
	v_add_f32_e32 v118, v80, v101
	v_and_b32_e32 v101, 0xffff0000, v85
	v_and_b32_e32 v100, 0xffff0000, v81
	v_pk_mov_b32 v[80:81], v[112:113], v[100:101] op_sel:[1,0]
	v_mul_f32_e32 v102, v102, v115
	v_pk_mul_f32 v[84:85], v[8:9], v[80:81]
	v_pk_mul_f32 v[80:81], v[4:5], v[80:81]
	v_add_f32_e32 v84, v229, v84
	v_add_f32_e32 v112, v84, v85
	v_mul_f32_e32 v84, 0xbfb8aa3b, v112
	v_exp_f32_e32 v113, v84
	v_pk_mul_f32 v[84:85], v[8:9], v[100:101]
	v_add_f32_e32 v80, v13, v80
	v_add_f32_e32 v84, v118, v84
	v_add_f32_e32 v84, v84, v85
	v_mul_f32_e32 v85, 0xbfb8aa3b, v84
	v_exp_f32_e32 v85, v85
	v_add_f32_e32 v113, 1.0, v113
	v_rcp_f32_e32 v113, v113
	v_add_f32_e32 v85, 1.0, v85
	v_rcp_f32_e32 v85, v85
	v_mul_f32_e32 v112, v112, v113
	v_cvt_pk_bf16_f32 v133, v103, v112
	ds_write_b128 v230, v[130:133] offset:256
	v_mul_f32_e32 v84, v84, v85
	v_cvt_pk_bf16_f32 v112, v231, v232
	v_cvt_pk_bf16_f32 v113, v233, v234
	v_cvt_pk_bf16_f32 v114, v117, v114
	v_cvt_pk_bf16_f32 v115, v102, v84
	v_xor_b32_e32 v84, 0x80, v116
	v_add3_u32 v84, v123, v84, v147
	ds_write_b128 v84, v[112:115] offset:512
	v_pk_mul_f32 v[84:85], v[124:125], v[136:137]
	v_add_f32_e32 v137, v80, v81
	v_add_f32_e32 v84, v22, v84
	v_add_f32_e32 v112, v84, v85
	v_pk_mul_f32 v[84:85], v[14:15], v[220:221]
	v_pk_mul_f32 v[80:81], v[124:125], v[108:109]
	v_add_f32_e32 v84, v23, v84
	v_add_f32_e32 v113, v84, v85
	v_pk_mul_f32 v[84:85], v[106:107], v[134:135]
	s_waitcnt vmcnt(11)
; __device__ __forceinline__ unsigned cvt_pk_bf16(float lo, float hi) { unsigned r; asm volatile("v_cvt_pk_bf16_f32 %0, %1, %2" : "=v"(r) : "v"(lo), "v"(hi)); return r; }
; #define LAS __attribute__((address_space(3)))
; __device__ __forceinline__ float silu_f(float x) { return x * __builtin_amdgcn_rcpf(1.f + __expf(-x)); }
; template <bool NEED_C>
; __device__ __forceinline__ void ssd_stage(LAS unsigned char* lds, const bf16_t* XBC, const float* cw, const float* cb, const float* DT, const float* a_log, int c, int g, int tid, int lane, int wave) {
;     ...
;             for (int i = 0; i < 16; ++i) { float xv[8]; unpack8(raw[3 + i], xv);
;                 float o[8];
; #pragma unroll
;                 for (int e = 0; e < 8; ++e) { o[e] = silu_f(b[e] + w[0][e] * xw[0][e] + w[1][e] * xw[1][e] + w[2][e] * xw[2][e] + w[3][e] * xv[e]); xw[0][e] = xw[1][e]; xw[1][e] = xw[2][e]; xw[2][e] = xv[e]; }
;                 u32x4 pk; pk.x = cvt_pk_bf16(o[0], o[1]); pk.y = cvt_pk_bf16(o[2], o[3]); pk.z = cvt_pk_bf16(o[4], o[5]); pk.w = cvt_pk_bf16(o[6], o[7]);
;                 *(LAS u32x4*)(tile + off_b(seg * 16 + i, tch)) = pk; }
	v_lshlrev_b32_e32 v103, 16, v74
	v_add_f32_e32 v84, v24, v84
	v_add_f32_e32 v114, v84, v85
	v_pk_mul_f32 v[84:85], v[16:17], v[222:223]
	v_lshlrev_b32_e32 v102, 16, v70
	v_add_f32_e32 v84, v25, v84
	v_add_f32_e32 v115, v84, v85
	v_pk_mul_f32 v[84:85], v[94:95], v[128:129]
	v_add_f32_e32 v80, v22, v80
	v_add_f32_e32 v84, v10, v84
	v_add_f32_e32 v117, v84, v85
	v_pk_mul_f32 v[84:85], v[2:3], v[224:225]
	v_pk_mov_b32 v[108:109], v[108:109], v[102:103] op_sel:[1,0]
	v_add_f32_e32 v84, v11, v84
	v_add_f32_e32 v118, v84, v85
	v_pk_mul_f32 v[84:85], v[86:87], v[226:227]
	s_nop 0
	v_add_f32_e32 v84, v12, v84
	v_add_f32_e32 v136, v84, v85
	v_add_f32_e32 v85, v80, v81
	v_pk_mul_f32 v[80:81], v[126:127], v[108:109]
	v_xor_b32_e32 v84, 0xc0, v116
	v_add_f32_e32 v80, v112, v80
	v_add_f32_e32 v112, v80, v81
	v_mul_f32_e32 v80, 0xbfb8aa3b, v112
	v_exp_f32_e32 v128, v80
	v_pk_mul_f32 v[80:81], v[126:127], v[102:103]
	v_add3_u32 v220, v123, v84, v147
	v_add_f32_e32 v80, v85, v80
	v_add_f32_e32 v130, v80, v81
	v_mul_f32_e32 v80, 0xbfb8aa3b, v130
	v_exp_f32_e32 v80, v80
	v_add_f32_e32 v81, 1.0, v128
	v_rcp_f32_e32 v131, v81
	v_and_b32_e32 v81, 0xffff0000, v74
	v_add_f32_e32 v80, 1.0, v80
	v_rcp_f32_e32 v132, v80
	v_and_b32_e32 v80, 0xffff0000, v70
	v_pk_mov_b32 v[128:129], v[88:89], v[80:81] op_sel:[1,0]
	v_mul_f32_e32 v131, v112, v131
	v_pk_mul_f32 v[84:85], v[18:19], v[128:129]
	v_mul_f32_e32 v221, v130, v132
	v_add_f32_e32 v70, v113, v84
	v_add_f32_e32 v70, v70, v85
	v_mul_f32_e32 v74, 0xbfb8aa3b, v70
	v_pk_mul_f32 v[84:85], v[14:15], v[88:89]
	v_exp_f32_e32 v74, v74
	v_add_f32_e32 v84, v23, v84
	v_add_f32_e32 v88, v84, v85
	v_pk_mul_f32 v[84:85], v[18:19], v[80:81]
	v_add_f32_e32 v74, 1.0, v74
	v_add_f32_e32 v84, v88, v84
	v_add_f32_e32 v133, v84, v85
	v_mul_f32_e32 v84, 0xbfb8aa3b, v133
	v_rcp_f32_e32 v74, v74
	v_exp_f32_e32 v84, v84
	v_lshlrev_b32_e32 v85, 16, v75
	v_and_b32_e32 v75, 0xffff0000, v75
	v_mul_f32_e32 v70, v70, v74
	v_add_f32_e32 v74, 1.0, v84
	v_lshlrev_b32_e32 v84, 16, v71
	v_pk_mov_b32 v[88:89], v[96:97], v[84:85] op_sel:[1,0]
	v_pk_mul_f32 v[96:97], v[106:107], v[96:97]
	v_pk_mul_f32 v[112:113], v[110:111], v[88:89]
	v_add_f32_e32 v96, v24, v96
	v_add_f32_e32 v112, v114, v112
	v_add_f32_e32 v113, v112, v113
	v_mul_f32_e32 v112, 0xbfb8aa3b, v113
	v_exp_f32_e32 v112, v112
	v_add_f32_e32 v114, v96, v97
	v_rcp_f32_e32 v74, v74
	v_add_f32_e32 v96, 1.0, v112
	v_rcp_f32_e32 v130, v96
	v_pk_mul_f32 v[96:97], v[110:111], v[84:85]
	v_mul_f32_e32 v222, v133, v74
	v_add_f32_e32 v96, v114, v96
	v_add_f32_e32 v96, v96, v97
	v_mul_f32_e32 v97, 0xbfb8aa3b, v96
	v_exp_f32_e32 v97, v97
	v_and_b32_e32 v74, 0xffff0000, v71
	v_cvt_pk_bf16_f32 v112, v131, v70
	v_mul_f32_e32 v113, v113, v130
	v_add_f32_e32 v70, 1.0, v97
	v_pk_mov_b32 v[130:131], v[82:83], v[74:75] op_sel:[1,0]
	v_rcp_f32_e32 v97, v70
	v_pk_mul_f32 v[70:71], v[20:21], v[130:131]
	v_mul_f32_e32 v223, v96, v97
	v_add_f32_e32 v70, v115, v70
	v_add_f32_e32 v114, v70, v71
	v_mul_f32_e32 v70, 0xbfb8aa3b, v114
	v_exp_f32_e32 v115, v70
	v_pk_mul_f32 v[70:71], v[16:17], v[82:83]
	v_lshlrev_b32_e32 v97, 16, v76
	v_add_f32_e32 v70, v25, v70
	v_add_f32_e32 v82, v70, v71
	v_add_f32_e32 v70, 1.0, v115
	v_rcp_f32_e32 v83, v70
	v_pk_mul_f32 v[70:71], v[20:21], v[74:75]
	v_lshlrev_b32_e32 v96, 16, v72
	v_add_f32_e32 v70, v82, v70
	v_add_f32_e32 v82, v70, v71
	v_mul_f32_e32 v70, 0xbfb8aa3b, v82
	v_exp_f32_e32 v70, v70
	v_mul_f32_e32 v71, v114, v83
	v_cvt_pk_bf16_f32 v113, v113, v71
	v_add_f32_e32 v70, 1.0, v70
	v_rcp_f32_e32 v83, v70
	v_pk_mul_f32 v[70:71], v[94:95], v[104:105]
	v_pk_mov_b32 v[104:105], v[104:105], v[96:97] op_sel:[1,0]
	v_add_f32_e32 v70, v10, v70
	v_add_f32_e32 v114, v70, v71
	v_pk_mul_f32 v[70:71], v[98:99], v[104:105]
	v_mul_f32_e32 v224, v82, v83
	v_add_f32_e32 v70, v117, v70
	v_add_f32_e32 v115, v70, v71
	v_mul_f32_e32 v70, 0xbfb8aa3b, v115
	v_exp_f32_e32 v117, v70
	v_pk_mul_f32 v[70:71], v[98:99], v[96:97]
	s_nop 0
	v_add_f32_e32 v70, v114, v70
	v_add_f32_e32 v114, v70, v71
	v_mul_f32_e32 v70, 0xbfb8aa3b, v114
	v_exp_f32_e32 v70, v70
	v_add_f32_e32 v71, 1.0, v117
	v_rcp_f32_e32 v117, v71
	v_and_b32_e32 v71, 0xffff0000, v76
	v_add_f32_e32 v70, 1.0, v70
	v_rcp_f32_e32 v134, v70
	v_and_b32_e32 v70, 0xffff0000, v72
	v_pk_mov_b32 v[132:133], v[78:79], v[70:71] op_sel:[1,0]
	v_pk_mul_f32 v[78:79], v[2:3], v[78:79]
	v_pk_mul_f32 v[82:83], v[6:7], v[132:133]
	v_add_f32_e32 v78, v11, v78
	v_add_f32_e32 v72, v118, v82
	v_add_f32_e32 v72, v72, v83
	v_mul_f32_e32 v76, 0xbfb8aa3b, v72
	v_exp_f32_e32 v76, v76
	v_add_f32_e32 v82, v78, v79
	v_pk_mul_f32 v[78:79], v[6:7], v[70:71]
	v_mul_f32_e32 v115, v115, v117
	v_add_f32_e32 v78, v82, v78
	v_add_f32_e32 v118, v78, v79
	v_add_f32_e32 v76, 1.0, v76
	v_mul_f32_e32 v78, 0xbfb8aa3b, v118
	v_rcp_f32_e32 v76, v76
	v_exp_f32_e32 v78, v78
	v_lshlrev_b32_e32 v79, 16, v77
	v_mul_f32_e32 v117, v114, v134
	v_mul_f32_e32 v72, v72, v76
	v_add_f32_e32 v76, 1.0, v78
	v_lshlrev_b32_e32 v78, 16, v73
	v_pk_mov_b32 v[134:135], v[92:93], v[78:79] op_sel:[1,0]
	v_rcp_f32_e32 v76, v76
	v_pk_mul_f32 v[82:83], v[90:91], v[134:135]
	v_mul_f32_e32 v118, v118, v76
	v_add_f32_e32 v82, v136, v82
	v_add_f32_e32 v136, v82, v83
	v_mul_f32_e32 v82, 0xbfb8aa3b, v136
	v_exp_f32_e32 v114, v82
	v_pk_mul_f32 v[82:83], v[86:87], v[92:93]
	s_nop 0
	v_add_f32_e32 v82, v12, v82
	v_add_f32_e32 v92, v82, v83
	v_add_f32_e32 v82, 1.0, v114
	v_rcp_f32_e32 v93, v82
	v_pk_mul_f32 v[82:83], v[90:91], v[78:79]
	v_cvt_pk_bf16_f32 v114, v115, v72
	v_mul_f32_e32 v93, v136, v93
	v_add_f32_e32 v82, v92, v82
	v_add_f32_e32 v92, v82, v83
	v_mul_f32_e32 v82, 0xbfb8aa3b, v92
	v_exp_f32_e32 v82, v82
	s_nop 0
; __device__ __forceinline__ unsigned cvt_pk_bf16(float lo, float hi) { unsigned r; asm volatile("v_cvt_pk_bf16_f32 %0, %1, %2" : "=v"(r) : "v"(lo), "v"(hi)); return r; }
; #define LAS __attribute__((address_space(3)))
; __device__ __forceinline__ float silu_f(float x) { return x * __builtin_amdgcn_rcpf(1.f + __expf(-x)); }
; template <bool NEED_C>
; __device__ __forceinline__ void ssd_stage(LAS unsigned char* lds, const bf16_t* XBC, const float* cw, const float* cb, const float* DT, const float* a_log, int c, int g, int tid, int lane, int wave) {
;     ...
;             for (int i = 0; i < 16; ++i) { float xv[8]; unpack8(raw[3 + i], xv);
;                 float o[8];
; #pragma unroll
;                 for (int e = 0; e < 8; ++e) { o[e] = silu_f(b[e] + w[0][e] * xw[0][e] + w[1][e] * xw[1][e] + w[2][e] * xw[2][e] + w[3][e] * xv[e]); xw[0][e] = xw[1][e]; xw[1][e] = xw[2][e]; xw[2][e] = xv[e]; }
;                 u32x4 pk; pk.x = cvt_pk_bf16(o[0], o[1]); pk.y = cvt_pk_bf16(o[2], o[3]); pk.z = cvt_pk_bf16(o[4], o[5]); pk.w = cvt_pk_bf16(o[6], o[7]);
;                 *(LAS u32x4*)(tile + off_b(seg * 16 + i, tch)) = pk; }
	v_add_f32_e32 v72, 1.0, v82
	v_pk_mul_f32 v[82:83], v[4:5], v[100:101]
	v_rcp_f32_e32 v115, v72
	v_add_f32_e32 v72, v13, v82
	v_add_f32_e32 v136, v72, v83
	v_and_b32_e32 v83, 0xffff0000, v77
	v_and_b32_e32 v82, 0xffff0000, v73
	v_pk_mov_b32 v[72:73], v[100:101], v[82:83] op_sel:[1,0]
	v_mul_f32_e32 v92, v92, v115
	v_pk_mul_f32 v[76:77], v[8:9], v[72:73]
	v_pk_mul_f32 v[72:73], v[4:5], v[72:73]
	v_add_f32_e32 v76, v137, v76
	v_add_f32_e32 v100, v76, v77
	v_mul_f32_e32 v76, 0xbfb8aa3b, v100
	v_exp_f32_e32 v101, v76
	v_pk_mul_f32 v[76:77], v[8:9], v[82:83]
	v_add_f32_e32 v72, v13, v72
	v_add_f32_e32 v76, v136, v76
	v_add_f32_e32 v76, v76, v77
	v_mul_f32_e32 v77, 0xbfb8aa3b, v76
	v_exp_f32_e32 v77, v77
	v_add_f32_e32 v101, 1.0, v101
	v_rcp_f32_e32 v101, v101
	v_add_f32_e32 v77, 1.0, v77
	v_rcp_f32_e32 v77, v77
	v_mul_f32_e32 v100, v100, v101
	v_cvt_pk_bf16_f32 v115, v93, v100
	ds_write_b128 v220, v[112:115] offset:768
	v_mul_f32_e32 v76, v76, v77
	v_cvt_pk_bf16_f32 v112, v221, v222
	v_cvt_pk_bf16_f32 v113, v223, v224
	v_cvt_pk_bf16_f32 v114, v117, v118
	v_cvt_pk_bf16_f32 v115, v92, v76
	v_xor_b32_e32 v76, 16, v116
	v_add3_u32 v76, v123, v76, v147
	ds_write_b128 v76, v[112:115] offset:1024
	v_pk_mul_f32 v[76:77], v[124:125], v[108:109]
	s_nop 0
	v_add_f32_e32 v76, v22, v76
	v_add_f32_e32 v100, v76, v77
	v_pk_mul_f32 v[76:77], v[14:15], v[128:129]
	s_nop 0
	v_add_f32_e32 v76, v23, v76
	v_add_f32_e32 v101, v76, v77
	v_pk_mul_f32 v[76:77], v[106:107], v[88:89]
	s_waitcnt vmcnt(9)
	v_lshlrev_b32_e32 v89, 16, v66
	v_add_f32_e32 v76, v24, v76
	v_add_f32_e32 v112, v76, v77
	v_pk_mul_f32 v[76:77], v[16:17], v[130:131]
	v_add_f32_e32 v130, v72, v73
	v_add_f32_e32 v76, v25, v76
	v_add_f32_e32 v114, v76, v77
	v_pk_mul_f32 v[76:77], v[94:95], v[104:105]
	v_pk_mul_f32 v[72:73], v[124:125], v[102:103]
	v_add_f32_e32 v76, v10, v76
	v_add_f32_e32 v115, v76, v77
	v_pk_mul_f32 v[76:77], v[2:3], v[132:133]
	v_lshlrev_b32_e32 v88, 16, v62
	v_add_f32_e32 v76, v11, v76
	v_add_f32_e32 v117, v76, v77
	v_pk_mul_f32 v[76:77], v[86:87], v[134:135]
	v_add_f32_e32 v72, v22, v72
	v_add_f32_e32 v76, v12, v76
	v_pk_mov_b32 v[92:93], v[102:103], v[88:89] op_sel:[1,0]
	v_add_f32_e32 v118, v76, v77
	v_add_f32_e32 v77, v72, v73
	v_pk_mul_f32 v[72:73], v[126:127], v[92:93]
	v_xor_b32_e32 v76, 0x50, v116
	v_add_f32_e32 v72, v100, v72
	v_add_f32_e32 v100, v72, v73
	v_mul_f32_e32 v72, 0xbfb8aa3b, v100
	v_exp_f32_e32 v102, v72
	v_pk_mul_f32 v[72:73], v[126:127], v[88:89]
	v_add3_u32 v131, v123, v76, v147
	v_add_f32_e32 v72, v77, v72
	v_add_f32_e32 v103, v72, v73
	v_mul_f32_e32 v72, 0xbfb8aa3b, v103
	v_exp_f32_e32 v72, v72
	v_add_f32_e32 v73, 1.0, v102
	v_rcp_f32_e32 v102, v73
	v_and_b32_e32 v73, 0xffff0000, v66
	v_add_f32_e32 v72, 1.0, v72
	v_rcp_f32_e32 v108, v72
	v_and_b32_e32 v72, 0xffff0000, v62
	v_pk_mov_b32 v[104:105], v[80:81], v[72:73] op_sel:[1,0]
	v_mul_f32_e32 v100, v100, v102
	v_pk_mul_f32 v[76:77], v[18:19], v[104:105]
	v_mul_f32_e32 v132, v103, v108
	v_add_f32_e32 v62, v101, v76
	v_add_f32_e32 v62, v62, v77
	v_mul_f32_e32 v66, 0xbfb8aa3b, v62
	v_pk_mul_f32 v[76:77], v[14:15], v[80:81]
	v_exp_f32_e32 v66, v66
	v_add_f32_e32 v76, v23, v76
	v_add_f32_e32 v80, v76, v77
	v_pk_mul_f32 v[76:77], v[18:19], v[72:73]
	v_add_f32_e32 v66, 1.0, v66
	v_add_f32_e32 v76, v80, v76
	v_add_f32_e32 v101, v76, v77
	v_mul_f32_e32 v76, 0xbfb8aa3b, v101
	v_rcp_f32_e32 v66, v66
	v_exp_f32_e32 v76, v76
	v_lshlrev_b32_e32 v77, 16, v67
	v_and_b32_e32 v67, 0xffff0000, v67
	v_mul_f32_e32 v62, v62, v66
	v_add_f32_e32 v66, 1.0, v76
	v_lshlrev_b32_e32 v76, 16, v63
	v_pk_mov_b32 v[108:109], v[84:85], v[76:77] op_sel:[1,0]
	v_rcp_f32_e32 v66, v66
	v_pk_mul_f32 v[80:81], v[110:111], v[108:109]
	v_cvt_pk_bf16_f32 v100, v100, v62
	s_nop 0
	v_add_f32_e32 v80, v112, v80
	v_add_f32_e32 v102, v80, v81
	v_mul_f32_e32 v80, 0xbfb8aa3b, v102
	v_exp_f32_e32 v103, v80
	v_pk_mul_f32 v[80:81], v[106:107], v[84:85]
	s_nop 0
	v_add_f32_e32 v80, v24, v80
	v_add_f32_e32 v84, v80, v81
	v_add_f32_e32 v80, 1.0, v103
	v_rcp_f32_e32 v85, v80
	v_pk_mul_f32 v[80:81], v[110:111], v[76:77]
	v_mul_f32_e32 v85, v102, v85
	v_add_f32_e32 v80, v84, v80
	v_add_f32_e32 v80, v80, v81
	v_mul_f32_e32 v81, 0xbfb8aa3b, v80
	v_exp_f32_e32 v81, v81
	v_mul_f32_e32 v84, v101, v66
	v_and_b32_e32 v66, 0xffff0000, v63
	v_pk_mov_b32 v[112:113], v[74:75], v[66:67] op_sel:[1,0]
	v_add_f32_e32 v62, 1.0, v81
	v_rcp_f32_e32 v81, v62
	v_pk_mul_f32 v[62:63], v[20:21], v[112:113]
	v_mul_f32_e32 v133, v80, v81
	v_add_f32_e32 v62, v114, v62
	v_add_f32_e32 v101, v62, v63
	v_mul_f32_e32 v62, 0xbfb8aa3b, v101
	v_exp_f32_e32 v102, v62
	v_pk_mul_f32 v[62:63], v[16:17], v[74:75]
	v_lshlrev_b32_e32 v81, 16, v68
	v_add_f32_e32 v62, v25, v62
	v_add_f32_e32 v74, v62, v63
	v_add_f32_e32 v62, 1.0, v102
	v_rcp_f32_e32 v75, v62
	v_pk_mul_f32 v[62:63], v[20:21], v[66:67]
	v_lshlrev_b32_e32 v80, 16, v64
	v_add_f32_e32 v62, v74, v62
	v_add_f32_e32 v74, v62, v63
	v_mul_f32_e32 v62, 0xbfb8aa3b, v74
	v_exp_f32_e32 v62, v62
	v_mul_f32_e32 v63, v101, v75
	v_cvt_pk_bf16_f32 v101, v85, v63
	v_add_f32_e32 v62, 1.0, v62
	v_rcp_f32_e32 v75, v62
	v_pk_mul_f32 v[62:63], v[94:95], v[96:97]
	v_pk_mov_b32 v[96:97], v[96:97], v[80:81] op_sel:[1,0]
	v_add_f32_e32 v62, v10, v62
	v_add_f32_e32 v85, v62, v63
	v_pk_mul_f32 v[62:63], v[98:99], v[96:97]
	v_mul_f32_e32 v134, v74, v75
	v_add_f32_e32 v62, v115, v62
	v_add_f32_e32 v102, v62, v63
	v_mul_f32_e32 v62, 0xbfb8aa3b, v102
	v_exp_f32_e32 v103, v62
	v_pk_mul_f32 v[62:63], v[98:99], v[80:81]
	s_nop 0
	v_add_f32_e32 v62, v85, v62
	v_add_f32_e32 v85, v62, v63
	v_mul_f32_e32 v62, 0xbfb8aa3b, v85
	v_exp_f32_e32 v62, v62
	v_add_f32_e32 v63, 1.0, v103
; __device__ __forceinline__ unsigned cvt_pk_bf16(float lo, float hi) { unsigned r; asm volatile("v_cvt_pk_bf16_f32 %0, %1, %2" : "=v"(r) : "v"(lo), "v"(hi)); return r; }
; #define LAS __attribute__((address_space(3)))
; __device__ __forceinline__ float silu_f(float x) { return x * __builtin_amdgcn_rcpf(1.f + __expf(-x)); }
; template <bool NEED_C>
; __device__ __forceinline__ void ssd_stage(LAS unsigned char* lds, const bf16_t* XBC, const float* cw, const float* cb, const float* DT, const float* a_log, int c, int g, int tid, int lane, int wave) {
;     ...
;             for (int i = 0; i < 16; ++i) { float xv[8]; unpack8(raw[3 + i], xv);
;                 float o[8];
; #pragma unroll
;                 for (int e = 0; e < 8; ++e) { o[e] = silu_f(b[e] + w[0][e] * xw[0][e] + w[1][e] * xw[1][e] + w[2][e] * xw[2][e] + w[3][e] * xv[e]); xw[0][e] = xw[1][e]; xw[1][e] = xw[2][e]; xw[2][e] = xv[e]; }
;                 u32x4 pk; pk.x = cvt_pk_bf16(o[0], o[1]); pk.y = cvt_pk_bf16(o[2], o[3]); pk.z = cvt_pk_bf16(o[4], o[5]); pk.w = cvt_pk_bf16(o[6], o[7]);
;                 *(LAS u32x4*)(tile + off_b(seg * 16 + i, tch)) = pk; }
	v_rcp_f32_e32 v103, v63
	v_and_b32_e32 v63, 0xffff0000, v68
	v_add_f32_e32 v62, 1.0, v62
	v_rcp_f32_e32 v128, v62
	v_and_b32_e32 v62, 0xffff0000, v64
	v_pk_mov_b32 v[114:115], v[70:71], v[62:63] op_sel:[1,0]
	v_pk_mul_f32 v[70:71], v[2:3], v[70:71]
	v_pk_mul_f32 v[74:75], v[6:7], v[114:115]
	v_add_f32_e32 v70, v11, v70
	v_add_f32_e32 v64, v117, v74
	v_add_f32_e32 v64, v64, v75
	v_mul_f32_e32 v68, 0xbfb8aa3b, v64
	v_exp_f32_e32 v68, v68
	v_add_f32_e32 v74, v70, v71
	v_pk_mul_f32 v[70:71], v[6:7], v[62:63]
	v_mul_f32_e32 v85, v85, v128
	v_add_f32_e32 v70, v74, v70
	v_add_f32_e32 v117, v70, v71
	v_add_f32_e32 v68, 1.0, v68
	v_mul_f32_e32 v70, 0xbfb8aa3b, v117
	v_rcp_f32_e32 v68, v68
	v_exp_f32_e32 v70, v70
	v_lshlrev_b32_e32 v71, 16, v69
	v_mul_f32_e32 v102, v102, v103
	v_mul_f32_e32 v64, v64, v68
	v_add_f32_e32 v68, 1.0, v70
	v_lshlrev_b32_e32 v70, 16, v65
	v_pk_mov_b32 v[128:129], v[78:79], v[70:71] op_sel:[1,0]
	v_rcp_f32_e32 v68, v68
	v_pk_mul_f32 v[74:75], v[90:91], v[128:129]
	v_cvt_pk_bf16_f32 v102, v102, v64
	v_mul_f32_e32 v117, v117, v68
	v_add_f32_e32 v74, v118, v74
	v_add_f32_e32 v103, v74, v75
	v_mul_f32_e32 v74, 0xbfb8aa3b, v103
	v_exp_f32_e32 v118, v74
	v_pk_mul_f32 v[74:75], v[86:87], v[78:79]
	s_nop 0
	v_add_f32_e32 v74, v12, v74
	v_add_f32_e32 v78, v74, v75
	v_add_f32_e32 v74, 1.0, v118
	v_rcp_f32_e32 v79, v74
	v_pk_mul_f32 v[74:75], v[90:91], v[70:71]
	v_mul_f32_e32 v79, v103, v79
	v_add_f32_e32 v74, v78, v74
	v_add_f32_e32 v78, v74, v75
	v_mul_f32_e32 v74, 0xbfb8aa3b, v78
	v_exp_f32_e32 v74, v74
	s_nop 0
	v_add_f32_e32 v64, 1.0, v74
	v_pk_mul_f32 v[74:75], v[4:5], v[82:83]
	v_rcp_f32_e32 v103, v64
	v_add_f32_e32 v64, v13, v74
	v_add_f32_e32 v118, v64, v75
	v_and_b32_e32 v75, 0xffff0000, v69
	v_and_b32_e32 v74, 0xffff0000, v65
	v_pk_mov_b32 v[64:65], v[82:83], v[74:75] op_sel:[1,0]
	v_mul_f32_e32 v78, v78, v103
	v_pk_mul_f32 v[68:69], v[8:9], v[64:65]
	v_pk_mul_f32 v[64:65], v[4:5], v[64:65]
	v_add_f32_e32 v68, v130, v68
	v_add_f32_e32 v82, v68, v69
	v_mul_f32_e32 v68, 0xbfb8aa3b, v82
	v_exp_f32_e32 v83, v68
	v_pk_mul_f32 v[68:69], v[8:9], v[74:75]
	v_add_f32_e32 v64, v13, v64
	v_add_f32_e32 v68, v118, v68
	v_add_f32_e32 v68, v68, v69
	v_mul_f32_e32 v69, 0xbfb8aa3b, v68
	v_exp_f32_e32 v69, v69
	v_add_f32_e32 v83, 1.0, v83
	v_rcp_f32_e32 v83, v83
	v_add_f32_e32 v69, 1.0, v69
	v_rcp_f32_e32 v69, v69
	v_mul_f32_e32 v82, v82, v83
	v_cvt_pk_bf16_f32 v103, v79, v82
	ds_write_b128 v131, v[100:103] offset:1280
	v_mul_f32_e32 v68, v68, v69
	v_cvt_pk_bf16_f32 v82, v132, v84
	v_cvt_pk_bf16_f32 v83, v133, v134
	v_cvt_pk_bf16_f32 v84, v85, v117
	v_cvt_pk_bf16_f32 v85, v78, v68
	v_xor_b32_e32 v68, 0x90, v116
	v_add3_u32 v68, v123, v68, v147
	ds_write_b128 v68, v[82:85] offset:1536
	v_pk_mul_f32 v[68:69], v[124:125], v[92:93]
	s_waitcnt vmcnt(7)
	v_lshlrev_b32_e32 v79, 16, v58
	v_add_f32_e32 v68, v22, v68
	v_add_f32_e32 v82, v68, v69
	v_pk_mul_f32 v[68:69], v[14:15], v[104:105]
	v_add_f32_e32 v105, v64, v65
	v_add_f32_e32 v68, v23, v68
	v_add_f32_e32 v83, v68, v69
	v_pk_mul_f32 v[68:69], v[106:107], v[108:109]
	v_pk_mul_f32 v[64:65], v[124:125], v[88:89]
	v_add_f32_e32 v68, v24, v68
	v_add_f32_e32 v84, v68, v69
	v_pk_mul_f32 v[68:69], v[16:17], v[112:113]
	v_lshlrev_b32_e32 v78, 16, v54
	v_add_f32_e32 v68, v25, v68
	v_add_f32_e32 v85, v68, v69
	v_pk_mul_f32 v[68:69], v[94:95], v[96:97]
	v_add_f32_e32 v64, v22, v64
	v_add_f32_e32 v68, v10, v68
	v_add_f32_e32 v100, v68, v69
	v_pk_mul_f32 v[68:69], v[2:3], v[114:115]
	v_pk_mov_b32 v[88:89], v[88:89], v[78:79] op_sel:[1,0]
	v_add_f32_e32 v68, v11, v68
	v_add_f32_e32 v102, v68, v69
	v_pk_mul_f32 v[68:69], v[86:87], v[128:129]
	s_nop 0
	v_add_f32_e32 v68, v12, v68
	v_add_f32_e32 v104, v68, v69
	v_add_f32_e32 v69, v64, v65
	v_pk_mul_f32 v[64:65], v[126:127], v[88:89]
	v_xor_b32_e32 v68, 0xd0, v116
	v_add_f32_e32 v64, v82, v64
	v_add_f32_e32 v82, v64, v65
	v_mul_f32_e32 v64, 0xbfb8aa3b, v82
	v_exp_f32_e32 v92, v64
	v_pk_mul_f32 v[64:65], v[126:127], v[78:79]
	v_add3_u32 v108, v123, v68, v147
	v_add_f32_e32 v64, v69, v64
	v_add_f32_e32 v96, v64, v65
	v_mul_f32_e32 v64, 0xbfb8aa3b, v96
	v_exp_f32_e32 v64, v64
	v_add_f32_e32 v65, 1.0, v92
	v_rcp_f32_e32 v97, v65
	v_and_b32_e32 v65, 0xffff0000, v58
	v_add_f32_e32 v64, 1.0, v64
	v_rcp_f32_e32 v101, v64
	v_and_b32_e32 v64, 0xffff0000, v54
	v_pk_mov_b32 v[92:93], v[72:73], v[64:65] op_sel:[1,0]
	v_mul_f32_e32 v97, v82, v97
	v_pk_mul_f32 v[68:69], v[18:19], v[92:93]
	v_mul_f32_e32 v109, v96, v101
	v_add_f32_e32 v54, v83, v68
	v_add_f32_e32 v54, v54, v69
	v_mul_f32_e32 v58, 0xbfb8aa3b, v54
	v_pk_mul_f32 v[68:69], v[14:15], v[72:73]
	v_exp_f32_e32 v58, v58
	v_add_f32_e32 v68, v23, v68
	v_add_f32_e32 v72, v68, v69
	v_pk_mul_f32 v[68:69], v[18:19], v[64:65]
	v_add_f32_e32 v58, 1.0, v58
	v_add_f32_e32 v68, v72, v68
	v_add_f32_e32 v103, v68, v69
	v_mul_f32_e32 v68, 0xbfb8aa3b, v103
	v_rcp_f32_e32 v58, v58
	v_exp_f32_e32 v68, v68
	v_lshlrev_b32_e32 v69, 16, v59
	v_and_b32_e32 v59, 0xffff0000, v59
	v_mul_f32_e32 v54, v54, v58
	v_add_f32_e32 v58, 1.0, v68
	v_lshlrev_b32_e32 v68, 16, v55
	v_pk_mov_b32 v[72:73], v[76:77], v[68:69] op_sel:[1,0]
	v_pk_mul_f32 v[76:77], v[106:107], v[76:77]
	v_pk_mul_f32 v[82:83], v[110:111], v[72:73]
	v_add_f32_e32 v76, v24, v76
	v_add_f32_e32 v82, v84, v82
	v_add_f32_e32 v83, v82, v83
	v_mul_f32_e32 v82, 0xbfb8aa3b, v83
	v_exp_f32_e32 v82, v82
	v_add_f32_e32 v84, v76, v77
	v_rcp_f32_e32 v58, v58
	v_add_f32_e32 v76, 1.0, v82
	v_rcp_f32_e32 v96, v76
	v_pk_mul_f32 v[76:77], v[110:111], v[68:69]
	v_mul_f32_e32 v112, v103, v58
	v_add_f32_e32 v76, v84, v76
	v_add_f32_e32 v76, v76, v77
	v_mul_f32_e32 v77, 0xbfb8aa3b, v76
	v_exp_f32_e32 v77, v77
; __device__ __forceinline__ unsigned cvt_pk_bf16(float lo, float hi) { unsigned r; asm volatile("v_cvt_pk_bf16_f32 %0, %1, %2" : "=v"(r) : "v"(lo), "v"(hi)); return r; }
; #define LAS __attribute__((address_space(3)))
; __device__ __forceinline__ float silu_f(float x) { return x * __builtin_amdgcn_rcpf(1.f + __expf(-x)); }
; template <bool NEED_C>
; __device__ __forceinline__ void ssd_stage(LAS unsigned char* lds, const bf16_t* XBC, const float* cw, const float* cb, const float* DT, const float* a_log, int c, int g, int tid, int lane, int wave) {
;     ...
;             for (int i = 0; i < 16; ++i) { float xv[8]; unpack8(raw[3 + i], xv);
;                 float o[8];
; #pragma unroll
;                 for (int e = 0; e < 8; ++e) { o[e] = silu_f(b[e] + w[0][e] * xw[0][e] + w[1][e] * xw[1][e] + w[2][e] * xw[2][e] + w[3][e] * xv[e]); xw[0][e] = xw[1][e]; xw[1][e] = xw[2][e]; xw[2][e] = xv[e]; }
;                 u32x4 pk; pk.x = cvt_pk_bf16(o[0], o[1]); pk.y = cvt_pk_bf16(o[2], o[3]); pk.z = cvt_pk_bf16(o[4], o[5]); pk.w = cvt_pk_bf16(o[6], o[7]);
;                 *(LAS u32x4*)(tile + off_b(seg * 16 + i, tch)) = pk; }
	v_and_b32_e32 v58, 0xffff0000, v55
	v_cvt_pk_bf16_f32 v82, v97, v54
	v_mul_f32_e32 v83, v83, v96
	v_add_f32_e32 v54, 1.0, v77
	v_pk_mov_b32 v[96:97], v[66:67], v[58:59] op_sel:[1,0]
	v_rcp_f32_e32 v77, v54
	v_pk_mul_f32 v[54:55], v[20:21], v[96:97]
	v_mul_f32_e32 v113, v76, v77
	v_add_f32_e32 v54, v85, v54
	v_add_f32_e32 v84, v54, v55
	v_mul_f32_e32 v54, 0xbfb8aa3b, v84
	v_exp_f32_e32 v85, v54
	v_pk_mul_f32 v[54:55], v[16:17], v[66:67]
	v_lshlrev_b32_e32 v77, 16, v60
	v_add_f32_e32 v54, v25, v54
	v_add_f32_e32 v66, v54, v55
	v_add_f32_e32 v54, 1.0, v85
	v_rcp_f32_e32 v67, v54
	v_pk_mul_f32 v[54:55], v[20:21], v[58:59]
	v_lshlrev_b32_e32 v76, 16, v56
	v_add_f32_e32 v54, v66, v54
	v_add_f32_e32 v66, v54, v55
	v_mul_f32_e32 v54, 0xbfb8aa3b, v66
	v_exp_f32_e32 v54, v54
	v_mul_f32_e32 v55, v84, v67
	v_cvt_pk_bf16_f32 v83, v83, v55
	v_add_f32_e32 v54, 1.0, v54
	v_rcp_f32_e32 v67, v54
	v_pk_mul_f32 v[54:55], v[94:95], v[80:81]
	v_pk_mov_b32 v[80:81], v[80:81], v[76:77] op_sel:[1,0]
	v_add_f32_e32 v54, v10, v54
	v_add_f32_e32 v84, v54, v55
	v_pk_mul_f32 v[54:55], v[98:99], v[80:81]
	v_mul_f32_e32 v114, v66, v67
	v_add_f32_e32 v54, v100, v54
	v_add_f32_e32 v85, v54, v55
	v_mul_f32_e32 v54, 0xbfb8aa3b, v85
	v_exp_f32_e32 v100, v54
	v_pk_mul_f32 v[54:55], v[98:99], v[76:77]
	s_nop 0
	v_add_f32_e32 v54, v84, v54
	v_add_f32_e32 v84, v54, v55
	v_mul_f32_e32 v54, 0xbfb8aa3b, v84
	v_exp_f32_e32 v54, v54
	v_add_f32_e32 v55, 1.0, v100
	v_rcp_f32_e32 v103, v55
	v_and_b32_e32 v55, 0xffff0000, v60
	v_add_f32_e32 v54, 1.0, v54
	v_rcp_f32_e32 v115, v54
	v_and_b32_e32 v54, 0xffff0000, v56
	v_pk_mov_b32 v[100:101], v[62:63], v[54:55] op_sel:[1,0]
	v_pk_mul_f32 v[62:63], v[2:3], v[62:63]
	v_pk_mul_f32 v[66:67], v[6:7], v[100:101]
	v_add_f32_e32 v62, v11, v62
	v_add_f32_e32 v56, v102, v66
	v_add_f32_e32 v56, v56, v67
	v_mul_f32_e32 v60, 0xbfb8aa3b, v56
	v_exp_f32_e32 v60, v60
	v_add_f32_e32 v66, v62, v63
	v_pk_mul_f32 v[62:63], v[6:7], v[54:55]
	v_lshlrev_b32_e32 v67, 16, v61
	v_add_f32_e32 v62, v66, v62
	v_add_f32_e32 v117, v62, v63
	v_add_f32_e32 v60, 1.0, v60
	v_mul_f32_e32 v62, 0xbfb8aa3b, v117
	v_rcp_f32_e32 v60, v60
	v_exp_f32_e32 v62, v62
	v_lshlrev_b32_e32 v66, 16, v57
	v_mul_f32_e32 v85, v85, v103
	v_pk_mov_b32 v[102:103], v[70:71], v[66:67] op_sel:[1,0]
	v_mul_f32_e32 v56, v56, v60
	v_add_f32_e32 v60, 1.0, v62
	v_pk_mul_f32 v[62:63], v[90:91], v[102:103]
	v_mul_f32_e32 v115, v84, v115
	v_add_f32_e32 v62, v104, v62
	v_add_f32_e32 v104, v62, v63
	v_mul_f32_e32 v62, 0xbfb8aa3b, v104
	v_exp_f32_e32 v84, v62
	v_pk_mul_f32 v[62:63], v[86:87], v[70:71]
	v_rcp_f32_e32 v60, v60
	v_add_f32_e32 v62, v12, v62
	v_add_f32_e32 v70, v62, v63
	v_add_f32_e32 v62, 1.0, v84
	v_rcp_f32_e32 v71, v62
	v_pk_mul_f32 v[62:63], v[90:91], v[66:67]
	v_cvt_pk_bf16_f32 v84, v85, v56
	v_mul_f32_e32 v117, v117, v60
	v_add_f32_e32 v62, v70, v62
	v_add_f32_e32 v118, v62, v63
	v_mul_f32_e32 v62, 0xbfb8aa3b, v118
	v_exp_f32_e32 v62, v62
	v_mul_f32_e32 v85, v104, v71
	v_and_b32_e32 v71, 0xffff0000, v61
	v_and_b32_e32 v70, 0xffff0000, v57
	v_add_f32_e32 v56, 1.0, v62
	v_pk_mul_f32 v[62:63], v[4:5], v[74:75]
	v_rcp_f32_e32 v104, v56
	v_add_f32_e32 v56, v13, v62
	v_add_f32_e32 v62, v56, v63
	v_pk_mov_b32 v[56:57], v[74:75], v[70:71] op_sel:[1,0]
	s_nop 0
	v_pk_mul_f32 v[60:61], v[8:9], v[56:57]
	v_pk_mul_f32 v[56:57], v[4:5], v[56:57]
	v_add_f32_e32 v60, v105, v60
	v_add_f32_e32 v63, v60, v61
	v_mul_f32_e32 v60, 0xbfb8aa3b, v63
	v_exp_f32_e32 v74, v60
	v_pk_mul_f32 v[60:61], v[8:9], v[70:71]
	v_add_f32_e32 v56, v13, v56
	v_add_f32_e32 v60, v62, v60
	v_add_f32_e32 v60, v60, v61
	v_mul_f32_e32 v61, 0xbfb8aa3b, v60
	v_exp_f32_e32 v61, v61
	v_add_f32_e32 v62, 1.0, v74
	v_rcp_f32_e32 v62, v62
	v_mul_f32_e32 v74, v118, v104
	v_add_f32_e32 v61, 1.0, v61
	v_rcp_f32_e32 v61, v61
	v_mul_f32_e32 v62, v63, v62
	v_cvt_pk_bf16_f32 v85, v85, v62
	ds_write_b128 v108, v[82:85] offset:1792
	v_mul_f32_e32 v63, v60, v61
	v_cvt_pk_bf16_f32 v60, v109, v112
	v_cvt_pk_bf16_f32 v61, v113, v114
	v_cvt_pk_bf16_f32 v62, v115, v117
	v_cvt_pk_bf16_f32 v63, v74, v63
	v_xor_b32_e32 v74, 32, v116
	v_add3_u32 v74, v123, v74, v147
	ds_write_b128 v74, v[60:63] offset:2048
	v_pk_mul_f32 v[60:61], v[124:125], v[88:89]
	v_add_f32_e32 v89, v56, v57
	v_add_f32_e32 v60, v22, v60
	v_add_f32_e32 v62, v60, v61
	v_pk_mul_f32 v[60:61], v[14:15], v[92:93]
	v_pk_mul_f32 v[56:57], v[124:125], v[78:79]
	v_add_f32_e32 v60, v23, v60
	v_add_f32_e32 v63, v60, v61
	v_pk_mul_f32 v[60:61], v[106:107], v[72:73]
	s_waitcnt vmcnt(5)
; __device__ __forceinline__ unsigned cvt_pk_bf16(float lo, float hi) { unsigned r; asm volatile("v_cvt_pk_bf16_f32 %0, %1, %2" : "=v"(r) : "v"(lo), "v"(hi)); return r; }
; #define LAS __attribute__((address_space(3)))
; __device__ __forceinline__ float silu_f(float x) { return x * __builtin_amdgcn_rcpf(1.f + __expf(-x)); }
; template <bool NEED_C>
; __device__ __forceinline__ void ssd_stage(LAS unsigned char* lds, const bf16_t* XBC, const float* cw, const float* cb, const float* DT, const float* a_log, int c, int g, int tid, int lane, int wave) {
;     ...
; #pragma unroll
;             for (int k = 0; k < 3; ++k) unpack8(raw[k], xw[k]);
; #pragma unroll
;             for (int i = 0; i < 16; ++i) { float xv[8]; unpack8(raw[3 + i], xv);
;                 float o[8];
; #pragma unroll
;                 for (int e = 0; e < 8; ++e) { o[e] = silu_f(b[e] + w[0][e] * xw[0][e] + w[1][e] * xw[1][e] + w[2][e] * xw[2][e] + w[3][e] * xv[e]); xw[0][e] = xw[1][e]; xw[1][e] = xw[2][e]; xw[2][e] = xv[e]; }
;                 u32x4 pk; pk.x = cvt_pk_bf16(o[0], o[1]); pk.y = cvt_pk_bf16(o[2], o[3]); pk.z = cvt_pk_bf16(o[4], o[5]); pk.w = cvt_pk_bf16(o[6], o[7]);
;                 *(LAS u32x4*)(tile + off_b(seg * 16 + i, tch)) = pk; }
	v_lshlrev_b32_e32 v73, 16, v50
	v_add_f32_e32 v60, v24, v60
	v_add_f32_e32 v82, v60, v61
	v_pk_mul_f32 v[60:61], v[16:17], v[96:97]
	v_lshlrev_b32_e32 v72, 16, v46
	v_add_f32_e32 v60, v25, v60
	v_add_f32_e32 v83, v60, v61
	v_pk_mul_f32 v[60:61], v[94:95], v[80:81]
	v_add_f32_e32 v56, v22, v56
	v_add_f32_e32 v60, v10, v60
	v_add_f32_e32 v80, v60, v61
	v_pk_mul_f32 v[60:61], v[2:3], v[100:101]
	v_pk_mov_b32 v[74:75], v[78:79], v[72:73] op_sel:[1,0]
	v_add_f32_e32 v60, v11, v60
	v_add_f32_e32 v84, v60, v61
	v_pk_mul_f32 v[60:61], v[86:87], v[102:103]
	s_nop 0
	v_add_f32_e32 v60, v12, v60
	v_add_f32_e32 v88, v60, v61
	v_add_f32_e32 v61, v56, v57
	v_pk_mul_f32 v[56:57], v[126:127], v[74:75]
	v_xor_b32_e32 v60, 0x60, v116
	v_add_f32_e32 v56, v62, v56
	v_add_f32_e32 v62, v56, v57
	v_mul_f32_e32 v56, 0xbfb8aa3b, v62
	v_exp_f32_e32 v78, v56
	v_pk_mul_f32 v[56:57], v[126:127], v[72:73]
	v_add3_u32 v92, v123, v60, v147
	v_add_f32_e32 v56, v61, v56
	v_add_f32_e32 v81, v56, v57
	v_mul_f32_e32 v56, 0xbfb8aa3b, v81
	v_exp_f32_e32 v56, v56
	v_add_f32_e32 v57, 1.0, v78
	v_rcp_f32_e32 v85, v57
	v_and_b32_e32 v57, 0xffff0000, v50
	v_add_f32_e32 v56, 1.0, v56
	v_rcp_f32_e32 v93, v56
	v_and_b32_e32 v56, 0xffff0000, v46
	v_pk_mov_b32 v[78:79], v[64:65], v[56:57] op_sel:[1,0]
	v_mul_f32_e32 v85, v62, v85
	v_pk_mul_f32 v[60:61], v[18:19], v[78:79]
	v_lshlrev_b32_e32 v62, 16, v47
	v_add_f32_e32 v46, v63, v60
	v_add_f32_e32 v46, v46, v61
	v_mul_f32_e32 v50, 0xbfb8aa3b, v46
	v_pk_mul_f32 v[60:61], v[14:15], v[64:65]
	v_exp_f32_e32 v50, v50
	v_add_f32_e32 v60, v23, v60
	v_add_f32_e32 v63, v60, v61
	v_pk_mul_f32 v[60:61], v[18:19], v[56:57]
	v_add_f32_e32 v50, 1.0, v50
	v_add_f32_e32 v60, v63, v60
	v_add_f32_e32 v96, v60, v61
	v_mul_f32_e32 v60, 0xbfb8aa3b, v96
	v_rcp_f32_e32 v50, v50
	v_exp_f32_e32 v60, v60
	v_lshlrev_b32_e32 v63, 16, v51
	v_pk_mov_b32 v[64:65], v[68:69], v[62:63] op_sel:[1,0]
	v_mul_f32_e32 v46, v46, v50
	v_add_f32_e32 v50, 1.0, v60
	v_pk_mul_f32 v[60:61], v[110:111], v[64:65]
	v_mul_f32_e32 v93, v81, v93
	v_add_f32_e32 v60, v82, v60
	v_add_f32_e32 v81, v60, v61
	v_mul_f32_e32 v60, 0xbfb8aa3b, v81
	v_exp_f32_e32 v82, v60
	v_pk_mul_f32 v[60:61], v[106:107], v[68:69]
	v_rcp_f32_e32 v50, v50
	v_add_f32_e32 v60, v24, v60
	v_add_f32_e32 v68, v60, v61
	v_add_f32_e32 v60, 1.0, v82
	v_rcp_f32_e32 v69, v60
	v_pk_mul_f32 v[60:61], v[110:111], v[62:63]
	v_mul_f32_e32 v96, v96, v50
	v_add_f32_e32 v60, v68, v60
	v_add_f32_e32 v82, v60, v61
	v_mul_f32_e32 v60, 0xbfb8aa3b, v82
	v_exp_f32_e32 v60, v60
	v_and_b32_e32 v61, 0xffff0000, v51
	v_cvt_pk_bf16_f32 v46, v85, v46
	v_mul_f32_e32 v81, v81, v69
	v_add_f32_e32 v50, 1.0, v60
	v_and_b32_e32 v60, 0xffff0000, v47
	v_rcp_f32_e32 v85, v50
	v_pk_mov_b32 v[50:51], v[58:59], v[60:61] op_sel:[1,0]
	v_pk_mul_f32 v[58:59], v[16:17], v[58:59]
	v_pk_mul_f32 v[68:69], v[20:21], v[50:51]
	v_add_f32_e32 v58, v25, v58
	v_add_f32_e32 v47, v83, v68
	v_add_f32_e32 v47, v47, v69
	v_mul_f32_e32 v68, 0xbfb8aa3b, v47
	v_exp_f32_e32 v68, v68
	v_add_f32_e32 v69, v58, v59
	v_mul_f32_e32 v97, v82, v85
	v_add_f32_e32 v58, 1.0, v68
	v_rcp_f32_e32 v68, v58
	v_pk_mul_f32 v[58:59], v[20:21], v[60:61]
	v_mul_f32_e32 v47, v47, v68
	v_add_f32_e32 v58, v69, v58
	v_add_f32_e32 v83, v58, v59
	v_mul_f32_e32 v58, 0xbfb8aa3b, v83
	v_exp_f32_e32 v58, v58
	v_cvt_pk_bf16_f32 v47, v81, v47
	v_lshlrev_b32_e32 v69, 16, v52
	v_lshlrev_b32_e32 v68, 16, v48
	v_add_f32_e32 v58, 1.0, v58
	v_rcp_f32_e32 v81, v58
	v_pk_mul_f32 v[58:59], v[94:95], v[76:77]
	v_pk_mov_b32 v[76:77], v[76:77], v[68:69] op_sel:[1,0]
	v_add_f32_e32 v58, v10, v58
	v_add_f32_e32 v82, v58, v59
	v_pk_mul_f32 v[58:59], v[98:99], v[76:77]
	v_mul_f32_e32 v101, v83, v81
	v_add_f32_e32 v58, v80, v58
	v_add_f32_e32 v85, v58, v59
	v_mul_f32_e32 v58, 0xbfb8aa3b, v85
	v_exp_f32_e32 v80, v58
	v_pk_mul_f32 v[58:59], v[98:99], v[68:69]
	s_nop 0
	v_add_f32_e32 v58, v82, v58
	v_add_f32_e32 v100, v58, v59
	v_mul_f32_e32 v58, 0xbfb8aa3b, v100
	v_exp_f32_e32 v58, v58
	v_add_f32_e32 v59, 1.0, v80
	v_rcp_f32_e32 v102, v59
	v_and_b32_e32 v59, 0xffff0000, v52
	v_add_f32_e32 v58, 1.0, v58
	v_rcp_f32_e32 v103, v58
	v_and_b32_e32 v58, 0xffff0000, v48
	v_pk_mov_b32 v[80:81], v[54:55], v[58:59] op_sel:[1,0]
	v_pk_mul_f32 v[54:55], v[2:3], v[54:55]
	v_pk_mul_f32 v[82:83], v[6:7], v[80:81]
	v_add_f32_e32 v54, v11, v54
	v_add_f32_e32 v48, v84, v82
	v_add_f32_e32 v48, v48, v83
	v_mul_f32_e32 v52, 0xbfb8aa3b, v48
	v_exp_f32_e32 v52, v52
	v_add_f32_e32 v82, v54, v55
	v_pk_mul_f32 v[54:55], v[6:7], v[58:59]
	v_mul_f32_e32 v102, v85, v102
	v_add_f32_e32 v54, v82, v54
	v_add_f32_e32 v104, v54, v55
	v_add_f32_e32 v52, 1.0, v52
	v_mul_f32_e32 v54, 0xbfb8aa3b, v104
	v_rcp_f32_e32 v52, v52
	v_exp_f32_e32 v54, v54
	v_lshlrev_b32_e32 v55, 16, v53
	v_mul_f32_e32 v100, v100, v103
	v_mul_f32_e32 v48, v48, v52
	v_add_f32_e32 v52, 1.0, v54
	v_lshlrev_b32_e32 v54, 16, v49
	v_pk_mov_b32 v[82:83], v[66:67], v[54:55] op_sel:[1,0]
	v_pk_mul_f32 v[66:67], v[86:87], v[66:67]
	v_pk_mul_f32 v[84:85], v[90:91], v[82:83]
	v_add_f32_e32 v66, v12, v66
	v_add_f32_e32 v84, v88, v84
	v_add_f32_e32 v84, v84, v85
	v_mul_f32_e32 v85, 0xbfb8aa3b, v84
	v_exp_f32_e32 v85, v85
	v_add_f32_e32 v88, v66, v67
	v_rcp_f32_e32 v52, v52
	v_cvt_pk_bf16_f32 v48, v102, v48
	v_add_f32_e32 v66, 1.0, v85
	v_rcp_f32_e32 v85, v66
	v_pk_mul_f32 v[66:67], v[90:91], v[54:55]
	v_mul_f32_e32 v102, v104, v52
	v_add_f32_e32 v66, v88, v66
	v_add_f32_e32 v88, v66, v67
	v_mul_f32_e32 v66, 0xbfb8aa3b, v88
	v_exp_f32_e32 v66, v66
	v_mul_f32_e32 v84, v84, v85
	v_add_f32_e32 v52, 1.0, v66
	v_pk_mul_f32 v[66:67], v[4:5], v[70:71]
	v_rcp_f32_e32 v85, v52
	v_add_f32_e32 v52, v13, v66
	v_add_f32_e32 v103, v52, v67
	v_and_b32_e32 v67, 0xffff0000, v53
	v_and_b32_e32 v66, 0xffff0000, v49
	v_pk_mov_b32 v[52:53], v[70:71], v[66:67] op_sel:[1,0]
	v_mul_f32_e32 v85, v88, v85
	v_pk_mul_f32 v[70:71], v[8:9], v[52:53]
	s_nop 0
	v_add_f32_e32 v49, v89, v70
	v_add_f32_e32 v49, v49, v71
	v_mul_f32_e32 v70, 0xbfb8aa3b, v49
	v_exp_f32_e32 v89, v70
	v_pk_mul_f32 v[70:71], v[8:9], v[66:67]
	v_add_f32_e32 v89, 1.0, v89
	v_add_f32_e32 v70, v103, v70
	v_add_f32_e32 v70, v70, v71
	v_mul_f32_e32 v71, 0xbfb8aa3b, v70
	v_exp_f32_e32 v71, v71
	v_rcp_f32_e32 v89, v89
	v_add_f32_e32 v71, 1.0, v71
	v_rcp_f32_e32 v71, v71
	v_mul_f32_e32 v49, v49, v89
	v_cvt_pk_bf16_f32 v49, v84, v49
	ds_write_b128 v92, v[46:49] offset:2304
	v_mul_f32_e32 v49, v70, v71
	v_xor_b32_e32 v70, 0xa0, v116
	v_cvt_pk_bf16_f32 v46, v93, v96
	v_cvt_pk_bf16_f32 v47, v97, v101
	v_add3_u32 v70, v123, v70, v147
	v_cvt_pk_bf16_f32 v48, v100, v102
	v_cvt_pk_bf16_f32 v49, v85, v49
	ds_write_b128 v70, v[46:49] offset:2560
	v_pk_mul_f32 v[46:47], v[124:125], v[74:75]
	s_nop 0
	v_add_f32_e32 v46, v22, v46
	v_add_f32_e32 v48, v46, v47
	v_pk_mul_f32 v[46:47], v[14:15], v[78:79]
	s_nop 0
	v_add_f32_e32 v46, v23, v46
	v_add_f32_e32 v49, v46, v47
	v_pk_mul_f32 v[46:47], v[106:107], v[64:65]
	s_waitcnt vmcnt(3)
; __device__ __forceinline__ unsigned cvt_pk_bf16(float lo, float hi) { unsigned r; asm volatile("v_cvt_pk_bf16_f32 %0, %1, %2" : "=v"(r) : "v"(lo), "v"(hi)); return r; }
; #define LAS __attribute__((address_space(3)))
; __device__ __forceinline__ float silu_f(float x) { return x * __builtin_amdgcn_rcpf(1.f + __expf(-x)); }
; template <bool NEED_C>
; __device__ __forceinline__ void ssd_stage(LAS unsigned char* lds, const bf16_t* XBC, const float* cw, const float* cb, const float* DT, const float* a_log, int c, int g, int tid, int lane, int wave) {
;     ...
; #pragma unroll
;             for (int k = 0; k < 3; ++k) unpack8(raw[k], xw[k]);
; #pragma unroll
;             for (int i = 0; i < 16; ++i) { float xv[8]; unpack8(raw[3 + i], xv);
;                 float o[8];
; #pragma unroll
;                 for (int e = 0; e < 8; ++e) { o[e] = silu_f(b[e] + w[0][e] * xw[0][e] + w[1][e] * xw[1][e] + w[2][e] * xw[2][e] + w[3][e] * xv[e]); xw[0][e] = xw[1][e]; xw[1][e] = xw[2][e]; xw[2][e] = xv[e]; }
;                 u32x4 pk; pk.x = cvt_pk_bf16(o[0], o[1]); pk.y = cvt_pk_bf16(o[2], o[3]); pk.z = cvt_pk_bf16(o[4], o[5]); pk.w = cvt_pk_bf16(o[6], o[7]);
;                 *(LAS u32x4*)(tile + off_b(seg * 16 + i, tch)) = pk; }
	v_lshlrev_b32_e32 v65, 16, v42
	v_add_f32_e32 v46, v24, v46
	v_add_f32_e32 v78, v46, v47
	v_pk_mul_f32 v[46:47], v[16:17], v[50:51]
	v_lshlrev_b32_e32 v64, 16, v38
	v_add_f32_e32 v46, v25, v46
	v_add_f32_e32 v79, v46, v47
	v_pk_mul_f32 v[46:47], v[94:95], v[76:77]
	v_pk_mov_b32 v[70:71], v[72:73], v[64:65] op_sel:[1,0]
	v_add_f32_e32 v46, v10, v46
	v_add_f32_e32 v76, v46, v47
	v_pk_mul_f32 v[46:47], v[2:3], v[80:81]
	v_xor_b32_e32 v50, 0xe0, v116
	v_add_f32_e32 v46, v11, v46
	v_add_f32_e32 v77, v46, v47
	v_pk_mul_f32 v[46:47], v[86:87], v[82:83]
	v_add3_u32 v82, v123, v50, v147
	v_add_f32_e32 v46, v12, v46
	v_add_f32_e32 v80, v46, v47
	v_pk_mul_f32 v[46:47], v[4:5], v[52:53]
	v_and_b32_e32 v50, 0xffff0000, v38
	v_add_f32_e32 v46, v13, v46
	v_add_f32_e32 v81, v46, v47
	v_pk_mul_f32 v[46:47], v[124:125], v[72:73]
	s_nop 0
	v_add_f32_e32 v46, v22, v46
	v_add_f32_e32 v51, v46, v47
	v_pk_mul_f32 v[46:47], v[126:127], v[70:71]
	s_nop 0
	v_add_f32_e32 v46, v48, v46
	v_add_f32_e32 v48, v46, v47
	v_mul_f32_e32 v46, 0xbfb8aa3b, v48
	v_exp_f32_e32 v52, v46
	v_pk_mul_f32 v[46:47], v[126:127], v[64:65]
	s_nop 0
	v_add_f32_e32 v46, v51, v46
	v_add_f32_e32 v53, v46, v47
	v_mul_f32_e32 v46, 0xbfb8aa3b, v53
	v_exp_f32_e32 v46, v46
	v_and_b32_e32 v51, 0xffff0000, v42
	v_add_f32_e32 v47, 1.0, v52
	v_pk_mov_b32 v[72:73], v[56:57], v[50:51] op_sel:[1,0]
	v_add_f32_e32 v46, 1.0, v46
	v_rcp_f32_e32 v52, v47
	v_rcp_f32_e32 v74, v46
	v_pk_mul_f32 v[46:47], v[18:19], v[72:73]
	v_mul_f32_e32 v52, v48, v52
	v_add_f32_e32 v38, v49, v46
	v_add_f32_e32 v38, v38, v47
	v_mul_f32_e32 v42, 0xbfb8aa3b, v38
	v_pk_mul_f32 v[46:47], v[14:15], v[56:57]
	v_exp_f32_e32 v42, v42
	v_add_f32_e32 v46, v23, v46
	v_add_f32_e32 v49, v46, v47
	v_pk_mul_f32 v[46:47], v[18:19], v[50:51]
	v_add_f32_e32 v42, 1.0, v42
	v_add_f32_e32 v46, v49, v46
	v_add_f32_e32 v57, v46, v47
	v_mul_f32_e32 v46, 0xbfb8aa3b, v57
	v_rcp_f32_e32 v42, v42
	v_exp_f32_e32 v46, v46
	v_lshlrev_b32_e32 v49, 16, v43
	v_lshlrev_b32_e32 v48, 16, v39
	v_mul_f32_e32 v83, v53, v74
	v_pk_mov_b32 v[74:75], v[62:63], v[48:49] op_sel:[1,0]
	v_mul_f32_e32 v38, v38, v42
	v_add_f32_e32 v42, 1.0, v46
	v_pk_mul_f32 v[46:47], v[110:111], v[74:75]
	v_rcp_f32_e32 v42, v42
	v_add_f32_e32 v46, v78, v46
	v_add_f32_e32 v53, v46, v47
	v_mul_f32_e32 v46, 0xbfb8aa3b, v53
	v_exp_f32_e32 v56, v46
	v_pk_mul_f32 v[46:47], v[106:107], v[62:63]
	v_mul_f32_e32 v84, v57, v42
	v_add_f32_e32 v46, v24, v46
	v_add_f32_e32 v62, v46, v47
	v_add_f32_e32 v46, 1.0, v56
	v_rcp_f32_e32 v63, v46
	v_pk_mul_f32 v[46:47], v[110:111], v[48:49]
	v_cvt_pk_bf16_f32 v56, v52, v38
	v_mul_f32_e32 v42, v53, v63
	v_add_f32_e32 v46, v62, v46
	v_add_f32_e32 v78, v46, v47
	v_mul_f32_e32 v46, 0xbfb8aa3b, v78
	v_exp_f32_e32 v46, v46
	v_and_b32_e32 v47, 0xffff0000, v43
	v_add_f32_e32 v38, 1.0, v46
	v_and_b32_e32 v46, 0xffff0000, v39
	v_pk_mov_b32 v[62:63], v[60:61], v[46:47] op_sel:[1,0]
	v_rcp_f32_e32 v52, v38
	v_pk_mul_f32 v[38:39], v[20:21], v[62:63]
	v_mul_f32_e32 v78, v78, v52
	v_add_f32_e32 v38, v79, v38
	v_add_f32_e32 v43, v38, v39
	v_mul_f32_e32 v38, 0xbfb8aa3b, v43
	v_exp_f32_e32 v53, v38
	v_pk_mul_f32 v[38:39], v[16:17], v[60:61]
	v_lshlrev_b32_e32 v52, 16, v40
	v_add_f32_e32 v38, v25, v38
	v_add_f32_e32 v57, v38, v39
	v_add_f32_e32 v38, 1.0, v53
	v_rcp_f32_e32 v53, v38
	v_pk_mul_f32 v[38:39], v[20:21], v[46:47]
	s_nop 0
	v_add_f32_e32 v38, v57, v38
	v_add_f32_e32 v79, v38, v39
	v_mul_f32_e32 v38, 0xbfb8aa3b, v79
	v_exp_f32_e32 v38, v38
	v_mul_f32_e32 v39, v43, v53
	v_cvt_pk_bf16_f32 v57, v42, v39
	v_lshlrev_b32_e32 v53, 16, v44
	v_add_f32_e32 v38, 1.0, v38
	v_rcp_f32_e32 v42, v38
	v_pk_mul_f32 v[38:39], v[94:95], v[68:69]
	v_pk_mov_b32 v[60:61], v[68:69], v[52:53] op_sel:[1,0]
	v_add_f32_e32 v38, v10, v38
	v_add_f32_e32 v43, v38, v39
	v_pk_mul_f32 v[38:39], v[98:99], v[60:61]
	v_mul_f32_e32 v79, v79, v42
	v_add_f32_e32 v38, v76, v38
	v_add_f32_e32 v76, v38, v39
	v_mul_f32_e32 v38, 0xbfb8aa3b, v76
	v_exp_f32_e32 v68, v38
	v_pk_mul_f32 v[38:39], v[98:99], v[52:53]
	v_and_b32_e32 v42, 0xffff0000, v40
	v_add_f32_e32 v38, v43, v38
	v_add_f32_e32 v85, v38, v39
	v_mul_f32_e32 v38, 0xbfb8aa3b, v85
	v_exp_f32_e32 v38, v38
	v_and_b32_e32 v43, 0xffff0000, v44
	v_add_f32_e32 v39, 1.0, v68
	v_pk_mov_b32 v[68:69], v[58:59], v[42:43] op_sel:[1,0]
	v_add_f32_e32 v38, 1.0, v38
	v_rcp_f32_e32 v88, v39
	v_rcp_f32_e32 v89, v38
	v_pk_mul_f32 v[38:39], v[6:7], v[68:69]
	v_mul_f32_e32 v88, v76, v88
	v_add_f32_e32 v38, v77, v38
	v_add_f32_e32 v40, v38, v39
	v_mul_f32_e32 v38, 0xbfb8aa3b, v40
	v_exp_f32_e32 v44, v38
	v_pk_mul_f32 v[38:39], v[2:3], v[58:59]
	v_mul_f32_e32 v85, v85, v89
	v_add_f32_e32 v38, v11, v38
	v_add_f32_e32 v58, v38, v39
	v_add_f32_e32 v38, 1.0, v44
	v_rcp_f32_e32 v44, v38
	v_pk_mul_f32 v[38:39], v[6:7], v[42:43]
	v_mul_f32_e32 v40, v40, v44
	v_add_f32_e32 v38, v58, v38
	v_add_f32_e32 v92, v38, v39
	v_mul_f32_e32 v38, 0xbfb8aa3b, v92
	v_exp_f32_e32 v38, v38
	v_lshlrev_b32_e32 v39, 16, v45
	v_and_b32_e32 v45, 0xffff0000, v45
	v_add_f32_e32 v38, 1.0, v38
	v_rcp_f32_e32 v44, v38
	v_lshlrev_b32_e32 v38, 16, v41
	v_pk_mov_b32 v[76:77], v[54:55], v[38:39] op_sel:[1,0]
	v_pk_mul_f32 v[54:55], v[86:87], v[54:55]
	v_pk_mul_f32 v[58:59], v[90:91], v[76:77]
	v_add_f32_e32 v54, v12, v54
	v_add_f32_e32 v58, v80, v58
	v_add_f32_e32 v59, v58, v59
	v_mul_f32_e32 v58, 0xbfb8aa3b, v59
	v_exp_f32_e32 v58, v58
	v_add_f32_e32 v80, v54, v55
	v_add_f32_e32 v54, 1.0, v58
	v_rcp_f32_e32 v89, v54
	v_pk_mul_f32 v[54:55], v[90:91], v[38:39]
	v_cvt_pk_bf16_f32 v58, v88, v40
	v_mul_f32_e32 v88, v92, v44
	v_add_f32_e32 v54, v80, v54
	v_add_f32_e32 v80, v54, v55
	v_mul_f32_e32 v54, 0xbfb8aa3b, v80
; __device__ __forceinline__ unsigned cvt_pk_bf16(float lo, float hi) { unsigned r; asm volatile("v_cvt_pk_bf16_f32 %0, %1, %2" : "=v"(r) : "v"(lo), "v"(hi)); return r; }
; #define LAS __attribute__((address_space(3)))
; __device__ __forceinline__ float silu_f(float x) { return x * __builtin_amdgcn_rcpf(1.f + __expf(-x)); }
; template <bool NEED_C>
; __device__ __forceinline__ void ssd_stage(LAS unsigned char* lds, const bf16_t* XBC, const float* cw, const float* cb, const float* DT, const float* a_log, int c, int g, int tid, int lane, int wave) {
;     ...
; #pragma unroll
;             for (int k = 0; k < 3; ++k) unpack8(raw[k], xw[k]);
; #pragma unroll
;             for (int i = 0; i < 16; ++i) { float xv[8]; unpack8(raw[3 + i], xv);
;                 float o[8];
; #pragma unroll
;                 for (int e = 0; e < 8; ++e) { o[e] = silu_f(b[e] + w[0][e] * xw[0][e] + w[1][e] * xw[1][e] + w[2][e] * xw[2][e] + w[3][e] * xv[e]); xw[0][e] = xw[1][e]; xw[1][e] = xw[2][e]; xw[2][e] = xv[e]; }
;                 u32x4 pk; pk.x = cvt_pk_bf16(o[0], o[1]); pk.y = cvt_pk_bf16(o[2], o[3]); pk.z = cvt_pk_bf16(o[4], o[5]); pk.w = cvt_pk_bf16(o[6], o[7]);
;                 *(LAS u32x4*)(tile + off_b(seg * 16 + i, tch)) = pk; }
	v_exp_f32_e32 v54, v54
	v_mul_f32_e32 v59, v59, v89
	v_and_b32_e32 v44, 0xffff0000, v41
	v_add_f32_e32 v40, 1.0, v54
	v_pk_mul_f32 v[54:55], v[4:5], v[66:67]
	v_rcp_f32_e32 v89, v40
	v_add_f32_e32 v40, v13, v54
	v_add_f32_e32 v92, v40, v55
	v_pk_mov_b32 v[40:41], v[66:67], v[44:45] op_sel:[1,0]
	v_mul_f32_e32 v80, v80, v89
	v_pk_mul_f32 v[54:55], v[8:9], v[40:41]
	v_pk_mul_f32 v[40:41], v[4:5], v[40:41]
	v_add_f32_e32 v54, v81, v54
	v_add_f32_e32 v66, v54, v55
	v_mul_f32_e32 v54, 0xbfb8aa3b, v66
	v_exp_f32_e32 v67, v54
	v_pk_mul_f32 v[54:55], v[8:9], v[44:45]
	v_add_f32_e32 v40, v13, v40
	v_add_f32_e32 v54, v92, v54
	v_add_f32_e32 v54, v54, v55
	v_mul_f32_e32 v55, 0xbfb8aa3b, v54
	v_exp_f32_e32 v55, v55
	v_add_f32_e32 v67, 1.0, v67
	v_rcp_f32_e32 v67, v67
	v_add_f32_e32 v55, 1.0, v55
	v_rcp_f32_e32 v55, v55
	v_mul_f32_e32 v66, v66, v67
	v_cvt_pk_bf16_f32 v59, v59, v66
	ds_write_b128 v82, v[56:59] offset:2816
	v_xor_b32_e32 v58, 48, v116
	v_mul_f32_e32 v57, v54, v55
	v_cvt_pk_bf16_f32 v54, v83, v84
	v_cvt_pk_bf16_f32 v55, v78, v79
	v_add3_u32 v58, v123, v58, v147
	v_cvt_pk_bf16_f32 v56, v85, v88
	v_cvt_pk_bf16_f32 v57, v80, v57
	ds_write_b128 v58, v[54:57] offset:3072
	v_pk_mul_f32 v[54:55], v[124:125], v[70:71]
	v_xor_b32_e32 v59, 0x70, v116
	v_add_f32_e32 v54, v22, v54
	v_add_f32_e32 v58, v54, v55
	v_pk_mul_f32 v[54:55], v[14:15], v[72:73]
	v_add_f32_e32 v73, v40, v41
	v_add_f32_e32 v54, v23, v54
	v_add_f32_e32 v66, v54, v55
	v_pk_mul_f32 v[54:55], v[106:107], v[74:75]
	v_pk_mul_f32 v[40:41], v[124:125], v[64:65]
	v_add_f32_e32 v54, v24, v54
	v_add_f32_e32 v67, v54, v55
	v_pk_mul_f32 v[54:55], v[16:17], v[62:63]
	v_add_f32_e32 v40, v22, v40
	v_add_f32_e32 v54, v25, v54
	v_add_f32_e32 v70, v54, v55
	v_pk_mul_f32 v[54:55], v[94:95], v[60:61]
	v_add_f32_e32 v60, v40, v41
	v_add_f32_e32 v54, v10, v54
	v_add_f32_e32 v71, v54, v55
	v_pk_mul_f32 v[54:55], v[2:3], v[68:69]
	s_waitcnt vmcnt(2)
	v_lshlrev_b32_e32 v40, 16, v30
	v_add_f32_e32 v54, v11, v54
	v_add_f32_e32 v68, v54, v55
	v_pk_mul_f32 v[54:55], v[86:87], v[76:77]
	s_waitcnt vmcnt(1)
	v_lshlrev_b32_e32 v41, 16, v34
	v_add_f32_e32 v54, v12, v54
	v_add_f32_e32 v72, v54, v55
	v_pk_mov_b32 v[54:55], v[64:65], v[40:41] op_sel:[1,0]
	v_add3_u32 v74, v123, v59, v147
	v_pk_mul_f32 v[56:57], v[126:127], v[54:55]
	v_pk_mul_f32 v[54:55], v[124:125], v[54:55]
	v_add_f32_e32 v56, v58, v56
	v_add_f32_e32 v62, v56, v57
	v_mul_f32_e32 v56, 0xbfb8aa3b, v62
	v_exp_f32_e32 v58, v56
	v_pk_mul_f32 v[56:57], v[126:127], v[40:41]
	v_add_f32_e32 v22, v22, v54
	v_add_f32_e32 v40, v60, v56
	v_add_f32_e32 v40, v40, v57
	v_mul_f32_e32 v56, 0xbfb8aa3b, v40
	v_exp_f32_e32 v56, v56
	v_add_f32_e32 v57, 1.0, v58
	v_rcp_f32_e32 v63, v57
	v_and_b32_e32 v57, 0xffff0000, v34
	v_add_f32_e32 v56, 1.0, v56
	v_rcp_f32_e32 v64, v56
	v_and_b32_e32 v56, 0xffff0000, v30
	v_pk_mov_b32 v[58:59], v[50:51], v[56:57] op_sel:[1,0]
	v_pk_mul_f32 v[50:51], v[14:15], v[50:51]
	v_pk_mul_f32 v[60:61], v[18:19], v[58:59]
	v_add_f32_e32 v50, v23, v50
	v_add_f32_e32 v30, v66, v60
	v_add_f32_e32 v30, v30, v61
	v_mul_f32_e32 v34, 0xbfb8aa3b, v30
	v_exp_f32_e32 v34, v34
	v_add_f32_e32 v60, v50, v51
	v_pk_mul_f32 v[50:51], v[18:19], v[56:57]
	v_mul_f32_e32 v65, v62, v63
	v_add_f32_e32 v50, v60, v50
	v_add_f32_e32 v56, v50, v51
	v_add_f32_e32 v34, 1.0, v34
	v_mul_f32_e32 v50, 0xbfb8aa3b, v56
	v_rcp_f32_e32 v34, v34
	v_exp_f32_e32 v50, v50
	v_lshlrev_b32_e32 v51, 16, v35
	v_mul_f32_e32 v40, v40, v64
	v_mul_f32_e32 v30, v30, v34
	v_add_f32_e32 v34, 1.0, v50
	v_lshlrev_b32_e32 v50, 16, v31
	v_pk_mov_b32 v[60:61], v[48:49], v[50:51] op_sel:[1,0]
	v_pk_mul_f32 v[48:49], v[106:107], v[48:49]
	v_pk_mul_f32 v[62:63], v[110:111], v[60:61]
	v_add_f32_e32 v48, v24, v48
	v_add_f32_e32 v62, v67, v62
	v_add_f32_e32 v62, v62, v63
	v_mul_f32_e32 v63, 0xbfb8aa3b, v62
	v_exp_f32_e32 v63, v63
	v_add_f32_e32 v64, v48, v49
	v_rcp_f32_e32 v34, v34
	v_cvt_pk_bf16_f32 v30, v65, v30
	v_add_f32_e32 v48, 1.0, v63
	v_rcp_f32_e32 v63, v48
	v_pk_mul_f32 v[48:49], v[110:111], v[50:51]
	v_mul_f32_e32 v56, v56, v34
	v_add_f32_e32 v48, v64, v48
	v_add_f32_e32 v50, v48, v49
	v_mul_f32_e32 v48, 0xbfb8aa3b, v50
	v_exp_f32_e32 v48, v48
	v_and_b32_e32 v35, 0xffff0000, v35
	v_mul_f32_e32 v64, v62, v63
	v_pk_mul_f32 v[14:15], v[14:15], v[58:59]
	v_add_f32_e32 v34, 1.0, v48
	v_rcp_f32_e32 v65, v34
	v_and_b32_e32 v34, 0xffff0000, v31
	v_pk_mov_b32 v[48:49], v[46:47], v[34:35] op_sel:[1,0]
	v_pk_mul_f32 v[46:47], v[16:17], v[46:47]
	v_pk_mul_f32 v[62:63], v[20:21], v[48:49]
	v_add_f32_e32 v46, v25, v46
	v_add_f32_e32 v31, v70, v62
	v_add_f32_e32 v31, v31, v63
	v_mul_f32_e32 v62, 0xbfb8aa3b, v31
	v_exp_f32_e32 v62, v62
	v_add_f32_e32 v63, v46, v47
	v_mul_f32_e32 v50, v50, v65
	v_add_f32_e32 v14, v23, v14
	v_add_f32_e32 v46, 1.0, v62
	v_rcp_f32_e32 v62, v46
	v_pk_mul_f32 v[46:47], v[20:21], v[34:35]
	v_add_f32_e32 v23, v14, v15
	v_add_f32_e32 v34, v63, v46
	v_add_f32_e32 v34, v34, v47
	v_mul_f32_e32 v46, 0xbfb8aa3b, v34
	v_exp_f32_e32 v46, v46
	v_mul_f32_e32 v31, v31, v62
	v_cvt_pk_bf16_f32 v31, v64, v31
	v_add_f32_e32 v22, v22, v55
	v_add_f32_e32 v46, 1.0, v46
	v_rcp_f32_e32 v64, v46
	v_pk_mul_f32 v[46:47], v[94:95], v[52:53]
	v_mul_f32_e32 v34, v34, v64
	v_add_f32_e32 v46, v10, v46
	v_add_f32_e32 v65, v46, v47
	v_lshlrev_b32_e32 v46, 16, v32
	v_lshlrev_b32_e32 v47, 16, v36
	v_pk_mov_b32 v[52:53], v[52:53], v[46:47] op_sel:[1,0]
	s_nop 0
	v_pk_mul_f32 v[62:63], v[98:99], v[52:53]
	s_nop 0
	v_add_f32_e32 v62, v71, v62
	v_add_f32_e32 v69, v62, v63
	v_mul_f32_e32 v62, 0xbfb8aa3b, v69
	v_exp_f32_e32 v66, v62
	v_pk_mul_f32 v[62:63], v[98:99], v[46:47]
	s_nop 0
	v_add_f32_e32 v46, v65, v62
; __device__ __forceinline__ unsigned cvt_pk_bf16(float lo, float hi) { unsigned r; asm volatile("v_cvt_pk_bf16_f32 %0, %1, %2" : "=v"(r) : "v"(lo), "v"(hi)); return r; }
; #define LAS __attribute__((address_space(3)))
; __device__ __forceinline__ float silu_f(float x) { return x * __builtin_amdgcn_rcpf(1.f + __expf(-x)); }
; template <bool NEED_C>
; __device__ __forceinline__ void ssd_stage(LAS unsigned char* lds, const bf16_t* XBC, const float* cw, const float* cb, const float* DT, const float* a_log, int c, int g, int tid, int lane, int wave) {
;     ...
;             for (int i = 0; i < 16; ++i) { float xv[8]; unpack8(raw[3 + i], xv);
;                 float o[8];
; #pragma unroll
;                 for (int e = 0; e < 8; ++e) { o[e] = silu_f(b[e] + w[0][e] * xw[0][e] + w[1][e] * xw[1][e] + w[2][e] * xw[2][e] + w[3][e] * xv[e]); xw[0][e] = xw[1][e]; xw[1][e] = xw[2][e]; xw[2][e] = xv[e]; }
;                 u32x4 pk; pk.x = cvt_pk_bf16(o[0], o[1]); pk.y = cvt_pk_bf16(o[2], o[3]); pk.z = cvt_pk_bf16(o[4], o[5]); pk.w = cvt_pk_bf16(o[6], o[7]);
;                 *(LAS u32x4*)(tile + off_b(seg * 16 + i, tch)) = pk; }
;     ...
;     { const int l = tid >> 2, r = tid & 3, hd = 4 * g + r; const float dtv = DT[(size_t)(c * 128 + l) * 32 + hd]; const float a = -expf(a_log[hd]);
;       ((LAS float*)(lds + SSD_DT))[r * 128 + l] = dtv; ((LAS float*)(lds + SSD_ACS))[r * 128 + l] = dtv * a; }
;     __syncthreads();
	v_add_f32_e32 v46, v46, v63
	v_mul_f32_e32 v62, 0xbfb8aa3b, v46
	v_exp_f32_e32 v62, v62
	v_add_f32_e32 v63, 1.0, v66
	v_rcp_f32_e32 v70, v63
	v_and_b32_e32 v63, 0xffff0000, v36
	v_add_f32_e32 v62, 1.0, v62
	v_rcp_f32_e32 v71, v62
	v_and_b32_e32 v62, 0xffff0000, v32
	v_pk_mov_b32 v[64:65], v[42:43], v[62:63] op_sel:[1,0]
	v_pk_mul_f32 v[42:43], v[2:3], v[42:43]
	v_pk_mul_f32 v[66:67], v[6:7], v[64:65]
	v_add_f32_e32 v42, v11, v42
	v_add_f32_e32 v32, v68, v66
	v_add_f32_e32 v32, v32, v67
	v_mul_f32_e32 v36, 0xbfb8aa3b, v32
	v_exp_f32_e32 v36, v36
	v_add_f32_e32 v66, v42, v43
	v_pk_mul_f32 v[42:43], v[6:7], v[62:63]
	v_mul_f32_e32 v70, v69, v70
	v_add_f32_e32 v42, v66, v42
	v_add_f32_e32 v62, v42, v43
	v_add_f32_e32 v36, 1.0, v36
	v_mul_f32_e32 v42, 0xbfb8aa3b, v62
	v_rcp_f32_e32 v36, v36
	v_exp_f32_e32 v42, v42
	v_lshlrev_b32_e32 v43, 16, v37
	v_mul_f32_e32 v46, v46, v71
	v_mul_f32_e32 v32, v32, v36
	v_add_f32_e32 v36, 1.0, v42
	v_lshlrev_b32_e32 v42, 16, v33
	v_pk_mov_b32 v[66:67], v[38:39], v[42:43] op_sel:[1,0]
	v_pk_mul_f32 v[38:39], v[86:87], v[38:39]
	v_pk_mul_f32 v[68:69], v[90:91], v[66:67]
	v_add_f32_e32 v38, v12, v38
	v_add_f32_e32 v68, v72, v68
	v_add_f32_e32 v68, v68, v69
	v_mul_f32_e32 v69, 0xbfb8aa3b, v68
	v_exp_f32_e32 v69, v69
	v_add_f32_e32 v71, v38, v39
	v_rcp_f32_e32 v36, v36
	v_cvt_pk_bf16_f32 v32, v70, v32
	v_add_f32_e32 v38, 1.0, v69
	v_rcp_f32_e32 v69, v38
	v_pk_mul_f32 v[38:39], v[90:91], v[42:43]
	v_mul_f32_e32 v62, v62, v36
	v_add_f32_e32 v38, v71, v38
	v_add_f32_e32 v42, v38, v39
	v_mul_f32_e32 v38, 0xbfb8aa3b, v42
	v_exp_f32_e32 v38, v38
	v_mul_f32_e32 v68, v68, v69
	v_and_b32_e32 v37, 0xffff0000, v37
	v_pk_mul_f32 v[2:3], v[2:3], v[64:65]
	v_add_f32_e32 v36, 1.0, v38
	v_pk_mul_f32 v[38:39], v[4:5], v[44:45]
	v_rcp_f32_e32 v69, v36
	v_add_f32_e32 v36, v13, v38
	v_add_f32_e32 v70, v36, v39
	v_and_b32_e32 v36, 0xffff0000, v33
	v_pk_mov_b32 v[38:39], v[44:45], v[36:37] op_sel:[1,0]
	v_mul_f32_e32 v42, v42, v69
	v_pk_mul_f32 v[44:45], v[8:9], v[38:39]
	s_waitcnt vmcnt(0)
	v_lshlrev_b32_e32 v69, 16, v28
	v_add_f32_e32 v33, v73, v44
	v_add_f32_e32 v33, v33, v45
	v_mul_f32_e32 v44, 0xbfb8aa3b, v33
	v_exp_f32_e32 v71, v44
	v_pk_mul_f32 v[44:45], v[8:9], v[36:37]
	v_add_f32_e32 v2, v11, v2
	v_add_f32_e32 v36, v70, v44
	v_add_f32_e32 v36, v36, v45
	v_mul_f32_e32 v44, 0xbfb8aa3b, v36
	v_exp_f32_e32 v44, v44
	v_add_f32_e32 v45, 1.0, v71
	v_rcp_f32_e32 v45, v45
	v_add_f32_e32 v11, v2, v3
	v_add_f32_e32 v44, 1.0, v44
	v_rcp_f32_e32 v44, v44
	v_mul_f32_e32 v33, v33, v45
	v_cvt_pk_bf16_f32 v33, v68, v33
	ds_write_b128 v74, v[30:33] offset:3328
	v_mul_f32_e32 v33, v36, v44
	v_cvt_pk_bf16_f32 v30, v40, v56
	v_cvt_pk_bf16_f32 v31, v50, v34
	v_xor_b32_e32 v34, 0xb0, v116
	v_cvt_pk_bf16_f32 v32, v46, v62
	v_cvt_pk_bf16_f32 v33, v42, v33
	v_add3_u32 v34, v123, v34, v147
	ds_write_b128 v34, v[30:33] offset:3584
	v_and_b32_e32 v33, 0xffff0000, v26
	v_mov_b32_e32 v32, v57
	v_pk_mul_f32 v[14:15], v[18:19], v[32:33]
	v_lshlrev_b32_e32 v45, 16, v27
	v_add_f32_e32 v14, v23, v14
	v_add_f32_e32 v18, v14, v15
	v_mul_f32_e32 v14, 0xbfb8aa3b, v18
	v_exp_f32_e32 v19, v14
	v_pk_mul_f32 v[14:15], v[106:107], v[60:61]
	v_mov_b32_e32 v44, v51
	v_add_f32_e32 v14, v24, v14
	v_lshlrev_b32_e32 v31, 16, v26
	v_mov_b32_e32 v30, v41
	v_add_f32_e32 v23, v14, v15
	v_pk_mul_f32 v[14:15], v[110:111], v[44:45]
	v_pk_mul_f32 v[30:31], v[126:127], v[30:31]
	v_add_f32_e32 v14, v23, v14
	v_add_f32_e32 v22, v22, v30
	v_add_f32_e32 v23, v14, v15
	v_add_f32_e32 v22, v22, v31
	v_mul_f32_e32 v14, 0xbfb8aa3b, v23
	v_mul_f32_e32 v26, 0xbfb8aa3b, v22
	v_exp_f32_e32 v14, v14
	v_exp_f32_e32 v26, v26
	v_add_f32_e32 v15, 1.0, v19
	v_and_b32_e32 v31, 0xffff0000, v28
	v_add_f32_e32 v14, 1.0, v14
	v_add_f32_e32 v26, 1.0, v26
	v_rcp_f32_e32 v19, v15
	v_rcp_f32_e32 v28, v14
	v_pk_mul_f32 v[14:15], v[16:17], v[48:49]
	v_and_b32_e32 v27, 0xffff0000, v27
	v_rcp_f32_e32 v24, v26
	v_add_f32_e32 v14, v25, v14
	v_mov_b32_e32 v26, v35
	v_add_f32_e32 v16, v14, v15
	v_pk_mul_f32 v[14:15], v[20:21], v[26:27]
	v_mov_b32_e32 v68, v47
	v_add_f32_e32 v14, v16, v14
	v_add_f32_e32 v16, v14, v15
	v_mul_f32_e32 v14, 0xbfb8aa3b, v16
	v_exp_f32_e32 v14, v14
	v_mov_b32_e32 v30, v63
	v_pk_mul_f32 v[2:3], v[6:7], v[30:31]
	v_lshlrev_b32_e32 v41, 16, v29
	v_add_f32_e32 v14, 1.0, v14
	v_rcp_f32_e32 v20, v14
	v_pk_mul_f32 v[14:15], v[94:95], v[52:53]
	v_add_f32_e32 v2, v11, v2
	v_add_f32_e32 v10, v10, v14
	v_add_f32_e32 v10, v10, v15
	v_pk_mul_f32 v[14:15], v[98:99], v[68:69]
	v_add_f32_e32 v6, v2, v3
	v_add_f32_e32 v10, v10, v14
	v_add_f32_e32 v10, v10, v15
	v_mul_f32_e32 v14, 0xbfb8aa3b, v10
	v_exp_f32_e32 v14, v14
	v_mul_f32_e32 v2, 0xbfb8aa3b, v6
	v_exp_f32_e32 v2, v2
	v_mov_b32_e32 v40, v43
	v_add_f32_e32 v3, 1.0, v14
	v_rcp_f32_e32 v11, v3
	v_add_f32_e32 v14, 1.0, v2
	v_pk_mul_f32 v[2:3], v[86:87], v[66:67]
	v_and_b32_e32 v29, 0xffff0000, v29
	v_add_f32_e32 v2, v12, v2
	v_add_f32_e32 v12, v2, v3
	v_pk_mul_f32 v[2:3], v[90:91], v[40:41]
	v_mul_f32_e32 v18, v18, v19
	v_add_f32_e32 v2, v12, v2
	v_add_f32_e32 v12, v2, v3
	v_mul_f32_e32 v2, 0xbfb8aa3b, v12
	v_exp_f32_e32 v15, v2
	v_pk_mul_f32 v[2:3], v[4:5], v[38:39]
	v_mul_f32_e32 v19, v23, v28
	v_add_f32_e32 v2, v13, v2
	v_mov_b32_e32 v28, v37
	v_add_f32_e32 v4, v2, v3
	v_pk_mul_f32 v[2:3], v[8:9], v[28:29]
	v_add_f32_e32 v5, 1.0, v15
	v_add_f32_e32 v2, v4, v2
	v_add_f32_e32 v2, v2, v3
	v_mul_f32_e32 v3, 0xbfb8aa3b, v2
	v_exp_f32_e32 v3, v3
	v_rcp_f32_e32 v4, v14
	v_rcp_f32_e32 v5, v5
	v_mul_f32_e32 v17, v22, v24
	v_add_f32_e32 v3, 1.0, v3
	v_rcp_f32_e32 v3, v3
	v_mul_f32_e32 v4, v6, v4
	v_mul_f32_e32 v5, v12, v5
	v_mul_f32_e32 v7, v16, v20
	v_mul_f32_e32 v6, v2, v3
	v_mul_f32_e32 v8, v10, v11
	v_cvt_pk_bf16_f32 v2, v17, v18
	v_cvt_pk_bf16_f32 v3, v19, v7
	v_cvt_pk_bf16_f32 v4, v8, v4
	v_cvt_pk_bf16_f32 v5, v5, v6
	v_or_b32_e32 v6, s1, v149
	v_lshlrev_b32_e32 v118, 2, v6
	s_waitcnt vmcnt(0)
	v_mov_b32_e32 v8, v252
	v_add_u32_e32 v98, s90, v144
	v_ashrrev_i32_e32 v99, 31, v98
	v_lshlrev_b64 v[6:7], 7, v[98:99]
	v_lshl_add_u64 v[6:7], s[36:37], 0, v[6:7]
	v_lshl_add_u64 v[6:7], v[6:7], 0, v[118:119]
	v_mov_b32_e32 v6, v253
	s_waitcnt vmcnt(1)
	v_mul_f32_e32 v7, 0x3fb8aa3b, v8
	v_fma_f32 v9, v8, s84, -v7
	v_rndne_f32_e32 v10, v7
	v_fmac_f32_e32 v9, 0x32a5705f, v8
	v_sub_f32_e32 v7, v7, v10
	v_add_f32_e32 v7, v7, v9
	v_exp_f32_e32 v7, v7
	v_cvt_i32_f32_e32 v9, v10
	v_xor_b32_e32 v10, 0xf0, v116
	v_add3_u32 v10, v123, v10, v148
	ds_write_b128 v10, v[2:5]
	v_ldexp_f32 v2, v7, v9
	v_cmp_ngt_f32_e32 vcc, s85, v8
	s_waitcnt vmcnt(0)
	ds_write_b32 v150, v6
	v_cndmask_b32_e32 v2, 0, v2, vcc
	v_cmp_nlt_f32_e32 vcc, s86, v8
	s_nop 1
	v_cndmask_b32_e32 v2, v218, v2, vcc
	v_mul_f32_e64 v2, v6, -v2
	s_andn2_b64 vcc, exec, s[44:45]
	ds_write_b32 v151, v2
	s_waitcnt lgkmcnt(0)
	s_barrier
; #define LAS __attribute__((address_space(3)))
; template <bool NEED_C>
; __device__ __forceinline__ void ssd_stage(LAS unsigned char* lds, const bf16_t* XBC, const float* cw, const float* cb, const float* DT, const float* a_log, int c, int g, int tid, int lane, int wave) {
;     ...
;     if (wave < 4) { LAS float* ac = (LAS float*)(lds + SSD_ACS) + wave * 128; const float v0 = ac[2 * lane], v1 = ac[2 * lane + 1]; const float s = v0 + v1; float inc = s;
; #pragma unroll
;         for (int o = 1; o < 64; o <<= 1) { const float t = __shfl_up(inc, o); if (lane >= o) inc += t; }
;         ac[2 * lane] = inc - s + v0; ac[2 * lane + 1] = inc; }
	s_cbranch_vccnz .LBB0_1052
	v_add_u32_e32 v4, s60, v141
	ds_read_b64 v[2:3], v4
	v_and_b32_e32 v5, 64, v219
	v_add_u32_e32 v6, -1, v219
	v_cmp_lt_i32_e32 vcc, v6, v5
	v_add_u32_e32 v8, -4, v219
	s_waitcnt lgkmcnt(0)
	v_add_f32_e32 v7, v2, v3
	v_cndmask_b32_e32 v6, v6, v219, vcc
	v_lshlrev_b32_e32 v3, 2, v6
	ds_bpermute_b32 v3, v3, v7
	v_add_u32_e32 v6, -2, v219
	v_cmp_lt_i32_e32 vcc, v6, v5
	s_waitcnt lgkmcnt(0)
	v_add_f32_e32 v3, v7, v3
	v_cndmask_b32_e32 v6, v6, v219, vcc
	v_cndmask_b32_e64 v3, v3, v7, s[8:9]
	v_lshlrev_b32_e32 v6, 2, v6
	ds_bpermute_b32 v6, v6, v3
	v_cmp_lt_i32_e32 vcc, v8, v5
	s_waitcnt lgkmcnt(0)
	v_add_f32_e32 v6, v3, v6
	v_cndmask_b32_e32 v8, v8, v219, vcc
	v_cndmask_b32_e64 v3, v6, v3, s[10:11]
	v_lshlrev_b32_e32 v6, 2, v8
	ds_bpermute_b32 v6, v6, v3
	v_add_u32_e32 v8, -8, v219
	v_cmp_lt_i32_e32 vcc, v8, v5
	s_waitcnt lgkmcnt(0)
	v_add_f32_e32 v6, v3, v6
	v_cndmask_b32_e32 v8, v8, v219, vcc
	v_cndmask_b32_e64 v3, v6, v3, s[12:13]
	v_lshlrev_b32_e32 v6, 2, v8
	ds_bpermute_b32 v6, v6, v3
	v_add_u32_e32 v8, -16, v219
	v_cmp_lt_i32_e32 vcc, v8, v5
	s_waitcnt lgkmcnt(0)
	v_add_f32_e32 v6, v3, v6
	v_cndmask_b32_e32 v8, v8, v219, vcc
	v_cndmask_b32_e64 v3, v6, v3, s[14:15]
	v_lshlrev_b32_e32 v6, 2, v8
	ds_bpermute_b32 v6, v6, v3
	v_subrev_u32_e32 v8, 32, v219
	v_cmp_lt_i32_e32 vcc, v8, v5
	s_waitcnt lgkmcnt(0)
	v_add_f32_e32 v6, v3, v6
	v_cndmask_b32_e32 v5, v8, v219, vcc
	v_cndmask_b32_e64 v3, v6, v3, s[16:17]
	v_lshlrev_b32_e32 v5, 2, v5
	ds_bpermute_b32 v5, v5, v3
	s_waitcnt lgkmcnt(0)
	v_add_f32_e32 v5, v3, v5
	v_cndmask_b32_e64 v3, v5, v3, s[6:7]
	v_sub_f32_e32 v5, v3, v7
	v_add_f32_e32 v2, v2, v5
	ds_write_b64 v4, v[2:3]
